# speedup vs baseline: 1.0170x; 1.0007x over previous
.LBB0_96:
	ds_read_b128 v[162:165], v141
	ds_read_b128 v[166:169], v142
	ds_read_b128 v[170:173], v143
	ds_read_b128 v[174:177], v144
	s_add_u32 s82, s34, 0xffffff00
	s_addc_u32 s83, s35, -1
	s_mov_b32 m0, s77
	ds_read_b128 v[178:181], v160
	ds_read_b128 v[182:185], v160 offset:1024
	ds_read_b128 v[186:189], v160 offset:2048
	ds_read_b128 v[190:193], v160 offset:3072
	ds_read_b128 v[194:197], v160 offset:4096
	ds_read_b128 v[198:201], v160 offset:5120
	ds_read_b128 v[202:205], v160 offset:6144
	ds_read_b128 v[206:209], v160 offset:7168
	v_lshl_add_u64 v[210:211], v[134:135], 0, s[82:83]
	global_load_lds_dwordx4 v[210:211], off
	v_lshl_add_u64 v[210:211], v[210:211], 0, s[0:1]
	s_mov_b32 m0, s68
	s_nop 0
	global_load_lds_dwordx4 v[210:211], off
	s_waitcnt lgkmcnt(8)
	s_barrier
	s_waitcnt lgkmcnt(0)
	v_mfma_f32_16x16x32_bf16 v[124:127], v[162:165], v[178:181], v[124:127]
	v_mfma_f32_16x16x32_bf16 v[120:123], v[170:173], v[178:181], v[120:123]
	v_mfma_f32_16x16x32_bf16 v[116:119], v[162:165], v[186:189], v[116:119]
	v_mfma_f32_16x16x32_bf16 v[112:115], v[170:173], v[186:189], v[112:115]
	v_mfma_f32_16x16x32_bf16 v[108:111], v[162:165], v[194:197], v[108:111]
	v_mfma_f32_16x16x32_bf16 v[104:107], v[170:173], v[194:197], v[104:107]
	v_mfma_f32_16x16x32_bf16 v[100:103], v[162:165], v[202:205], v[100:103]
	v_mfma_f32_16x16x32_bf16 v[96:99], v[170:173], v[202:205], v[96:99]
	v_mfma_f32_16x16x32_bf16 v[124:127], v[166:169], v[182:185], v[124:127]
	v_mfma_f32_16x16x32_bf16 v[120:123], v[174:177], v[182:185], v[120:123]
	v_mfma_f32_16x16x32_bf16 v[116:119], v[166:169], v[190:193], v[116:119]
	v_mfma_f32_16x16x32_bf16 v[112:115], v[174:177], v[190:193], v[112:115]
	v_mfma_f32_16x16x32_bf16 v[108:111], v[166:169], v[198:201], v[108:111]
	v_mfma_f32_16x16x32_bf16 v[104:107], v[174:177], v[198:201], v[104:107]
	v_mfma_f32_16x16x32_bf16 v[100:103], v[166:169], v[206:209], v[100:103]
	v_mfma_f32_16x16x32_bf16 v[96:99], v[174:177], v[206:209], v[96:99]
	s_barrier
	s_add_u32 s82, s34, 0xffefff80
	s_addc_u32 s83, s35, -1
	s_mov_b64 s[84:85], s[82:83]
	s_mov_b32 m0, s71
	ds_read_b128 v[210:213], v145
	ds_read_b128 v[214:217], v146
	ds_read_b128 v[218:221], v147
	ds_read_b128 v[222:225], v148
	v_lshl_add_u64 v[226:227], v[136:137], 0, s[84:85]
	global_load_lds_dwordx4 v[226:227], off
	v_lshl_add_u64 v[226:227], v[226:227], 0, s[0:1]
	s_mov_b32 m0, s72
	s_nop 0
	global_load_lds_dwordx4 v[226:227], off
	s_barrier
	s_waitcnt lgkmcnt(0)
	v_mfma_f32_16x16x32_bf16 v[92:95], v[210:213], v[178:181], v[92:95]
	v_mfma_f32_16x16x32_bf16 v[88:91], v[218:221], v[178:181], v[88:91]
	v_mfma_f32_16x16x32_bf16 v[84:87], v[210:213], v[186:189], v[84:87]
	v_mfma_f32_16x16x32_bf16 v[80:83], v[218:221], v[186:189], v[80:83]
	v_mfma_f32_16x16x32_bf16 v[76:79], v[210:213], v[194:197], v[76:79]
	v_mfma_f32_16x16x32_bf16 v[72:75], v[218:221], v[194:197], v[72:75]
	v_mfma_f32_16x16x32_bf16 v[68:71], v[210:213], v[202:205], v[68:71]
	v_mfma_f32_16x16x32_bf16 v[64:67], v[218:221], v[202:205], v[64:67]
	v_mfma_f32_16x16x32_bf16 v[92:95], v[214:217], v[182:185], v[92:95]
	v_mfma_f32_16x16x32_bf16 v[88:91], v[222:225], v[182:185], v[88:91]
	v_mfma_f32_16x16x32_bf16 v[84:87], v[214:217], v[190:193], v[84:87]
	v_mfma_f32_16x16x32_bf16 v[80:83], v[222:225], v[190:193], v[80:83]
	v_mfma_f32_16x16x32_bf16 v[76:79], v[214:217], v[198:201], v[76:79]
	v_mfma_f32_16x16x32_bf16 v[72:75], v[222:225], v[198:201], v[72:75]
	v_mfma_f32_16x16x32_bf16 v[68:71], v[214:217], v[206:209], v[68:71]
	v_mfma_f32_16x16x32_bf16 v[64:67], v[222:225], v[206:209], v[64:67]
	s_mov_b32 m0, s7
	s_barrier
	ds_read_b128 v[178:181], v160 offset:16384
	ds_read_b128 v[182:185], v160 offset:17408
	ds_read_b128 v[186:189], v160 offset:18432
	ds_read_b128 v[190:193], v160 offset:19456
	ds_read_b128 v[194:197], v160 offset:20480
	ds_read_b128 v[198:201], v160 offset:21504
	ds_read_b128 v[202:205], v160 offset:22528
	ds_read_b128 v[206:209], v160 offset:23552
	v_lshl_add_u64 v[226:227], v[134:135], 0, s[82:83]
	global_load_lds_dwordx4 v[226:227], off
	v_lshl_add_u64 v[226:227], v[226:227], 0, s[0:1]
	s_mov_b32 m0, s79
	s_nop 0
	global_load_lds_dwordx4 v[226:227], off
	s_barrier
	s_waitcnt lgkmcnt(0)
	v_mfma_f32_16x16x32_bf16 v[60:63], v[162:165], v[178:181], v[60:63]
	v_mfma_f32_16x16x32_bf16 v[56:59], v[170:173], v[178:181], v[56:59]
	v_mfma_f32_16x16x32_bf16 v[52:55], v[162:165], v[186:189], v[52:55]
	v_mfma_f32_16x16x32_bf16 v[48:51], v[170:173], v[186:189], v[48:51]
	v_mfma_f32_16x16x32_bf16 v[44:47], v[162:165], v[194:197], v[44:47]
	v_mfma_f32_16x16x32_bf16 v[40:43], v[170:173], v[194:197], v[40:43]
	v_mfma_f32_16x16x32_bf16 v[36:39], v[162:165], v[202:205], v[36:39]
	v_mfma_f32_16x16x32_bf16 v[32:35], v[170:173], v[202:205], v[32:35]
	v_mfma_f32_16x16x32_bf16 v[60:63], v[166:169], v[182:185], v[60:63]
	v_mfma_f32_16x16x32_bf16 v[56:59], v[174:177], v[182:185], v[56:59]
	v_mfma_f32_16x16x32_bf16 v[52:55], v[166:169], v[190:193], v[52:55]
	v_mfma_f32_16x16x32_bf16 v[48:51], v[174:177], v[190:193], v[48:51]
	v_mfma_f32_16x16x32_bf16 v[44:47], v[166:169], v[198:201], v[44:47]
	v_mfma_f32_16x16x32_bf16 v[40:43], v[174:177], v[198:201], v[40:43]
	v_mfma_f32_16x16x32_bf16 v[36:39], v[166:169], v[206:209], v[36:39]
	v_mfma_f32_16x16x32_bf16 v[32:35], v[174:177], v[206:209], v[32:35]
	s_barrier
	s_add_u32 s82, s34, 0xffffff80
	s_addc_u32 s83, s35, -1
	s_mov_b64 s[84:85], s[82:83]
	s_mov_b32 m0, s73
	v_lshl_add_u64 v[162:163], v[136:137], 0, s[84:85]
	global_load_lds_dwordx4 v[162:163], off
	v_lshl_add_u64 v[162:163], v[162:163], 0, s[0:1]
	s_mov_b32 m0, s74
	s_nop 0
	global_load_lds_dwordx4 v[162:163], off
	s_waitcnt vmcnt(6)
	s_barrier
	v_mfma_f32_16x16x32_bf16 v[28:31], v[210:213], v[178:181], v[28:31]
	v_mfma_f32_16x16x32_bf16 v[24:27], v[218:221], v[178:181], v[24:27]
	v_mfma_f32_16x16x32_bf16 v[20:23], v[210:213], v[186:189], v[20:23]
	v_mfma_f32_16x16x32_bf16 v[16:19], v[218:221], v[186:189], v[16:19]
	v_mfma_f32_16x16x32_bf16 v[12:15], v[210:213], v[194:197], v[12:15]
	v_mfma_f32_16x16x32_bf16 v[8:11], v[218:221], v[194:197], v[8:11]
	v_mfma_f32_16x16x32_bf16 v[4:7], v[210:213], v[202:205], v[4:7]
	v_mfma_f32_16x16x32_bf16 v[0:3], v[218:221], v[202:205], v[0:3]
	v_mfma_f32_16x16x32_bf16 v[28:31], v[214:217], v[182:185], v[28:31]
	v_mfma_f32_16x16x32_bf16 v[24:27], v[222:225], v[182:185], v[24:27]
	v_mfma_f32_16x16x32_bf16 v[20:23], v[214:217], v[190:193], v[20:23]
	v_mfma_f32_16x16x32_bf16 v[16:19], v[222:225], v[190:193], v[16:19]
	v_mfma_f32_16x16x32_bf16 v[12:15], v[214:217], v[198:201], v[12:15]
	v_mfma_f32_16x16x32_bf16 v[8:11], v[222:225], v[198:201], v[8:11]
	v_mfma_f32_16x16x32_bf16 v[4:7], v[214:217], v[206:209], v[4:7]
	v_mfma_f32_16x16x32_bf16 v[0:3], v[222:225], v[206:209], v[0:3]
	s_barrier
	ds_read_b128 v[162:165], v149
	ds_read_b128 v[166:169], v150
	ds_read_b128 v[170:173], v151
	ds_read_b128 v[174:177], v152
	s_mov_b32 m0, s80
	ds_read_b128 v[178:181], v160 offset:32768
	ds_read_b128 v[182:185], v160 offset:33792
	ds_read_b128 v[186:189], v160 offset:34816
	ds_read_b128 v[190:193], v160 offset:35840
	ds_read_b128 v[194:197], v160 offset:36864
	ds_read_b128 v[198:201], v160 offset:37888
	ds_read_b128 v[202:205], v160 offset:38912
	ds_read_b128 v[206:209], v160 offset:39936
	v_lshl_add_u64 v[210:211], v[134:135], 0, s[82:83]
	global_load_lds_dwordx4 v[210:211], off
	v_lshl_add_u64 v[210:211], v[210:211], 0, s[0:1]
	s_mov_b32 m0, s81
	s_nop 0
	global_load_lds_dwordx4 v[210:211], off
	s_waitcnt lgkmcnt(8)
	s_barrier
	s_waitcnt lgkmcnt(0)
	v_mfma_f32_16x16x32_bf16 v[124:127], v[162:165], v[178:181], v[124:127]
	v_mfma_f32_16x16x32_bf16 v[120:123], v[170:173], v[178:181], v[120:123]
	v_mfma_f32_16x16x32_bf16 v[116:119], v[162:165], v[186:189], v[116:119]
	v_mfma_f32_16x16x32_bf16 v[112:115], v[170:173], v[186:189], v[112:115]
	v_mfma_f32_16x16x32_bf16 v[108:111], v[162:165], v[194:197], v[108:111]
	v_mfma_f32_16x16x32_bf16 v[104:107], v[170:173], v[194:197], v[104:107]
	v_mfma_f32_16x16x32_bf16 v[100:103], v[162:165], v[202:205], v[100:103]
	v_mfma_f32_16x16x32_bf16 v[96:99], v[170:173], v[202:205], v[96:99]
	v_mfma_f32_16x16x32_bf16 v[124:127], v[166:169], v[182:185], v[124:127]
	v_mfma_f32_16x16x32_bf16 v[120:123], v[174:177], v[182:185], v[120:123]
	v_mfma_f32_16x16x32_bf16 v[116:119], v[166:169], v[190:193], v[116:119]
	v_mfma_f32_16x16x32_bf16 v[112:115], v[174:177], v[190:193], v[112:115]
	v_mfma_f32_16x16x32_bf16 v[108:111], v[166:169], v[198:201], v[108:111]
	v_mfma_f32_16x16x32_bf16 v[104:107], v[174:177], v[198:201], v[104:107]
	v_mfma_f32_16x16x32_bf16 v[100:103], v[166:169], v[206:209], v[100:103]
	v_mfma_f32_16x16x32_bf16 v[96:99], v[174:177], v[206:209], v[96:99]
	s_barrier
	s_add_u32 s82, s34, 0xfff00000
	s_addc_u32 s83, s35, -1
	s_mov_b64 s[84:85], s[82:83]
	s_mov_b32 m0, s11
	ds_read_b128 v[210:213], v153
	ds_read_b128 v[214:217], v154
	ds_read_b128 v[218:221], v155
	ds_read_b128 v[222:225], v156
	v_lshl_add_u64 v[226:227], v[136:137], 0, s[84:85]
	global_load_lds_dwordx4 v[226:227], off
	v_lshl_add_u64 v[226:227], v[226:227], 0, s[0:1]
	s_mov_b32 m0, s63
	s_nop 0
	global_load_lds_dwordx4 v[226:227], off
	s_barrier
	s_waitcnt lgkmcnt(0)
	v_mfma_f32_16x16x32_bf16 v[92:95], v[210:213], v[178:181], v[92:95]
	v_mfma_f32_16x16x32_bf16 v[88:91], v[218:221], v[178:181], v[88:91]
	v_mfma_f32_16x16x32_bf16 v[84:87], v[210:213], v[186:189], v[84:87]
	v_mfma_f32_16x16x32_bf16 v[80:83], v[218:221], v[186:189], v[80:83]
	v_mfma_f32_16x16x32_bf16 v[76:79], v[210:213], v[194:197], v[76:79]
	v_mfma_f32_16x16x32_bf16 v[72:75], v[218:221], v[194:197], v[72:75]
	v_mfma_f32_16x16x32_bf16 v[68:71], v[210:213], v[202:205], v[68:71]
	v_mfma_f32_16x16x32_bf16 v[64:67], v[218:221], v[202:205], v[64:67]
	v_mfma_f32_16x16x32_bf16 v[92:95], v[214:217], v[182:185], v[92:95]
	v_mfma_f32_16x16x32_bf16 v[88:91], v[222:225], v[182:185], v[88:91]
	v_mfma_f32_16x16x32_bf16 v[84:87], v[214:217], v[190:193], v[84:87]
	v_mfma_f32_16x16x32_bf16 v[80:83], v[222:225], v[190:193], v[80:83]
	v_mfma_f32_16x16x32_bf16 v[76:79], v[214:217], v[198:201], v[76:79]
	v_mfma_f32_16x16x32_bf16 v[72:75], v[222:225], v[198:201], v[72:75]
	v_mfma_f32_16x16x32_bf16 v[68:71], v[214:217], v[206:209], v[68:71]
	v_mfma_f32_16x16x32_bf16 v[64:67], v[222:225], v[206:209], v[64:67]
	s_mov_b32 m0, s66
	s_barrier
	ds_read_b128 v[178:181], v160 offset:49152
	ds_read_b128 v[182:185], v160 offset:50176
	ds_read_b128 v[186:189], v160 offset:51200
	ds_read_b128 v[190:193], v160 offset:52224
	ds_read_b128 v[194:197], v160 offset:53248
	ds_read_b128 v[198:201], v160 offset:54272
	ds_read_b128 v[202:205], v160 offset:55296
	ds_read_b128 v[206:209], v160 offset:56320
	v_lshl_add_u64 v[226:227], v[134:135], 0, s[82:83]
	global_load_lds_dwordx4 v[226:227], off
	v_lshl_add_u64 v[226:227], v[226:227], 0, s[0:1]
	s_mov_b32 m0, s67
	s_nop 0
	global_load_lds_dwordx4 v[226:227], off
	s_barrier
	s_waitcnt lgkmcnt(0)
	v_mfma_f32_16x16x32_bf16 v[60:63], v[162:165], v[178:181], v[60:63]
	v_mfma_f32_16x16x32_bf16 v[56:59], v[170:173], v[178:181], v[56:59]
	v_mfma_f32_16x16x32_bf16 v[52:55], v[162:165], v[186:189], v[52:55]
	v_mfma_f32_16x16x32_bf16 v[48:51], v[170:173], v[186:189], v[48:51]
	v_mfma_f32_16x16x32_bf16 v[44:47], v[162:165], v[194:197], v[44:47]
	v_mfma_f32_16x16x32_bf16 v[40:43], v[170:173], v[194:197], v[40:43]
	v_mfma_f32_16x16x32_bf16 v[36:39], v[162:165], v[202:205], v[36:39]
	v_mfma_f32_16x16x32_bf16 v[32:35], v[170:173], v[202:205], v[32:35]
	v_mfma_f32_16x16x32_bf16 v[60:63], v[166:169], v[182:185], v[60:63]
	v_mfma_f32_16x16x32_bf16 v[56:59], v[174:177], v[182:185], v[56:59]
	v_mfma_f32_16x16x32_bf16 v[52:55], v[166:169], v[190:193], v[52:55]
	v_mfma_f32_16x16x32_bf16 v[48:51], v[174:177], v[190:193], v[48:51]
	v_mfma_f32_16x16x32_bf16 v[44:47], v[166:169], v[198:201], v[44:47]
	v_mfma_f32_16x16x32_bf16 v[40:43], v[174:177], v[198:201], v[40:43]
	v_mfma_f32_16x16x32_bf16 v[36:39], v[166:169], v[206:209], v[36:39]
	v_mfma_f32_16x16x32_bf16 v[32:35], v[174:177], v[206:209], v[32:35]
	s_barrier
	s_mov_b64 s[82:83], s[34:35]
	s_mov_b32 m0, s69
	v_lshl_add_u64 v[162:163], v[136:137], 0, s[82:83]
	global_load_lds_dwordx4 v[162:163], off
	v_lshl_add_u64 v[162:163], v[162:163], 0, s[0:1]
	s_mov_b32 m0, s70
	s_nop 0
	global_load_lds_dwordx4 v[162:163], off
	s_waitcnt vmcnt(6)
	s_barrier
	v_mfma_f32_16x16x32_bf16 v[28:31], v[210:213], v[178:181], v[28:31]
	v_mfma_f32_16x16x32_bf16 v[24:27], v[218:221], v[178:181], v[24:27]
	v_mfma_f32_16x16x32_bf16 v[20:23], v[210:213], v[186:189], v[20:23]
	v_mfma_f32_16x16x32_bf16 v[16:19], v[218:221], v[186:189], v[16:19]
	v_mfma_f32_16x16x32_bf16 v[12:15], v[210:213], v[194:197], v[12:15]
	v_mfma_f32_16x16x32_bf16 v[8:11], v[218:221], v[194:197], v[8:11]
	v_mfma_f32_16x16x32_bf16 v[4:7], v[210:213], v[202:205], v[4:7]
	v_mfma_f32_16x16x32_bf16 v[0:3], v[218:221], v[202:205], v[0:3]
	v_mfma_f32_16x16x32_bf16 v[28:31], v[214:217], v[182:185], v[28:31]
	v_mfma_f32_16x16x32_bf16 v[24:27], v[222:225], v[182:185], v[24:27]
	v_mfma_f32_16x16x32_bf16 v[20:23], v[214:217], v[190:193], v[20:23]
	v_mfma_f32_16x16x32_bf16 v[16:19], v[222:225], v[190:193], v[16:19]
	v_mfma_f32_16x16x32_bf16 v[12:15], v[214:217], v[198:201], v[12:15]
	v_mfma_f32_16x16x32_bf16 v[8:11], v[222:225], v[198:201], v[8:11]
	v_mfma_f32_16x16x32_bf16 v[4:7], v[214:217], v[206:209], v[4:7]
	v_mfma_f32_16x16x32_bf16 v[0:3], v[222:225], v[206:209], v[0:3]
	s_add_i32 s75, s75, 2
	s_add_u32 s34, s34, 0x100
	s_addc_u32 s35, s35, 0
	s_cmp_lt_u32 s75, 60
	s_barrier
	s_cbranch_scc1 .LBB0_96
	s_mov_b64 s[34:35], 0x101f80
	s_mov_b32 m0, s77
	ds_read_b128 v[162:165], v141
	ds_read_b128 v[166:169], v142
	ds_read_b128 v[170:173], v143
	ds_read_b128 v[174:177], v144
	ds_read_b128 v[178:181], v160
	ds_read_b128 v[182:185], v160 offset:1024
	ds_read_b128 v[186:189], v160 offset:2048
	ds_read_b128 v[190:193], v160 offset:3072
	ds_read_b128 v[194:197], v160 offset:4096
	ds_read_b128 v[198:201], v160 offset:5120
	ds_read_b128 v[202:205], v160 offset:6144
	ds_read_b128 v[206:209], v160 offset:7168
	s_nop 0
	v_lshl_add_u64 v[134:135], v[134:135], 0, s[34:35]
	global_load_lds_dwordx4 v[134:135], off
	v_lshl_add_u64 v[134:135], v[134:135], 0, s[0:1]
	s_mov_b32 m0, s68
	s_nop 0
	global_load_lds_dwordx4 v[134:135], off
	s_barrier
	s_waitcnt lgkmcnt(0)
	s_waitcnt lgkmcnt(0)
	v_mfma_f32_16x16x32_bf16 v[124:127], v[162:165], v[178:181], v[124:127]
	v_mfma_f32_16x16x32_bf16 v[116:119], v[162:165], v[186:189], v[116:119]
	v_mfma_f32_16x16x32_bf16 v[112:115], v[170:173], v[186:189], v[112:115]
	v_mfma_f32_16x16x32_bf16 v[100:103], v[162:165], v[202:205], v[100:103]
	v_mfma_f32_16x16x32_bf16 v[96:99], v[170:173], v[202:205], v[96:99]
	v_mfma_f32_16x16x32_bf16 v[124:127], v[166:169], v[182:185], v[124:127]
	v_mfma_f32_16x16x32_bf16 v[120:123], v[170:173], v[178:181], v[120:123]
	v_mfma_f32_16x16x32_bf16 v[116:119], v[166:169], v[190:193], v[116:119]
	v_mfma_f32_16x16x32_bf16 v[112:115], v[174:177], v[190:193], v[112:115]
	v_mfma_f32_16x16x32_bf16 v[108:111], v[162:165], v[194:197], v[108:111]
	v_mfma_f32_16x16x32_bf16 v[104:107], v[170:173], v[194:197], v[104:107]
	v_mfma_f32_16x16x32_bf16 v[100:103], v[166:169], v[206:209], v[100:103]
	v_mfma_f32_16x16x32_bf16 v[96:99], v[174:177], v[206:209], v[96:99]
	v_mfma_f32_16x16x32_bf16 v[134:137], v[174:177], v[182:185], v[120:123]
	v_mfma_f32_16x16x32_bf16 v[210:213], v[166:169], v[198:201], v[108:111]
	v_mfma_f32_16x16x32_bf16 v[214:217], v[174:177], v[198:201], v[104:107]
	s_barrier
	s_nop 0
	ds_read_b128 v[104:107], v145
	ds_read_b128 v[108:111], v146
	ds_read_b128 v[120:123], v147
	ds_read_b128 v[218:221], v148
	s_barrier
	s_waitcnt lgkmcnt(0)
	s_waitcnt lgkmcnt(0)
	v_mfma_f32_16x16x32_bf16 v[84:87], v[104:107], v[186:189], v[84:87]
	v_mfma_f32_16x16x32_bf16 v[80:83], v[120:123], v[186:189], v[80:83]
	v_mfma_f32_16x16x32_bf16 v[68:71], v[104:107], v[202:205], v[68:71]
	v_mfma_f32_16x16x32_bf16 v[92:95], v[104:107], v[178:181], v[92:95]
	v_mfma_f32_16x16x32_bf16 v[88:91], v[120:123], v[178:181], v[88:91]
	v_mfma_f32_16x16x32_bf16 v[84:87], v[108:111], v[190:193], v[84:87]
	v_mfma_f32_16x16x32_bf16 v[80:83], v[218:221], v[190:193], v[80:83]
	v_mfma_f32_16x16x32_bf16 v[76:79], v[104:107], v[194:197], v[76:79]
	v_mfma_f32_16x16x32_bf16 v[72:75], v[120:123], v[194:197], v[72:75]
	v_mfma_f32_16x16x32_bf16 v[68:71], v[108:111], v[206:209], v[68:71]
	v_mfma_f32_16x16x32_bf16 v[64:67], v[120:123], v[202:205], v[64:67]
	v_mfma_f32_16x16x32_bf16 v[222:225], v[108:111], v[182:185], v[92:95]
	v_mfma_f32_16x16x32_bf16 v[178:181], v[218:221], v[182:185], v[88:91]
	v_mfma_f32_16x16x32_bf16 v[182:185], v[108:111], v[198:201], v[76:79]
	v_mfma_f32_16x16x32_bf16 v[186:189], v[218:221], v[198:201], v[72:75]
	v_mfma_f32_16x16x32_bf16 v[190:193], v[218:221], v[206:209], v[64:67]
	s_barrier
	s_nop 0
	ds_read_b128 v[64:67], v160 offset:16384
	ds_read_b128 v[72:75], v160 offset:17408
	ds_read_b128 v[76:79], v160 offset:18432
	ds_read_b128 v[88:91], v160 offset:19456
	ds_read_b128 v[92:95], v160 offset:20480
	ds_read_b128 v[194:197], v160 offset:21504
	ds_read_b128 v[198:201], v160 offset:22528
	ds_read_b128 v[202:205], v160 offset:23552
	s_waitcnt vmcnt(4)
	s_barrier
	s_waitcnt lgkmcnt(0)
	s_waitcnt lgkmcnt(0)
	v_mfma_f32_16x16x32_bf16 v[60:63], v[162:165], v[64:67], v[60:63]
	v_mfma_f32_16x16x32_bf16 v[52:55], v[162:165], v[76:79], v[52:55]
	v_mfma_f32_16x16x32_bf16 v[48:51], v[170:173], v[76:79], v[48:51]
	v_mfma_f32_16x16x32_bf16 v[36:39], v[162:165], v[198:201], v[36:39]
	v_mfma_f32_16x16x32_bf16 v[32:35], v[170:173], v[198:201], v[32:35]
	v_mfma_f32_16x16x32_bf16 v[60:63], v[166:169], v[72:75], v[60:63]
	v_mfma_f32_16x16x32_bf16 v[56:59], v[170:173], v[64:67], v[56:59]
	v_mfma_f32_16x16x32_bf16 v[52:55], v[166:169], v[88:91], v[52:55]
	v_mfma_f32_16x16x32_bf16 v[48:51], v[174:177], v[88:91], v[48:51]
	v_mfma_f32_16x16x32_bf16 v[44:47], v[162:165], v[92:95], v[44:47]
	v_mfma_f32_16x16x32_bf16 v[40:43], v[170:173], v[92:95], v[40:43]
	v_mfma_f32_16x16x32_bf16 v[36:39], v[166:169], v[202:205], v[36:39]
	v_mfma_f32_16x16x32_bf16 v[32:35], v[174:177], v[202:205], v[32:35]
	v_mfma_f32_16x16x32_bf16 v[206:209], v[174:177], v[72:75], v[56:59]
	v_mfma_f32_16x16x32_bf16 v[226:229], v[166:169], v[194:197], v[44:47]
	v_mfma_f32_16x16x32_bf16 v[230:233], v[174:177], v[194:197], v[40:43]
	v_mfma_f32_16x16x32_bf16 v[20:23], v[104:107], v[76:79], v[20:23]
	v_mfma_f32_16x16x32_bf16 v[16:19], v[120:123], v[76:79], v[16:19]
	v_mfma_f32_16x16x32_bf16 v[4:7], v[104:107], v[198:201], v[4:7]
	v_mfma_f32_16x16x32_bf16 v[28:31], v[104:107], v[64:67], v[28:31]
	v_mfma_f32_16x16x32_bf16 v[24:27], v[120:123], v[64:67], v[24:27]
	v_mfma_f32_16x16x32_bf16 v[20:23], v[108:111], v[88:91], v[20:23]
	v_mfma_f32_16x16x32_bf16 v[16:19], v[218:221], v[88:91], v[16:19]
	v_mfma_f32_16x16x32_bf16 v[12:15], v[104:107], v[92:95], v[12:15]
	v_mfma_f32_16x16x32_bf16 v[8:11], v[120:123], v[92:95], v[8:11]
	v_mfma_f32_16x16x32_bf16 v[4:7], v[108:111], v[202:205], v[4:7]
	v_mfma_f32_16x16x32_bf16 v[0:3], v[120:123], v[198:201], v[0:3]
	v_mfma_f32_16x16x32_bf16 v[162:165], v[108:111], v[72:75], v[28:31]
	v_mfma_f32_16x16x32_bf16 v[166:169], v[218:221], v[72:75], v[24:27]
	v_mfma_f32_16x16x32_bf16 v[170:173], v[108:111], v[194:197], v[12:15]
	v_mfma_f32_16x16x32_bf16 v[174:177], v[218:221], v[194:197], v[8:11]
	v_mfma_f32_16x16x32_bf16 v[194:197], v[218:221], v[202:205], v[0:3]
	s_barrier
	s_nop 0
	ds_read_b128 v[0:3], v149
	ds_read_b128 v[8:11], v150
	ds_read_b128 v[12:15], v151
	ds_read_b128 v[198:201], v152
	ds_read_b128 v[24:27], v160 offset:32768
	ds_read_b128 v[28:31], v160 offset:33792
	ds_read_b128 v[40:43], v160 offset:34816
	ds_read_b128 v[44:47], v160 offset:35840
	ds_read_b128 v[56:59], v160 offset:36864
	ds_read_b128 v[64:67], v160 offset:37888
	ds_read_b128 v[202:205], v160 offset:38912
	ds_read_b128 v[218:221], v160 offset:39936
	s_waitcnt vmcnt(2)
	s_barrier
	s_waitcnt lgkmcnt(0)
	s_waitcnt lgkmcnt(0)
	v_mfma_f32_16x16x32_bf16 v[72:75], v[0:3], v[24:27], v[124:127]
	v_mfma_f32_16x16x32_bf16 v[120:123], v[8:11], v[28:31], v[72:75]
	v_mfma_f32_16x16x32_bf16 v[72:75], v[12:15], v[24:27], v[134:137]
	v_mfma_f32_16x16x32_bf16 v[124:127], v[198:201], v[28:31], v[72:75]
	v_mfma_f32_16x16x32_bf16 v[72:75], v[0:3], v[40:43], v[116:119]
	v_mfma_f32_16x16x32_bf16 v[104:107], v[8:11], v[44:47], v[72:75]
	v_mfma_f32_16x16x32_bf16 v[72:75], v[12:15], v[40:43], v[112:115]
	v_mfma_f32_16x16x32_bf16 v[108:111], v[198:201], v[44:47], v[72:75]
	v_mfma_f32_16x16x32_bf16 v[72:75], v[0:3], v[56:59], v[210:213]
	v_mfma_f32_16x16x32_bf16 v[88:91], v[8:11], v[64:67], v[72:75]
	v_mfma_f32_16x16x32_bf16 v[72:75], v[12:15], v[56:59], v[214:217]
	v_mfma_f32_16x16x32_bf16 v[92:95], v[198:201], v[64:67], v[72:75]
	v_mfma_f32_16x16x32_bf16 v[72:75], v[0:3], v[202:205], v[100:103]
	v_mfma_f32_16x16x32_bf16 v[76:79], v[12:15], v[202:205], v[96:99]
	v_mfma_f32_16x16x32_bf16 v[72:75], v[8:11], v[218:221], v[72:75]
	v_mfma_f32_16x16x32_bf16 v[76:79], v[198:201], v[218:221], v[76:79]
	s_barrier
	ds_read_b128 v[134:137], v153
	ds_read_b128 v[210:213], v154
	ds_read_b128 v[214:217], v155
	ds_read_b128 v[234:237], v156
	s_waitcnt vmcnt(0)
	s_barrier
	s_waitcnt lgkmcnt(0)
	s_waitcnt lgkmcnt(0)
	v_mfma_f32_16x16x32_bf16 v[96:99], v[134:137], v[24:27], v[222:225]
	v_mfma_f32_16x16x32_bf16 v[24:27], v[214:217], v[24:27], v[178:181]
	v_mfma_f32_16x16x32_bf16 v[116:119], v[234:237], v[28:31], v[24:27]
	v_mfma_f32_16x16x32_bf16 v[24:27], v[134:137], v[40:43], v[84:87]
	v_mfma_f32_16x16x32_bf16 v[112:115], v[210:213], v[28:31], v[96:99]
	v_mfma_f32_16x16x32_bf16 v[96:99], v[210:213], v[44:47], v[24:27]
	v_mfma_f32_16x16x32_bf16 v[24:27], v[214:217], v[40:43], v[80:83]
	v_mfma_f32_16x16x32_bf16 v[100:103], v[234:237], v[44:47], v[24:27]
	v_mfma_f32_16x16x32_bf16 v[24:27], v[134:137], v[56:59], v[182:185]
	v_mfma_f32_16x16x32_bf16 v[80:83], v[210:213], v[64:67], v[24:27]
	v_mfma_f32_16x16x32_bf16 v[24:27], v[214:217], v[56:59], v[186:189]
	v_mfma_f32_16x16x32_bf16 v[84:87], v[234:237], v[64:67], v[24:27]
	v_mfma_f32_16x16x32_bf16 v[24:27], v[134:137], v[202:205], v[68:71]
	v_mfma_f32_16x16x32_bf16 v[64:67], v[210:213], v[218:221], v[24:27]
	v_mfma_f32_16x16x32_bf16 v[24:27], v[214:217], v[202:205], v[190:193]
	v_mfma_f32_16x16x32_bf16 v[68:71], v[234:237], v[218:221], v[24:27]
	s_barrier
	ds_read_b128 v[178:181], v160 offset:49152
	ds_read_b128 v[182:185], v160 offset:50176
	ds_read_b128 v[186:189], v160 offset:51200
	ds_read_b128 v[190:193], v160 offset:52224
	ds_read_b128 v[202:205], v160 offset:53248
	ds_read_b128 v[218:221], v160 offset:54272
	ds_read_b128 v[222:225], v160 offset:55296
	ds_read_b128 v[238:241], v160 offset:56320
	s_barrier
	s_waitcnt lgkmcnt(0)
	s_waitcnt lgkmcnt(0)
	v_mfma_f32_16x16x32_bf16 v[24:27], v[0:3], v[178:181], v[60:63]
	v_mfma_f32_16x16x32_bf16 v[56:59], v[8:11], v[182:185], v[24:27]
	v_mfma_f32_16x16x32_bf16 v[24:27], v[12:15], v[178:181], v[206:209]
	v_mfma_f32_16x16x32_bf16 v[60:63], v[198:201], v[182:185], v[24:27]
	v_mfma_f32_16x16x32_bf16 v[24:27], v[0:3], v[186:189], v[52:55]
	v_mfma_f32_16x16x32_bf16 v[40:43], v[8:11], v[190:193], v[24:27]
	v_mfma_f32_16x16x32_bf16 v[24:27], v[12:15], v[186:189], v[48:51]
	v_mfma_f32_16x16x32_bf16 v[44:47], v[198:201], v[190:193], v[24:27]
	v_mfma_f32_16x16x32_bf16 v[24:27], v[0:3], v[202:205], v[226:229]
	v_mfma_f32_16x16x32_bf16 v[0:3], v[0:3], v[222:225], v[36:39]
	v_mfma_f32_16x16x32_bf16 v[24:27], v[8:11], v[218:221], v[24:27]
	v_mfma_f32_16x16x32_bf16 v[28:31], v[12:15], v[202:205], v[230:233]
	v_mfma_f32_16x16x32_bf16 v[8:11], v[8:11], v[238:241], v[0:3]
	v_mfma_f32_16x16x32_bf16 v[0:3], v[12:15], v[222:225], v[32:35]
	v_mfma_f32_16x16x32_bf16 v[28:31], v[198:201], v[218:221], v[28:31]
	v_mfma_f32_16x16x32_bf16 v[12:15], v[198:201], v[238:241], v[0:3]
	v_mfma_f32_16x16x32_bf16 v[0:3], v[134:137], v[178:181], v[162:165]
	v_mfma_f32_16x16x32_bf16 v[48:51], v[210:213], v[182:185], v[0:3]
	v_mfma_f32_16x16x32_bf16 v[0:3], v[214:217], v[178:181], v[166:169]
	v_mfma_f32_16x16x32_bf16 v[52:55], v[234:237], v[182:185], v[0:3]
	v_mfma_f32_16x16x32_bf16 v[0:3], v[134:137], v[186:189], v[20:23]
	v_mfma_f32_16x16x32_bf16 v[32:35], v[210:213], v[190:193], v[0:3]
	v_mfma_f32_16x16x32_bf16 v[0:3], v[214:217], v[186:189], v[16:19]
	v_mfma_f32_16x16x32_bf16 v[36:39], v[234:237], v[190:193], v[0:3]
	v_mfma_f32_16x16x32_bf16 v[0:3], v[134:137], v[202:205], v[170:173]
	v_mfma_f32_16x16x32_bf16 v[16:19], v[210:213], v[218:221], v[0:3]
	v_mfma_f32_16x16x32_bf16 v[0:3], v[214:217], v[202:205], v[174:177]
	v_mfma_f32_16x16x32_bf16 v[20:23], v[234:237], v[218:221], v[0:3]
	v_mfma_f32_16x16x32_bf16 v[0:3], v[134:137], v[222:225], v[4:7]
	v_mfma_f32_16x16x32_bf16 v[4:7], v[214:217], v[222:225], v[194:197]
	v_mfma_f32_16x16x32_bf16 v[0:3], v[210:213], v[238:241], v[0:3]
	v_mfma_f32_16x16x32_bf16 v[4:7], v[234:237], v[238:241], v[4:7]
	s_barrier
	s_and_saveexec_b64 s[34:35], s[4:5]
	s_cbranch_execz .LBB0_99
	s_barrier

.LBB0_291:
	ds_read_b128 v[160:163], v137
	ds_read_b128 v[164:167], v138
	ds_read_b128 v[168:171], v139
	ds_read_b128 v[172:175], v140
	s_add_u32 s80, s18, 0xffffff80
	s_addc_u32 s81, s19, -1
	s_mov_b32 m0, s72
	ds_read_b128 v[176:179], v158
	ds_read_b128 v[180:183], v158 offset:1024
	ds_read_b128 v[184:187], v158 offset:2048
	ds_read_b128 v[188:191], v158 offset:3072
	ds_read_b128 v[192:195], v158 offset:4096
	ds_read_b128 v[196:199], v158 offset:5120
	ds_read_b128 v[200:203], v158 offset:6144
	ds_read_b128 v[204:207], v158 offset:7168
	s_nop 0
	v_lshl_add_u64 v[208:209], v[132:133], 0, s[80:81]
	global_load_lds_dwordx4 v[208:209], off
	v_lshl_add_u64 v[208:209], v[208:209], 0, s[10:11]
	s_mov_b32 m0, s62
	s_nop 0
	global_load_lds_dwordx4 v[208:209], off
	s_waitcnt lgkmcnt(8)
	s_barrier
	s_waitcnt lgkmcnt(0)
	s_waitcnt lgkmcnt(0)
	v_mfma_f32_16x16x32_bf16 v[124:127], v[160:163], v[176:179], v[124:127]
	v_mfma_f32_16x16x32_bf16 v[120:123], v[168:171], v[176:179], v[120:123]
	v_mfma_f32_16x16x32_bf16 v[116:119], v[160:163], v[184:187], v[116:119]
	v_mfma_f32_16x16x32_bf16 v[112:115], v[168:171], v[184:187], v[112:115]
	v_mfma_f32_16x16x32_bf16 v[108:111], v[160:163], v[192:195], v[108:111]
	v_mfma_f32_16x16x32_bf16 v[104:107], v[168:171], v[192:195], v[104:107]
	v_mfma_f32_16x16x32_bf16 v[100:103], v[160:163], v[200:203], v[100:103]
	v_mfma_f32_16x16x32_bf16 v[96:99], v[168:171], v[200:203], v[96:99]
	v_mfma_f32_16x16x32_bf16 v[124:127], v[164:167], v[180:183], v[124:127]
	v_mfma_f32_16x16x32_bf16 v[120:123], v[172:175], v[180:183], v[120:123]
	v_mfma_f32_16x16x32_bf16 v[116:119], v[164:167], v[188:191], v[116:119]
	v_mfma_f32_16x16x32_bf16 v[112:115], v[172:175], v[188:191], v[112:115]
	v_mfma_f32_16x16x32_bf16 v[108:111], v[164:167], v[196:199], v[108:111]
	v_mfma_f32_16x16x32_bf16 v[104:107], v[172:175], v[196:199], v[104:107]
	v_mfma_f32_16x16x32_bf16 v[100:103], v[164:167], v[204:207], v[100:103]
	v_mfma_f32_16x16x32_bf16 v[96:99], v[172:175], v[204:207], v[96:99]
	s_barrier
	s_add_u32 s80, s18, 0xfffa0000
	s_addc_u32 s81, s19, -1
	s_mov_b64 s[82:83], s[80:81]
	s_mov_b32 m0, s67
	ds_read_b128 v[208:211], v141
	ds_read_b128 v[212:215], v142
	ds_read_b128 v[216:219], v143
	ds_read_b128 v[220:223], v144
	s_nop 0
	v_lshl_add_u64 v[224:225], v[134:135], 0, s[82:83]
	global_load_lds_dwordx4 v[224:225], off
	v_lshl_add_u64 v[224:225], v[224:225], 0, s[8:9]
	s_mov_b32 m0, s68
	s_nop 0
	global_load_lds_dwordx4 v[224:225], off
	s_barrier
	s_waitcnt lgkmcnt(0)
	s_waitcnt lgkmcnt(0)
	v_mfma_f32_16x16x32_bf16 v[92:95], v[208:211], v[176:179], v[92:95]
	v_mfma_f32_16x16x32_bf16 v[88:91], v[216:219], v[176:179], v[88:91]
	v_mfma_f32_16x16x32_bf16 v[84:87], v[208:211], v[184:187], v[84:87]
	v_mfma_f32_16x16x32_bf16 v[80:83], v[216:219], v[184:187], v[80:83]
	v_mfma_f32_16x16x32_bf16 v[76:79], v[208:211], v[192:195], v[76:79]
	v_mfma_f32_16x16x32_bf16 v[72:75], v[216:219], v[192:195], v[72:75]
	v_mfma_f32_16x16x32_bf16 v[68:71], v[208:211], v[200:203], v[68:71]
	v_mfma_f32_16x16x32_bf16 v[64:67], v[216:219], v[200:203], v[64:67]
	v_mfma_f32_16x16x32_bf16 v[92:95], v[212:215], v[180:183], v[92:95]
	v_mfma_f32_16x16x32_bf16 v[88:91], v[220:223], v[180:183], v[88:91]
	v_mfma_f32_16x16x32_bf16 v[84:87], v[212:215], v[188:191], v[84:87]
	v_mfma_f32_16x16x32_bf16 v[80:83], v[220:223], v[188:191], v[80:83]
	v_mfma_f32_16x16x32_bf16 v[76:79], v[212:215], v[196:199], v[76:79]
	v_mfma_f32_16x16x32_bf16 v[72:75], v[220:223], v[196:199], v[72:75]
	v_mfma_f32_16x16x32_bf16 v[68:71], v[212:215], v[204:207], v[68:71]
	v_mfma_f32_16x16x32_bf16 v[64:67], v[220:223], v[204:207], v[64:67]
	s_mov_b32 m0, s31
	s_barrier
	ds_read_b128 v[176:179], v158 offset:16384
	ds_read_b128 v[180:183], v158 offset:17408
	ds_read_b128 v[184:187], v158 offset:18432
	ds_read_b128 v[188:191], v158 offset:19456
	ds_read_b128 v[192:195], v158 offset:20480
	ds_read_b128 v[196:199], v158 offset:21504
	ds_read_b128 v[200:203], v158 offset:22528
	ds_read_b128 v[204:207], v158 offset:23552
	s_nop 0
	v_lshl_add_u64 v[224:225], v[132:133], 0, s[80:81]
	global_load_lds_dwordx4 v[224:225], off
	v_lshl_add_u64 v[224:225], v[224:225], 0, s[10:11]
	s_mov_b32 m0, s73
	s_nop 0
	global_load_lds_dwordx4 v[224:225], off
	s_barrier
	s_waitcnt lgkmcnt(0)
	s_waitcnt lgkmcnt(0)
	v_mfma_f32_16x16x32_bf16 v[60:63], v[160:163], v[176:179], v[60:63]
	v_mfma_f32_16x16x32_bf16 v[56:59], v[168:171], v[176:179], v[56:59]
	v_mfma_f32_16x16x32_bf16 v[52:55], v[160:163], v[184:187], v[52:55]
	v_mfma_f32_16x16x32_bf16 v[48:51], v[168:171], v[184:187], v[48:51]
	v_mfma_f32_16x16x32_bf16 v[44:47], v[160:163], v[192:195], v[44:47]
	v_mfma_f32_16x16x32_bf16 v[40:43], v[168:171], v[192:195], v[40:43]
	v_mfma_f32_16x16x32_bf16 v[36:39], v[160:163], v[200:203], v[36:39]
	v_mfma_f32_16x16x32_bf16 v[32:35], v[168:171], v[200:203], v[32:35]
	v_mfma_f32_16x16x32_bf16 v[60:63], v[164:167], v[180:183], v[60:63]
	v_mfma_f32_16x16x32_bf16 v[56:59], v[172:175], v[180:183], v[56:59]
	v_mfma_f32_16x16x32_bf16 v[52:55], v[164:167], v[188:191], v[52:55]
	v_mfma_f32_16x16x32_bf16 v[48:51], v[172:175], v[188:191], v[48:51]
	v_mfma_f32_16x16x32_bf16 v[44:47], v[164:167], v[196:199], v[44:47]
	v_mfma_f32_16x16x32_bf16 v[40:43], v[172:175], v[196:199], v[40:43]
	v_mfma_f32_16x16x32_bf16 v[36:39], v[164:167], v[204:207], v[36:39]
	v_mfma_f32_16x16x32_bf16 v[32:35], v[172:175], v[204:207], v[32:35]
	s_barrier
	s_add_u32 s80, s18, 0xfffd0000
	s_addc_u32 s81, s19, -1
	s_mov_b32 m0, s69
	s_nop 0
	v_lshl_add_u64 v[160:161], v[134:135], 0, s[80:81]
	global_load_lds_dwordx4 v[160:161], off
	v_lshl_add_u64 v[160:161], v[160:161], 0, s[8:9]
	s_mov_b32 m0, s70
	s_nop 0
	global_load_lds_dwordx4 v[160:161], off
	s_waitcnt vmcnt(6)
	s_barrier
	v_mfma_f32_16x16x32_bf16 v[28:31], v[208:211], v[176:179], v[28:31]
	v_mfma_f32_16x16x32_bf16 v[24:27], v[216:219], v[176:179], v[24:27]
	v_mfma_f32_16x16x32_bf16 v[20:23], v[208:211], v[184:187], v[20:23]
	v_mfma_f32_16x16x32_bf16 v[16:19], v[216:219], v[184:187], v[16:19]
	v_mfma_f32_16x16x32_bf16 v[12:15], v[208:211], v[192:195], v[12:15]
	v_mfma_f32_16x16x32_bf16 v[8:11], v[216:219], v[192:195], v[8:11]
	v_mfma_f32_16x16x32_bf16 v[4:7], v[208:211], v[200:203], v[4:7]
	v_mfma_f32_16x16x32_bf16 v[0:3], v[216:219], v[200:203], v[0:3]
	v_mfma_f32_16x16x32_bf16 v[28:31], v[212:215], v[180:183], v[28:31]
	v_mfma_f32_16x16x32_bf16 v[24:27], v[220:223], v[180:183], v[24:27]
	v_mfma_f32_16x16x32_bf16 v[20:23], v[212:215], v[188:191], v[20:23]
	v_mfma_f32_16x16x32_bf16 v[16:19], v[220:223], v[188:191], v[16:19]
	v_mfma_f32_16x16x32_bf16 v[12:15], v[212:215], v[196:199], v[12:15]
	v_mfma_f32_16x16x32_bf16 v[8:11], v[220:223], v[196:199], v[8:11]
	v_mfma_f32_16x16x32_bf16 v[4:7], v[212:215], v[204:207], v[4:7]
	v_mfma_f32_16x16x32_bf16 v[0:3], v[220:223], v[204:207], v[0:3]
	s_barrier
	ds_read_b128 v[160:163], v145
	ds_read_b128 v[164:167], v146
	ds_read_b128 v[168:171], v147
	ds_read_b128 v[172:175], v148
	s_mov_b64 s[80:81], s[18:19]
	s_mov_b32 m0, s74
	ds_read_b128 v[176:179], v158 offset:32768
	ds_read_b128 v[180:183], v158 offset:33792
	ds_read_b128 v[184:187], v158 offset:34816
	ds_read_b128 v[188:191], v158 offset:35840
	ds_read_b128 v[192:195], v158 offset:36864
	ds_read_b128 v[196:199], v158 offset:37888
	ds_read_b128 v[200:203], v158 offset:38912
	ds_read_b128 v[204:207], v158 offset:39936
	s_nop 0
	v_lshl_add_u64 v[208:209], v[132:133], 0, s[80:81]
	global_load_lds_dwordx4 v[208:209], off
	v_lshl_add_u64 v[208:209], v[208:209], 0, s[10:11]
	s_mov_b32 m0, s75
	s_nop 0
	global_load_lds_dwordx4 v[208:209], off
	s_waitcnt lgkmcnt(8)
	s_barrier
	s_waitcnt lgkmcnt(0)
	s_waitcnt lgkmcnt(0)
	v_mfma_f32_16x16x32_bf16 v[124:127], v[160:163], v[176:179], v[124:127]
	v_mfma_f32_16x16x32_bf16 v[120:123], v[168:171], v[176:179], v[120:123]
	v_mfma_f32_16x16x32_bf16 v[116:119], v[160:163], v[184:187], v[116:119]
	v_mfma_f32_16x16x32_bf16 v[112:115], v[168:171], v[184:187], v[112:115]
	v_mfma_f32_16x16x32_bf16 v[108:111], v[160:163], v[192:195], v[108:111]
	v_mfma_f32_16x16x32_bf16 v[104:107], v[168:171], v[192:195], v[104:107]
	v_mfma_f32_16x16x32_bf16 v[100:103], v[160:163], v[200:203], v[100:103]
	v_mfma_f32_16x16x32_bf16 v[96:99], v[168:171], v[200:203], v[96:99]
	v_mfma_f32_16x16x32_bf16 v[124:127], v[164:167], v[180:183], v[124:127]
	v_mfma_f32_16x16x32_bf16 v[120:123], v[172:175], v[180:183], v[120:123]
	v_mfma_f32_16x16x32_bf16 v[116:119], v[164:167], v[188:191], v[116:119]
	v_mfma_f32_16x16x32_bf16 v[112:115], v[172:175], v[188:191], v[112:115]
	v_mfma_f32_16x16x32_bf16 v[108:111], v[164:167], v[196:199], v[108:111]
	v_mfma_f32_16x16x32_bf16 v[104:107], v[172:175], v[196:199], v[104:107]
	v_mfma_f32_16x16x32_bf16 v[100:103], v[164:167], v[204:207], v[100:103]
	v_mfma_f32_16x16x32_bf16 v[96:99], v[172:175], v[204:207], v[96:99]
	s_barrier
	s_add_u32 s80, s18, 0xfffa0080
	s_addc_u32 s81, s19, -1
	s_mov_b64 s[82:83], s[80:81]
	s_mov_b32 m0, s34
	ds_read_b128 v[208:211], v149
	ds_read_b128 v[212:215], v150
	ds_read_b128 v[216:219], v151
	ds_read_b128 v[220:223], v152
	s_nop 0
	v_lshl_add_u64 v[224:225], v[134:135], 0, s[82:83]
	global_load_lds_dwordx4 v[224:225], off
	v_lshl_add_u64 v[224:225], v[224:225], 0, s[8:9]
	s_mov_b32 m0, s35
	s_nop 0
	global_load_lds_dwordx4 v[224:225], off
	s_barrier
	s_waitcnt lgkmcnt(0)
	s_waitcnt lgkmcnt(0)
	v_mfma_f32_16x16x32_bf16 v[92:95], v[208:211], v[176:179], v[92:95]
	v_mfma_f32_16x16x32_bf16 v[88:91], v[216:219], v[176:179], v[88:91]
	v_mfma_f32_16x16x32_bf16 v[84:87], v[208:211], v[184:187], v[84:87]
	v_mfma_f32_16x16x32_bf16 v[80:83], v[216:219], v[184:187], v[80:83]
	v_mfma_f32_16x16x32_bf16 v[76:79], v[208:211], v[192:195], v[76:79]
	v_mfma_f32_16x16x32_bf16 v[72:75], v[216:219], v[192:195], v[72:75]
	v_mfma_f32_16x16x32_bf16 v[68:71], v[208:211], v[200:203], v[68:71]
	v_mfma_f32_16x16x32_bf16 v[64:67], v[216:219], v[200:203], v[64:67]
	v_mfma_f32_16x16x32_bf16 v[92:95], v[212:215], v[180:183], v[92:95]
	v_mfma_f32_16x16x32_bf16 v[88:91], v[220:223], v[180:183], v[88:91]
	v_mfma_f32_16x16x32_bf16 v[84:87], v[212:215], v[188:191], v[84:87]
	v_mfma_f32_16x16x32_bf16 v[80:83], v[220:223], v[188:191], v[80:83]
	v_mfma_f32_16x16x32_bf16 v[76:79], v[212:215], v[196:199], v[76:79]
	v_mfma_f32_16x16x32_bf16 v[72:75], v[220:223], v[196:199], v[72:75]
	v_mfma_f32_16x16x32_bf16 v[68:71], v[212:215], v[204:207], v[68:71]
	v_mfma_f32_16x16x32_bf16 v[64:67], v[220:223], v[204:207], v[64:67]
	s_mov_b32 m0, s54
	s_barrier
	ds_read_b128 v[176:179], v158 offset:49152
	ds_read_b128 v[180:183], v158 offset:50176
	ds_read_b128 v[184:187], v158 offset:51200
	ds_read_b128 v[188:191], v158 offset:52224
	ds_read_b128 v[192:195], v158 offset:53248
	ds_read_b128 v[196:199], v158 offset:54272
	ds_read_b128 v[200:203], v158 offset:55296
	ds_read_b128 v[204:207], v158 offset:56320
	s_nop 0
	v_lshl_add_u64 v[224:225], v[132:133], 0, s[80:81]
	global_load_lds_dwordx4 v[224:225], off
	v_lshl_add_u64 v[224:225], v[224:225], 0, s[10:11]
	s_mov_b32 m0, s55
	s_nop 0
	global_load_lds_dwordx4 v[224:225], off
	s_barrier
	s_waitcnt lgkmcnt(0)
	s_waitcnt lgkmcnt(0)
	v_mfma_f32_16x16x32_bf16 v[60:63], v[160:163], v[176:179], v[60:63]
	v_mfma_f32_16x16x32_bf16 v[56:59], v[168:171], v[176:179], v[56:59]
	v_mfma_f32_16x16x32_bf16 v[52:55], v[160:163], v[184:187], v[52:55]
	v_mfma_f32_16x16x32_bf16 v[48:51], v[168:171], v[184:187], v[48:51]
	v_mfma_f32_16x16x32_bf16 v[44:47], v[160:163], v[192:195], v[44:47]
	v_mfma_f32_16x16x32_bf16 v[40:43], v[168:171], v[192:195], v[40:43]
	v_mfma_f32_16x16x32_bf16 v[36:39], v[160:163], v[200:203], v[36:39]
	v_mfma_f32_16x16x32_bf16 v[32:35], v[168:171], v[200:203], v[32:35]
	v_mfma_f32_16x16x32_bf16 v[60:63], v[164:167], v[180:183], v[60:63]
	v_mfma_f32_16x16x32_bf16 v[56:59], v[172:175], v[180:183], v[56:59]
	v_mfma_f32_16x16x32_bf16 v[52:55], v[164:167], v[188:191], v[52:55]
	v_mfma_f32_16x16x32_bf16 v[48:51], v[172:175], v[188:191], v[48:51]
	v_mfma_f32_16x16x32_bf16 v[44:47], v[164:167], v[196:199], v[44:47]
	v_mfma_f32_16x16x32_bf16 v[40:43], v[172:175], v[196:199], v[40:43]
	v_mfma_f32_16x16x32_bf16 v[36:39], v[164:167], v[204:207], v[36:39]
	v_mfma_f32_16x16x32_bf16 v[32:35], v[172:175], v[204:207], v[32:35]
	s_barrier
	s_add_u32 s80, s18, 0xfffd0080
	s_addc_u32 s81, s19, -1
	s_mov_b32 m0, s63
	s_nop 0
	v_lshl_add_u64 v[160:161], v[134:135], 0, s[80:81]
	global_load_lds_dwordx4 v[160:161], off
	v_lshl_add_u64 v[160:161], v[160:161], 0, s[8:9]
	s_mov_b32 m0, s66
	s_nop 0
	global_load_lds_dwordx4 v[160:161], off
	s_waitcnt vmcnt(6)
	s_barrier
	v_mfma_f32_16x16x32_bf16 v[28:31], v[208:211], v[176:179], v[28:31]
	v_mfma_f32_16x16x32_bf16 v[24:27], v[216:219], v[176:179], v[24:27]
	v_mfma_f32_16x16x32_bf16 v[20:23], v[208:211], v[184:187], v[20:23]
	v_mfma_f32_16x16x32_bf16 v[16:19], v[216:219], v[184:187], v[16:19]
	v_mfma_f32_16x16x32_bf16 v[12:15], v[208:211], v[192:195], v[12:15]
	v_mfma_f32_16x16x32_bf16 v[8:11], v[216:219], v[192:195], v[8:11]
	v_mfma_f32_16x16x32_bf16 v[4:7], v[208:211], v[200:203], v[4:7]
	v_mfma_f32_16x16x32_bf16 v[0:3], v[216:219], v[200:203], v[0:3]
	v_mfma_f32_16x16x32_bf16 v[28:31], v[212:215], v[180:183], v[28:31]
	v_mfma_f32_16x16x32_bf16 v[24:27], v[220:223], v[180:183], v[24:27]
	v_mfma_f32_16x16x32_bf16 v[20:23], v[212:215], v[188:191], v[20:23]
	v_mfma_f32_16x16x32_bf16 v[16:19], v[220:223], v[188:191], v[16:19]
	v_mfma_f32_16x16x32_bf16 v[12:15], v[212:215], v[196:199], v[12:15]
	v_mfma_f32_16x16x32_bf16 v[8:11], v[220:223], v[196:199], v[8:11]
	v_mfma_f32_16x16x32_bf16 v[4:7], v[212:215], v[204:207], v[4:7]
	v_mfma_f32_16x16x32_bf16 v[0:3], v[220:223], v[204:207], v[0:3]
	s_add_i32 s71, s71, 2
	s_add_u32 s18, s18, 0x100
	s_addc_u32 s19, s19, 0
	s_cmp_lt_u32 s71, 8
	s_barrier
	s_cbranch_scc1 .LBB0_291
	s_mov_b64 s[18:19], 0x60580
	s_mov_b32 m0, s72
	ds_read_b128 v[160:163], v137
	ds_read_b128 v[164:167], v138
	ds_read_b128 v[168:171], v139
	ds_read_b128 v[172:175], v140
	ds_read_b128 v[176:179], v158
	ds_read_b128 v[180:183], v158 offset:1024
	ds_read_b128 v[184:187], v158 offset:2048
	ds_read_b128 v[188:191], v158 offset:3072
	ds_read_b128 v[192:195], v158 offset:4096
	ds_read_b128 v[196:199], v158 offset:5120
	ds_read_b128 v[200:203], v158 offset:6144
	ds_read_b128 v[204:207], v158 offset:7168
	s_nop 0
	v_lshl_add_u64 v[132:133], v[132:133], 0, s[18:19]
	global_load_lds_dwordx4 v[132:133], off
	v_lshl_add_u64 v[132:133], v[132:133], 0, s[10:11]
	s_mov_b32 m0, s62
	s_nop 0
	global_load_lds_dwordx4 v[132:133], off
	s_barrier
	s_waitcnt lgkmcnt(0)
	s_waitcnt lgkmcnt(0)
	v_mfma_f32_16x16x32_bf16 v[124:127], v[160:163], v[176:179], v[124:127]
	v_mfma_f32_16x16x32_bf16 v[120:123], v[168:171], v[176:179], v[120:123]
	v_mfma_f32_16x16x32_bf16 v[108:111], v[160:163], v[192:195], v[108:111]
	v_mfma_f32_16x16x32_bf16 v[104:107], v[168:171], v[192:195], v[104:107]
	v_mfma_f32_16x16x32_bf16 v[124:127], v[164:167], v[180:183], v[124:127]
	v_mfma_f32_16x16x32_bf16 v[120:123], v[172:175], v[180:183], v[120:123]
	v_mfma_f32_16x16x32_bf16 v[116:119], v[160:163], v[184:187], v[116:119]
	v_mfma_f32_16x16x32_bf16 v[112:115], v[168:171], v[184:187], v[112:115]
	v_mfma_f32_16x16x32_bf16 v[108:111], v[164:167], v[196:199], v[108:111]
	v_mfma_f32_16x16x32_bf16 v[104:107], v[172:175], v[196:199], v[104:107]
	v_mfma_f32_16x16x32_bf16 v[100:103], v[160:163], v[200:203], v[100:103]
	v_mfma_f32_16x16x32_bf16 v[96:99], v[168:171], v[200:203], v[96:99]
	v_mfma_f32_16x16x32_bf16 v[132:135], v[164:167], v[188:191], v[116:119]
	v_mfma_f32_16x16x32_bf16 v[208:211], v[172:175], v[188:191], v[112:115]
	v_mfma_f32_16x16x32_bf16 v[212:215], v[164:167], v[204:207], v[100:103]
	v_mfma_f32_16x16x32_bf16 v[216:219], v[172:175], v[204:207], v[96:99]
	s_barrier
	s_nop 1
	ds_read_b128 v[96:99], v141
	ds_read_b128 v[100:103], v142
	ds_read_b128 v[112:115], v143
	ds_read_b128 v[116:119], v144
	s_barrier
	s_waitcnt lgkmcnt(0)
	s_waitcnt lgkmcnt(0)
	v_mfma_f32_16x16x32_bf16 v[92:95], v[96:99], v[176:179], v[92:95]
	v_mfma_f32_16x16x32_bf16 v[88:91], v[112:115], v[176:179], v[88:91]
	v_mfma_f32_16x16x32_bf16 v[76:79], v[96:99], v[192:195], v[76:79]
	v_mfma_f32_16x16x32_bf16 v[72:75], v[112:115], v[192:195], v[72:75]
	v_mfma_f32_16x16x32_bf16 v[68:71], v[96:99], v[200:203], v[68:71]
	v_mfma_f32_16x16x32_bf16 v[64:67], v[112:115], v[200:203], v[64:67]
	v_mfma_f32_16x16x32_bf16 v[92:95], v[100:103], v[180:183], v[92:95]
	v_mfma_f32_16x16x32_bf16 v[88:91], v[116:119], v[180:183], v[88:91]
	v_mfma_f32_16x16x32_bf16 v[84:87], v[96:99], v[184:187], v[84:87]
	v_mfma_f32_16x16x32_bf16 v[80:83], v[112:115], v[184:187], v[80:83]
	v_mfma_f32_16x16x32_bf16 v[76:79], v[100:103], v[196:199], v[76:79]
	v_mfma_f32_16x16x32_bf16 v[72:75], v[116:119], v[196:199], v[72:75]
	v_mfma_f32_16x16x32_bf16 v[68:71], v[100:103], v[204:207], v[68:71]
	v_mfma_f32_16x16x32_bf16 v[64:67], v[116:119], v[204:207], v[64:67]
	v_mfma_f32_16x16x32_bf16 v[176:179], v[100:103], v[188:191], v[84:87]
	v_mfma_f32_16x16x32_bf16 v[180:183], v[116:119], v[188:191], v[80:83]
	s_barrier
	s_nop 0
	ds_read_b128 v[80:83], v158 offset:16384
	ds_read_b128 v[84:87], v158 offset:17408
	ds_read_b128 v[184:187], v158 offset:18432
	ds_read_b128 v[188:191], v158 offset:19456
	ds_read_b128 v[192:195], v158 offset:20480
	ds_read_b128 v[196:199], v158 offset:21504
	ds_read_b128 v[200:203], v158 offset:22528
	ds_read_b128 v[204:207], v158 offset:23552
	s_waitcnt vmcnt(4)
	s_barrier
	s_waitcnt lgkmcnt(0)
	s_waitcnt lgkmcnt(0)
	v_mfma_f32_16x16x32_bf16 v[44:47], v[160:163], v[192:195], v[44:47]
	v_mfma_f32_16x16x32_bf16 v[40:43], v[168:171], v[192:195], v[40:43]
	v_mfma_f32_16x16x32_bf16 v[60:63], v[160:163], v[80:83], v[60:63]
	v_mfma_f32_16x16x32_bf16 v[56:59], v[168:171], v[80:83], v[56:59]
	v_mfma_f32_16x16x32_bf16 v[52:55], v[160:163], v[184:187], v[52:55]
	v_mfma_f32_16x16x32_bf16 v[48:51], v[168:171], v[184:187], v[48:51]
	v_mfma_f32_16x16x32_bf16 v[44:47], v[164:167], v[196:199], v[44:47]
	v_mfma_f32_16x16x32_bf16 v[40:43], v[172:175], v[196:199], v[40:43]
	v_mfma_f32_16x16x32_bf16 v[36:39], v[160:163], v[200:203], v[36:39]
	v_mfma_f32_16x16x32_bf16 v[32:35], v[168:171], v[200:203], v[32:35]
	v_mfma_f32_16x16x32_bf16 v[220:223], v[164:167], v[84:87], v[60:63]
	v_mfma_f32_16x16x32_bf16 v[224:227], v[172:175], v[84:87], v[56:59]
	v_mfma_f32_16x16x32_bf16 v[228:231], v[164:167], v[188:191], v[52:55]
	v_mfma_f32_16x16x32_bf16 v[232:235], v[172:175], v[188:191], v[48:51]
	v_mfma_f32_16x16x32_bf16 v[160:163], v[164:167], v[204:207], v[36:39]
	v_mfma_f32_16x16x32_bf16 v[164:167], v[172:175], v[204:207], v[32:35]
	v_mfma_f32_16x16x32_bf16 v[28:31], v[96:99], v[80:83], v[28:31]
	v_mfma_f32_16x16x32_bf16 v[24:27], v[112:115], v[80:83], v[24:27]
	v_mfma_f32_16x16x32_bf16 v[12:15], v[96:99], v[192:195], v[12:15]
	v_mfma_f32_16x16x32_bf16 v[8:11], v[112:115], v[192:195], v[8:11]
	v_mfma_f32_16x16x32_bf16 v[28:31], v[100:103], v[84:87], v[28:31]
	v_mfma_f32_16x16x32_bf16 v[24:27], v[116:119], v[84:87], v[24:27]
	v_mfma_f32_16x16x32_bf16 v[20:23], v[96:99], v[184:187], v[20:23]
	v_mfma_f32_16x16x32_bf16 v[16:19], v[112:115], v[184:187], v[16:19]
	v_mfma_f32_16x16x32_bf16 v[12:15], v[100:103], v[196:199], v[12:15]
	v_mfma_f32_16x16x32_bf16 v[8:11], v[116:119], v[196:199], v[8:11]
	v_mfma_f32_16x16x32_bf16 v[4:7], v[96:99], v[200:203], v[4:7]
	v_mfma_f32_16x16x32_bf16 v[0:3], v[112:115], v[200:203], v[0:3]
	v_mfma_f32_16x16x32_bf16 v[168:171], v[100:103], v[188:191], v[20:23]
	v_mfma_f32_16x16x32_bf16 v[172:175], v[116:119], v[188:191], v[16:19]
	v_mfma_f32_16x16x32_bf16 v[184:187], v[100:103], v[204:207], v[4:7]
	v_mfma_f32_16x16x32_bf16 v[188:191], v[116:119], v[204:207], v[0:3]
	s_barrier
	s_nop 1
	ds_read_b128 v[0:3], v145
	ds_read_b128 v[4:7], v146
	ds_read_b128 v[192:195], v147
	ds_read_b128 v[196:199], v148
	ds_read_b128 v[16:19], v158 offset:32768
	ds_read_b128 v[20:23], v158 offset:33792
	ds_read_b128 v[32:35], v158 offset:34816
	ds_read_b128 v[36:39], v158 offset:35840
	ds_read_b128 v[56:59], v158 offset:36864
	ds_read_b128 v[60:63], v158 offset:37888
	ds_read_b128 v[200:203], v158 offset:38912
	ds_read_b128 v[204:207], v158 offset:39936
	s_waitcnt vmcnt(2)
	s_barrier
	s_waitcnt lgkmcnt(0)
	s_waitcnt lgkmcnt(0)
	v_mfma_f32_16x16x32_bf16 v[48:51], v[0:3], v[16:19], v[124:127]
	v_mfma_f32_16x16x32_bf16 v[112:115], v[4:7], v[20:23], v[48:51]
	v_mfma_f32_16x16x32_bf16 v[48:51], v[192:195], v[16:19], v[120:123]
	v_mfma_f32_16x16x32_bf16 v[116:119], v[196:199], v[20:23], v[48:51]
	v_mfma_f32_16x16x32_bf16 v[48:51], v[0:3], v[32:35], v[132:135]
	v_mfma_f32_16x16x32_bf16 v[96:99], v[4:7], v[36:39], v[48:51]
	v_mfma_f32_16x16x32_bf16 v[48:51], v[192:195], v[32:35], v[208:211]
	v_mfma_f32_16x16x32_bf16 v[100:103], v[196:199], v[36:39], v[48:51]
	v_mfma_f32_16x16x32_bf16 v[48:51], v[0:3], v[56:59], v[108:111]
	v_mfma_f32_16x16x32_bf16 v[80:83], v[4:7], v[60:63], v[48:51]
	v_mfma_f32_16x16x32_bf16 v[48:51], v[192:195], v[56:59], v[104:107]
	v_mfma_f32_16x16x32_bf16 v[84:87], v[196:199], v[60:63], v[48:51]
	v_mfma_f32_16x16x32_bf16 v[48:51], v[0:3], v[200:203], v[212:215]
	v_mfma_f32_16x16x32_bf16 v[52:55], v[192:195], v[200:203], v[216:219]
	v_mfma_f32_16x16x32_bf16 v[48:51], v[4:7], v[204:207], v[48:51]
	v_mfma_f32_16x16x32_bf16 v[52:55], v[196:199], v[204:207], v[52:55]
	s_barrier
	ds_read_b128 v[132:135], v149
	ds_read_b128 v[208:211], v150
	ds_read_b128 v[212:215], v151
	ds_read_b128 v[216:219], v152
	s_waitcnt vmcnt(0)
	s_barrier
	s_waitcnt lgkmcnt(0)
	s_waitcnt lgkmcnt(0)
	v_mfma_f32_16x16x32_bf16 v[92:95], v[132:135], v[16:19], v[92:95]
	v_mfma_f32_16x16x32_bf16 v[16:19], v[212:215], v[16:19], v[88:91]
	v_mfma_f32_16x16x32_bf16 v[124:127], v[216:219], v[20:23], v[16:19]
	v_mfma_f32_16x16x32_bf16 v[16:19], v[132:135], v[32:35], v[176:179]
	v_mfma_f32_16x16x32_bf16 v[104:107], v[208:211], v[36:39], v[16:19]
	v_mfma_f32_16x16x32_bf16 v[16:19], v[212:215], v[32:35], v[180:183]
	v_mfma_f32_16x16x32_bf16 v[108:111], v[216:219], v[36:39], v[16:19]
	v_mfma_f32_16x16x32_bf16 v[16:19], v[132:135], v[56:59], v[76:79]
	v_mfma_f32_16x16x32_bf16 v[88:91], v[208:211], v[60:63], v[16:19]
	v_mfma_f32_16x16x32_bf16 v[16:19], v[212:215], v[56:59], v[72:75]
	v_mfma_f32_16x16x32_bf16 v[120:123], v[208:211], v[20:23], v[92:95]
	v_mfma_f32_16x16x32_bf16 v[92:95], v[216:219], v[60:63], v[16:19]
	v_mfma_f32_16x16x32_bf16 v[16:19], v[132:135], v[200:203], v[68:71]
	v_mfma_f32_16x16x32_bf16 v[56:59], v[208:211], v[204:207], v[16:19]
	v_mfma_f32_16x16x32_bf16 v[16:19], v[212:215], v[200:203], v[64:67]
	v_mfma_f32_16x16x32_bf16 v[60:63], v[216:219], v[204:207], v[16:19]
	s_barrier
	ds_read_b128 v[76:79], v158 offset:49152
	ds_read_b128 v[176:179], v158 offset:50176
	ds_read_b128 v[180:183], v158 offset:51200
	ds_read_b128 v[200:203], v158 offset:52224
	ds_read_b128 v[204:207], v158 offset:53248
	ds_read_b128 v[236:239], v158 offset:54272
	ds_read_b128 v[240:243], v158 offset:55296
	ds_read_b128 v[244:247], v158 offset:56320
	s_barrier
	s_waitcnt lgkmcnt(0)
	s_waitcnt lgkmcnt(0)
	v_mfma_f32_16x16x32_bf16 v[16:19], v[0:3], v[76:79], v[220:223]
	v_mfma_f32_16x16x32_bf16 v[64:67], v[4:7], v[176:179], v[16:19]
	v_mfma_f32_16x16x32_bf16 v[16:19], v[192:195], v[76:79], v[224:227]
	v_mfma_f32_16x16x32_bf16 v[68:71], v[196:199], v[176:179], v[16:19]
	v_mfma_f32_16x16x32_bf16 v[16:19], v[0:3], v[180:183], v[228:231]
	v_mfma_f32_16x16x32_bf16 v[32:35], v[4:7], v[200:203], v[16:19]
	v_mfma_f32_16x16x32_bf16 v[16:19], v[192:195], v[180:183], v[232:235]
	v_mfma_f32_16x16x32_bf16 v[36:39], v[196:199], v[200:203], v[16:19]
	v_mfma_f32_16x16x32_bf16 v[16:19], v[0:3], v[204:207], v[44:47]
	v_mfma_f32_16x16x32_bf16 v[0:3], v[0:3], v[240:243], v[160:163]
	v_mfma_f32_16x16x32_bf16 v[16:19], v[4:7], v[236:239], v[16:19]
	v_mfma_f32_16x16x32_bf16 v[20:23], v[192:195], v[204:207], v[40:43]
	v_mfma_f32_16x16x32_bf16 v[0:3], v[4:7], v[244:247], v[0:3]
	v_mfma_f32_16x16x32_bf16 v[4:7], v[192:195], v[240:243], v[164:167]
	v_mfma_f32_16x16x32_bf16 v[20:23], v[196:199], v[236:239], v[20:23]
	v_mfma_f32_16x16x32_bf16 v[4:7], v[196:199], v[244:247], v[4:7]
	v_mfma_f32_16x16x32_bf16 v[24:27], v[212:215], v[76:79], v[24:27]
	v_mfma_f32_16x16x32_bf16 v[28:31], v[132:135], v[76:79], v[28:31]
	v_mfma_f32_16x16x32_bf16 v[76:79], v[216:219], v[176:179], v[24:27]
	v_mfma_f32_16x16x32_bf16 v[24:27], v[132:135], v[180:183], v[168:171]
	v_mfma_f32_16x16x32_bf16 v[40:43], v[208:211], v[200:203], v[24:27]
	v_mfma_f32_16x16x32_bf16 v[24:27], v[212:215], v[180:183], v[172:175]
	v_mfma_f32_16x16x32_bf16 v[12:15], v[132:135], v[204:207], v[12:15]
	v_mfma_f32_16x16x32_bf16 v[8:11], v[212:215], v[204:207], v[8:11]
	v_mfma_f32_16x16x32_bf16 v[72:75], v[208:211], v[176:179], v[28:31]
	v_mfma_f32_16x16x32_bf16 v[44:47], v[216:219], v[200:203], v[24:27]
	v_mfma_f32_16x16x32_bf16 v[24:27], v[208:211], v[236:239], v[12:15]
	v_mfma_f32_16x16x32_bf16 v[28:31], v[216:219], v[236:239], v[8:11]
	v_mfma_f32_16x16x32_bf16 v[8:11], v[132:135], v[240:243], v[184:187]
	v_mfma_f32_16x16x32_bf16 v[12:15], v[212:215], v[240:243], v[188:191]
	v_mfma_f32_16x16x32_bf16 v[8:11], v[208:211], v[244:247], v[8:11]
	v_mfma_f32_16x16x32_bf16 v[12:15], v[216:219], v[244:247], v[12:15]
	s_barrier
	s_and_saveexec_b64 s[18:19], s[4:5]
	s_cbranch_execz .LBB0_294
	s_barrier

.LBB0_310:
	ds_read_b128 v[160:163], v138
	ds_read_b128 v[164:167], v139
	ds_read_b128 v[168:171], v140
	ds_read_b128 v[172:175], v141
	s_add_u32 s84, s30, 0xffffff80
	s_addc_u32 s85, s31, -1
	s_mov_b32 m0, s81
	ds_read_b128 v[176:179], v158
	ds_read_b128 v[180:183], v158 offset:1024
	ds_read_b128 v[184:187], v158 offset:2048
	ds_read_b128 v[188:191], v158 offset:3072
	ds_read_b128 v[192:195], v158 offset:4096
	ds_read_b128 v[196:199], v158 offset:5120
	ds_read_b128 v[200:203], v158 offset:6144
	ds_read_b128 v[204:207], v158 offset:7168
	s_nop 0
	v_lshl_add_u64 v[208:209], v[134:135], 0, s[84:85]
	global_load_lds_dwordx4 v[208:209], off
	v_lshl_add_u64 v[208:209], v[208:209], 0, s[8:9]
	s_mov_b32 m0, s71
	s_nop 0
	global_load_lds_dwordx4 v[208:209], off
	s_waitcnt lgkmcnt(8)
	s_barrier
	s_waitcnt lgkmcnt(0)
	s_waitcnt lgkmcnt(0)
	v_mfma_f32_16x16x32_bf16 v[124:127], v[160:163], v[176:179], v[124:127]
	v_mfma_f32_16x16x32_bf16 v[120:123], v[168:171], v[176:179], v[120:123]
	v_mfma_f32_16x16x32_bf16 v[116:119], v[160:163], v[184:187], v[116:119]
	v_mfma_f32_16x16x32_bf16 v[112:115], v[168:171], v[184:187], v[112:115]
	v_mfma_f32_16x16x32_bf16 v[108:111], v[160:163], v[192:195], v[108:111]
	v_mfma_f32_16x16x32_bf16 v[104:107], v[168:171], v[192:195], v[104:107]
	v_mfma_f32_16x16x32_bf16 v[100:103], v[160:163], v[200:203], v[100:103]
	v_mfma_f32_16x16x32_bf16 v[96:99], v[168:171], v[200:203], v[96:99]
	v_mfma_f32_16x16x32_bf16 v[124:127], v[164:167], v[180:183], v[124:127]
	v_mfma_f32_16x16x32_bf16 v[120:123], v[172:175], v[180:183], v[120:123]
	v_mfma_f32_16x16x32_bf16 v[116:119], v[164:167], v[188:191], v[116:119]
	v_mfma_f32_16x16x32_bf16 v[112:115], v[172:175], v[188:191], v[112:115]
	v_mfma_f32_16x16x32_bf16 v[108:111], v[164:167], v[196:199], v[108:111]
	v_mfma_f32_16x16x32_bf16 v[104:107], v[172:175], v[196:199], v[104:107]
	v_mfma_f32_16x16x32_bf16 v[100:103], v[164:167], v[204:207], v[100:103]
	v_mfma_f32_16x16x32_bf16 v[96:99], v[172:175], v[204:207], v[96:99]
	s_barrier
	s_add_u32 s84, s30, 0xfffa0000
	s_addc_u32 s85, s31, -1
	s_mov_b64 s[86:87], s[84:85]
	s_mov_b32 m0, s74
	ds_read_b128 v[208:211], v142
	ds_read_b128 v[212:215], v143
	ds_read_b128 v[216:219], v144
	ds_read_b128 v[220:223], v145
	s_nop 0
	v_lshl_add_u64 v[224:225], v[136:137], 0, s[86:87]
	global_load_lds_dwordx4 v[224:225], off
	v_lshl_add_u64 v[224:225], v[224:225], 0, s[6:7]
	s_mov_b32 m0, s75
	s_nop 0
	global_load_lds_dwordx4 v[224:225], off
	s_barrier
	s_waitcnt lgkmcnt(0)
	s_waitcnt lgkmcnt(0)
	v_mfma_f32_16x16x32_bf16 v[92:95], v[208:211], v[176:179], v[92:95]
	v_mfma_f32_16x16x32_bf16 v[88:91], v[216:219], v[176:179], v[88:91]
	v_mfma_f32_16x16x32_bf16 v[84:87], v[208:211], v[184:187], v[84:87]
	v_mfma_f32_16x16x32_bf16 v[80:83], v[216:219], v[184:187], v[80:83]
	v_mfma_f32_16x16x32_bf16 v[76:79], v[208:211], v[192:195], v[76:79]
	v_mfma_f32_16x16x32_bf16 v[72:75], v[216:219], v[192:195], v[72:75]
	v_mfma_f32_16x16x32_bf16 v[68:71], v[208:211], v[200:203], v[68:71]
	v_mfma_f32_16x16x32_bf16 v[64:67], v[216:219], v[200:203], v[64:67]
	v_mfma_f32_16x16x32_bf16 v[92:95], v[212:215], v[180:183], v[92:95]
	v_mfma_f32_16x16x32_bf16 v[88:91], v[220:223], v[180:183], v[88:91]
	v_mfma_f32_16x16x32_bf16 v[84:87], v[212:215], v[188:191], v[84:87]
	v_mfma_f32_16x16x32_bf16 v[80:83], v[220:223], v[188:191], v[80:83]
	v_mfma_f32_16x16x32_bf16 v[76:79], v[212:215], v[196:199], v[76:79]
	v_mfma_f32_16x16x32_bf16 v[72:75], v[220:223], v[196:199], v[72:75]
	v_mfma_f32_16x16x32_bf16 v[68:71], v[212:215], v[204:207], v[68:71]
	v_mfma_f32_16x16x32_bf16 v[64:67], v[220:223], v[204:207], v[64:67]
	s_mov_b32 m0, s29
	s_barrier
	ds_read_b128 v[176:179], v158 offset:16384
	ds_read_b128 v[180:183], v158 offset:17408
	ds_read_b128 v[184:187], v158 offset:18432
	ds_read_b128 v[188:191], v158 offset:19456
	ds_read_b128 v[192:195], v158 offset:20480
	ds_read_b128 v[196:199], v158 offset:21504
	ds_read_b128 v[200:203], v158 offset:22528
	ds_read_b128 v[204:207], v158 offset:23552
	s_nop 0
	v_lshl_add_u64 v[224:225], v[134:135], 0, s[84:85]
	global_load_lds_dwordx4 v[224:225], off
	v_lshl_add_u64 v[224:225], v[224:225], 0, s[8:9]
	s_mov_b32 m0, s82
	s_nop 0
	global_load_lds_dwordx4 v[224:225], off
	s_barrier
	s_waitcnt lgkmcnt(0)
	s_waitcnt lgkmcnt(0)
	v_mfma_f32_16x16x32_bf16 v[60:63], v[160:163], v[176:179], v[60:63]
	v_mfma_f32_16x16x32_bf16 v[56:59], v[168:171], v[176:179], v[56:59]
	v_mfma_f32_16x16x32_bf16 v[52:55], v[160:163], v[184:187], v[52:55]
	v_mfma_f32_16x16x32_bf16 v[48:51], v[168:171], v[184:187], v[48:51]
	v_mfma_f32_16x16x32_bf16 v[44:47], v[160:163], v[192:195], v[44:47]
	v_mfma_f32_16x16x32_bf16 v[40:43], v[168:171], v[192:195], v[40:43]
	v_mfma_f32_16x16x32_bf16 v[36:39], v[160:163], v[200:203], v[36:39]
	v_mfma_f32_16x16x32_bf16 v[32:35], v[168:171], v[200:203], v[32:35]
	v_mfma_f32_16x16x32_bf16 v[60:63], v[164:167], v[180:183], v[60:63]
	v_mfma_f32_16x16x32_bf16 v[56:59], v[172:175], v[180:183], v[56:59]
	v_mfma_f32_16x16x32_bf16 v[52:55], v[164:167], v[188:191], v[52:55]
	v_mfma_f32_16x16x32_bf16 v[48:51], v[172:175], v[188:191], v[48:51]
	v_mfma_f32_16x16x32_bf16 v[44:47], v[164:167], v[196:199], v[44:47]
	v_mfma_f32_16x16x32_bf16 v[40:43], v[172:175], v[196:199], v[40:43]
	v_mfma_f32_16x16x32_bf16 v[36:39], v[164:167], v[204:207], v[36:39]
	v_mfma_f32_16x16x32_bf16 v[32:35], v[172:175], v[204:207], v[32:35]
	s_barrier
	s_add_u32 s84, s30, 0xfffc0000
	s_addc_u32 s85, s31, -1
	s_mov_b32 m0, s77
	s_nop 0
	v_lshl_add_u64 v[160:161], v[136:137], 0, s[84:85]
	global_load_lds_dwordx4 v[160:161], off
	v_lshl_add_u64 v[160:161], v[160:161], 0, s[6:7]
	s_mov_b32 m0, s79
	s_nop 0
	global_load_lds_dwordx4 v[160:161], off
	s_waitcnt vmcnt(6)
	s_barrier
	v_mfma_f32_16x16x32_bf16 v[28:31], v[208:211], v[176:179], v[28:31]
	v_mfma_f32_16x16x32_bf16 v[24:27], v[216:219], v[176:179], v[24:27]
	v_mfma_f32_16x16x32_bf16 v[20:23], v[208:211], v[184:187], v[20:23]
	v_mfma_f32_16x16x32_bf16 v[16:19], v[216:219], v[184:187], v[16:19]
	v_mfma_f32_16x16x32_bf16 v[12:15], v[208:211], v[192:195], v[12:15]
	v_mfma_f32_16x16x32_bf16 v[8:11], v[216:219], v[192:195], v[8:11]
	v_mfma_f32_16x16x32_bf16 v[4:7], v[208:211], v[200:203], v[4:7]
	v_mfma_f32_16x16x32_bf16 v[0:3], v[216:219], v[200:203], v[0:3]
	v_mfma_f32_16x16x32_bf16 v[28:31], v[212:215], v[180:183], v[28:31]
	v_mfma_f32_16x16x32_bf16 v[24:27], v[220:223], v[180:183], v[24:27]
	v_mfma_f32_16x16x32_bf16 v[20:23], v[212:215], v[188:191], v[20:23]
	v_mfma_f32_16x16x32_bf16 v[16:19], v[220:223], v[188:191], v[16:19]
	v_mfma_f32_16x16x32_bf16 v[12:15], v[212:215], v[196:199], v[12:15]
	v_mfma_f32_16x16x32_bf16 v[8:11], v[220:223], v[196:199], v[8:11]
	v_mfma_f32_16x16x32_bf16 v[4:7], v[212:215], v[204:207], v[4:7]
	v_mfma_f32_16x16x32_bf16 v[0:3], v[220:223], v[204:207], v[0:3]
	s_barrier
	ds_read_b128 v[160:163], v146
	ds_read_b128 v[164:167], v147
	ds_read_b128 v[168:171], v148
	ds_read_b128 v[172:175], v149
	s_mov_b64 s[84:85], s[30:31]
	s_mov_b32 m0, s83
	ds_read_b128 v[176:179], v158 offset:32768
	ds_read_b128 v[180:183], v158 offset:33792
	ds_read_b128 v[184:187], v158 offset:34816
	ds_read_b128 v[188:191], v158 offset:35840
	ds_read_b128 v[192:195], v158 offset:36864
	ds_read_b128 v[196:199], v158 offset:37888
	ds_read_b128 v[200:203], v158 offset:38912
	ds_read_b128 v[204:207], v158 offset:39936
	s_nop 0
	v_lshl_add_u64 v[208:209], v[134:135], 0, s[84:85]
	global_load_lds_dwordx4 v[208:209], off
	v_lshl_add_u64 v[208:209], v[208:209], 0, s[8:9]
	s_add_i32 m0, s29, 0x6000
	s_nop 0
	global_load_lds_dwordx4 v[208:209], off
	s_waitcnt lgkmcnt(8)
	s_barrier
	s_waitcnt lgkmcnt(0)
	s_waitcnt lgkmcnt(0)
	v_mfma_f32_16x16x32_bf16 v[124:127], v[160:163], v[176:179], v[124:127]
	v_mfma_f32_16x16x32_bf16 v[120:123], v[168:171], v[176:179], v[120:123]
	v_mfma_f32_16x16x32_bf16 v[116:119], v[160:163], v[184:187], v[116:119]
	v_mfma_f32_16x16x32_bf16 v[112:115], v[168:171], v[184:187], v[112:115]
	v_mfma_f32_16x16x32_bf16 v[108:111], v[160:163], v[192:195], v[108:111]
	v_mfma_f32_16x16x32_bf16 v[104:107], v[168:171], v[192:195], v[104:107]
	v_mfma_f32_16x16x32_bf16 v[100:103], v[160:163], v[200:203], v[100:103]
	v_mfma_f32_16x16x32_bf16 v[96:99], v[168:171], v[200:203], v[96:99]
	v_mfma_f32_16x16x32_bf16 v[124:127], v[164:167], v[180:183], v[124:127]
	v_mfma_f32_16x16x32_bf16 v[120:123], v[172:175], v[180:183], v[120:123]
	v_mfma_f32_16x16x32_bf16 v[116:119], v[164:167], v[188:191], v[116:119]
	v_mfma_f32_16x16x32_bf16 v[112:115], v[172:175], v[188:191], v[112:115]
	v_mfma_f32_16x16x32_bf16 v[108:111], v[164:167], v[196:199], v[108:111]
	v_mfma_f32_16x16x32_bf16 v[104:107], v[172:175], v[196:199], v[104:107]
	v_mfma_f32_16x16x32_bf16 v[100:103], v[164:167], v[204:207], v[100:103]
	v_mfma_f32_16x16x32_bf16 v[96:99], v[172:175], v[204:207], v[96:99]
	s_barrier
	s_add_u32 s84, s30, 0xfffa0080
	s_addc_u32 s85, s31, -1
	s_mov_b64 s[86:87], s[84:85]
	s_mov_b32 m0, s67
	ds_read_b128 v[208:211], v150
	ds_read_b128 v[212:215], v151
	ds_read_b128 v[216:219], v152
	ds_read_b128 v[220:223], v153
	s_nop 0
	v_lshl_add_u64 v[224:225], v[136:137], 0, s[86:87]
	global_load_lds_dwordx4 v[224:225], off
	v_lshl_add_u64 v[224:225], v[224:225], 0, s[6:7]
	s_mov_b32 m0, s68
	s_nop 0
	global_load_lds_dwordx4 v[224:225], off
	s_barrier
	s_waitcnt lgkmcnt(0)
	s_waitcnt lgkmcnt(0)
	v_mfma_f32_16x16x32_bf16 v[92:95], v[208:211], v[176:179], v[92:95]
	v_mfma_f32_16x16x32_bf16 v[88:91], v[216:219], v[176:179], v[88:91]
	v_mfma_f32_16x16x32_bf16 v[84:87], v[208:211], v[184:187], v[84:87]
	v_mfma_f32_16x16x32_bf16 v[80:83], v[216:219], v[184:187], v[80:83]
	v_mfma_f32_16x16x32_bf16 v[76:79], v[208:211], v[192:195], v[76:79]
	v_mfma_f32_16x16x32_bf16 v[72:75], v[216:219], v[192:195], v[72:75]
	v_mfma_f32_16x16x32_bf16 v[68:71], v[208:211], v[200:203], v[68:71]
	v_mfma_f32_16x16x32_bf16 v[64:67], v[216:219], v[200:203], v[64:67]
	v_mfma_f32_16x16x32_bf16 v[92:95], v[212:215], v[180:183], v[92:95]
	v_mfma_f32_16x16x32_bf16 v[88:91], v[220:223], v[180:183], v[88:91]
	v_mfma_f32_16x16x32_bf16 v[84:87], v[212:215], v[188:191], v[84:87]
	v_mfma_f32_16x16x32_bf16 v[80:83], v[220:223], v[188:191], v[80:83]
	v_mfma_f32_16x16x32_bf16 v[76:79], v[212:215], v[196:199], v[76:79]
	v_mfma_f32_16x16x32_bf16 v[72:75], v[220:223], v[196:199], v[72:75]
	v_mfma_f32_16x16x32_bf16 v[68:71], v[212:215], v[204:207], v[68:71]
	v_mfma_f32_16x16x32_bf16 v[64:67], v[220:223], v[204:207], v[64:67]
	s_mov_b32 m0, s69
	s_barrier
	ds_read_b128 v[176:179], v158 offset:49152
	ds_read_b128 v[180:183], v158 offset:50176
	ds_read_b128 v[184:187], v158 offset:51200
	ds_read_b128 v[188:191], v158 offset:52224
	ds_read_b128 v[192:195], v158 offset:53248
	ds_read_b128 v[196:199], v158 offset:54272
	ds_read_b128 v[200:203], v158 offset:55296
	ds_read_b128 v[204:207], v158 offset:56320
	s_nop 0
	v_lshl_add_u64 v[224:225], v[134:135], 0, s[84:85]
	global_load_lds_dwordx4 v[224:225], off
	v_lshl_add_u64 v[224:225], v[224:225], 0, s[8:9]
	s_mov_b32 m0, s70
	s_nop 0
	global_load_lds_dwordx4 v[224:225], off
	s_barrier
; #define STA(b, h, half, kt) STAGE(((b) * 2 + (h)) * G_HT * 2, pA, ((size_t)(half) * G_HALF * lda + (size_t)(kt) * G_BK) * 2, lda)
; #define STB(b, h, half, kt) STAGE((4 + (b) * 2 + (h)) * G_HT * 2, pB, ((size_t)(half) * G_HALF * K + (size_t)(kt) * G_BK) * 2, K)
; #define LDA(dst, b, h) for (int m = 0; m < 4; ++m) for (int k = 0; k < 2; ++k) \
;     dst[m][k] = *reinterpret_cast<const bf16x8*>(aRd + (((b) * 2 + (h)) * G_HT * 2 + m * 2048 + k * 1024))
; #define LDB(dst, b, h) for (int n = 0; n < 2; ++n) for (int k = 0; k < 2; ++k) \
;     dst[n][k] = *reinterpret_cast<const bf16x8*>(bRd + (((b) * 2 + (h)) * G_HT * 2 + n * 2048 + k * 1024))
; #define MMA(ai, bj, At, Bx) do { __builtin_amdgcn_s_setprio(1); \
;     for (int m = 0; m < 4; ++m) for (int n = 0; n < 2; ++n) for (int k = 0; k < 2; ++k) \
;       acc[ai][bj][m][n] = __builtin_amdgcn_mfma_f32_16x16x32_bf16(Bx[n][k], At[m][k], acc[ai][bj][m][n], 0, 0, 0);     \
;     __builtin_amdgcn_s_setprio(0); } while (0)
; #define WAIT_V(n) asm volatile("s_waitcnt vmcnt(" #n ")" ::: "memory")
; #define WAIT_L(n) asm volatile("s_waitcnt lgkmcnt(" #n ")" ::: "memory")
; #define BAR __builtin_amdgcn_s_barrier()
; #define SCHED __builtin_amdgcn_sched_barrier(0)
; template <int EPI>
; __device__ __forceinline__ void gemm_tile(const bf16* __restrict__ A, int lda, const bf16* __restrict__ Bt, int K,
;                                           int brow, int bcol, const EpiArgs& ea, char* shmc, bool has_next, int nbrow, int nbcol, bool first_tile) {
;     ...
;     LDA(At, 1, 1); STA(1, 0, 0, t + 3);
;     BAR; WAIT_L(0); MMA(1, 0, At, B0); BAR; SCHED;
;     STB(1, 1, 1, t + 3);
;     WAIT_V(6); BAR; MMA(1, 1, At, B1); BAR;
;   }
;   { LDB(B0, 0, 0); LDA(At, 0, 0); STA(1, 1, 1, nt - 1);
;     BAR; WAIT_L(0); MMA(0, 0, At, B0); BAR;
;     LDB(B1, 0, 1); BAR; WAIT_L(0); MMA(0, 1, At, B1); BAR;
	s_waitcnt lgkmcnt(0)
	s_waitcnt lgkmcnt(0)
	v_mfma_f32_16x16x32_bf16 v[60:63], v[160:163], v[176:179], v[60:63]
	v_mfma_f32_16x16x32_bf16 v[56:59], v[168:171], v[176:179], v[56:59]
	v_mfma_f32_16x16x32_bf16 v[52:55], v[160:163], v[184:187], v[52:55]
	v_mfma_f32_16x16x32_bf16 v[48:51], v[168:171], v[184:187], v[48:51]
	v_mfma_f32_16x16x32_bf16 v[44:47], v[160:163], v[192:195], v[44:47]
	v_mfma_f32_16x16x32_bf16 v[40:43], v[168:171], v[192:195], v[40:43]
	v_mfma_f32_16x16x32_bf16 v[36:39], v[160:163], v[200:203], v[36:39]
	v_mfma_f32_16x16x32_bf16 v[32:35], v[168:171], v[200:203], v[32:35]
	v_mfma_f32_16x16x32_bf16 v[60:63], v[164:167], v[180:183], v[60:63]
	v_mfma_f32_16x16x32_bf16 v[56:59], v[172:175], v[180:183], v[56:59]
	v_mfma_f32_16x16x32_bf16 v[52:55], v[164:167], v[188:191], v[52:55]
	v_mfma_f32_16x16x32_bf16 v[48:51], v[172:175], v[188:191], v[48:51]
	v_mfma_f32_16x16x32_bf16 v[44:47], v[164:167], v[196:199], v[44:47]
	v_mfma_f32_16x16x32_bf16 v[40:43], v[172:175], v[196:199], v[40:43]
	v_mfma_f32_16x16x32_bf16 v[36:39], v[164:167], v[204:207], v[36:39]
	v_mfma_f32_16x16x32_bf16 v[32:35], v[172:175], v[204:207], v[32:35]
	s_barrier
	s_add_u32 s84, s30, 0xfffc0080
	s_addc_u32 s85, s31, -1
	s_mov_b32 m0, s72
	s_nop 0
	v_lshl_add_u64 v[160:161], v[136:137], 0, s[84:85]
	global_load_lds_dwordx4 v[160:161], off
	v_lshl_add_u64 v[160:161], v[160:161], 0, s[6:7]
	s_mov_b32 m0, s73
	s_nop 0
	global_load_lds_dwordx4 v[160:161], off
	s_waitcnt vmcnt(6)
	s_barrier
	v_mfma_f32_16x16x32_bf16 v[28:31], v[208:211], v[176:179], v[28:31]
	v_mfma_f32_16x16x32_bf16 v[24:27], v[216:219], v[176:179], v[24:27]
	v_mfma_f32_16x16x32_bf16 v[20:23], v[208:211], v[184:187], v[20:23]
	v_mfma_f32_16x16x32_bf16 v[16:19], v[216:219], v[184:187], v[16:19]
	v_mfma_f32_16x16x32_bf16 v[12:15], v[208:211], v[192:195], v[12:15]
	v_mfma_f32_16x16x32_bf16 v[8:11], v[216:219], v[192:195], v[8:11]
	v_mfma_f32_16x16x32_bf16 v[4:7], v[208:211], v[200:203], v[4:7]
	v_mfma_f32_16x16x32_bf16 v[0:3], v[216:219], v[200:203], v[0:3]
	v_mfma_f32_16x16x32_bf16 v[28:31], v[212:215], v[180:183], v[28:31]
	v_mfma_f32_16x16x32_bf16 v[24:27], v[220:223], v[180:183], v[24:27]
	v_mfma_f32_16x16x32_bf16 v[20:23], v[212:215], v[188:191], v[20:23]
	v_mfma_f32_16x16x32_bf16 v[16:19], v[220:223], v[188:191], v[16:19]
	v_mfma_f32_16x16x32_bf16 v[12:15], v[212:215], v[196:199], v[12:15]
	v_mfma_f32_16x16x32_bf16 v[8:11], v[220:223], v[196:199], v[8:11]
	v_mfma_f32_16x16x32_bf16 v[4:7], v[212:215], v[204:207], v[4:7]
	v_mfma_f32_16x16x32_bf16 v[0:3], v[220:223], v[204:207], v[0:3]
	s_add_i32 s80, s80, 2
	s_add_u32 s30, s30, 0x100
	s_addc_u32 s31, s31, 0
	s_cmp_lt_u32 s80, 4
	s_barrier
	s_cbranch_scc1 .LBB0_310
	s_mov_b64 s[30:31], 0x60380
	s_mov_b32 m0, s81
	ds_read_b128 v[160:163], v138
	ds_read_b128 v[164:167], v139
	ds_read_b128 v[168:171], v140
	ds_read_b128 v[172:175], v141
	ds_read_b128 v[176:179], v158
	ds_read_b128 v[180:183], v158 offset:1024
	ds_read_b128 v[184:187], v158 offset:2048
	ds_read_b128 v[188:191], v158 offset:3072
	ds_read_b128 v[192:195], v158 offset:4096
	ds_read_b128 v[196:199], v158 offset:5120
	ds_read_b128 v[200:203], v158 offset:6144
	ds_read_b128 v[204:207], v158 offset:7168
	s_nop 0
	v_lshl_add_u64 v[134:135], v[134:135], 0, s[30:31]
	global_load_lds_dwordx4 v[134:135], off
	v_lshl_add_u64 v[134:135], v[134:135], 0, s[8:9]
	s_mov_b32 m0, s71
	s_nop 0
	global_load_lds_dwordx4 v[134:135], off
	s_barrier
	s_waitcnt lgkmcnt(0)
	s_waitcnt lgkmcnt(0)
	v_mfma_f32_16x16x32_bf16 v[124:127], v[160:163], v[176:179], v[124:127]
	v_mfma_f32_16x16x32_bf16 v[120:123], v[168:171], v[176:179], v[120:123]
	v_mfma_f32_16x16x32_bf16 v[108:111], v[160:163], v[192:195], v[108:111]
	v_mfma_f32_16x16x32_bf16 v[104:107], v[168:171], v[192:195], v[104:107]
	v_mfma_f32_16x16x32_bf16 v[124:127], v[164:167], v[180:183], v[124:127]
	v_mfma_f32_16x16x32_bf16 v[120:123], v[172:175], v[180:183], v[120:123]
	v_mfma_f32_16x16x32_bf16 v[116:119], v[160:163], v[184:187], v[116:119]
	v_mfma_f32_16x16x32_bf16 v[112:115], v[168:171], v[184:187], v[112:115]
	v_mfma_f32_16x16x32_bf16 v[108:111], v[164:167], v[196:199], v[108:111]
	v_mfma_f32_16x16x32_bf16 v[104:107], v[172:175], v[196:199], v[104:107]
	v_mfma_f32_16x16x32_bf16 v[100:103], v[160:163], v[200:203], v[100:103]
	v_mfma_f32_16x16x32_bf16 v[96:99], v[168:171], v[200:203], v[96:99]
	v_mfma_f32_16x16x32_bf16 v[134:137], v[164:167], v[188:191], v[116:119]
	v_mfma_f32_16x16x32_bf16 v[208:211], v[172:175], v[188:191], v[112:115]
	v_mfma_f32_16x16x32_bf16 v[212:215], v[164:167], v[204:207], v[100:103]
	v_mfma_f32_16x16x32_bf16 v[216:219], v[172:175], v[204:207], v[96:99]
	s_barrier
	s_nop 1
	ds_read_b128 v[96:99], v142
	ds_read_b128 v[100:103], v143
	ds_read_b128 v[112:115], v144
	ds_read_b128 v[116:119], v145
	s_barrier
	s_waitcnt lgkmcnt(0)
	s_waitcnt lgkmcnt(0)
	v_mfma_f32_16x16x32_bf16 v[92:95], v[96:99], v[176:179], v[92:95]
	v_mfma_f32_16x16x32_bf16 v[88:91], v[112:115], v[176:179], v[88:91]
	v_mfma_f32_16x16x32_bf16 v[76:79], v[96:99], v[192:195], v[76:79]
	v_mfma_f32_16x16x32_bf16 v[72:75], v[112:115], v[192:195], v[72:75]
	v_mfma_f32_16x16x32_bf16 v[68:71], v[96:99], v[200:203], v[68:71]
	v_mfma_f32_16x16x32_bf16 v[64:67], v[112:115], v[200:203], v[64:67]
	v_mfma_f32_16x16x32_bf16 v[92:95], v[100:103], v[180:183], v[92:95]
	v_mfma_f32_16x16x32_bf16 v[88:91], v[116:119], v[180:183], v[88:91]
	v_mfma_f32_16x16x32_bf16 v[84:87], v[96:99], v[184:187], v[84:87]
	v_mfma_f32_16x16x32_bf16 v[80:83], v[112:115], v[184:187], v[80:83]
	v_mfma_f32_16x16x32_bf16 v[76:79], v[100:103], v[196:199], v[76:79]
	v_mfma_f32_16x16x32_bf16 v[72:75], v[116:119], v[196:199], v[72:75]
	v_mfma_f32_16x16x32_bf16 v[68:71], v[100:103], v[204:207], v[68:71]
	v_mfma_f32_16x16x32_bf16 v[64:67], v[116:119], v[204:207], v[64:67]
	v_mfma_f32_16x16x32_bf16 v[176:179], v[100:103], v[188:191], v[84:87]
	v_mfma_f32_16x16x32_bf16 v[180:183], v[116:119], v[188:191], v[80:83]
	s_barrier
; #define LDA(dst, b, h) for (int m = 0; m < 4; ++m) for (int k = 0; k < 2; ++k) \
;     dst[m][k] = *reinterpret_cast<const bf16x8*>(aRd + (((b) * 2 + (h)) * G_HT * 2 + m * 2048 + k * 1024))
; #define LDB(dst, b, h) for (int n = 0; n < 2; ++n) for (int k = 0; k < 2; ++k) \
;     dst[n][k] = *reinterpret_cast<const bf16x8*>(bRd + (((b) * 2 + (h)) * G_HT * 2 + n * 2048 + k * 1024))
; #define MMA(ai, bj, At, Bx) do { __builtin_amdgcn_s_setprio(1); \
;     for (int m = 0; m < 4; ++m) for (int n = 0; n < 2; ++n) for (int k = 0; k < 2; ++k) \
;       acc[ai][bj][m][n] = __builtin_amdgcn_mfma_f32_16x16x32_bf16(Bx[n][k], At[m][k], acc[ai][bj][m][n], 0, 0, 0);     \
;     __builtin_amdgcn_s_setprio(0); } while (0)
; #define WAIT_V(n) asm volatile("s_waitcnt vmcnt(" #n ")" ::: "memory")
; #define WAIT_L(n) asm volatile("s_waitcnt lgkmcnt(" #n ")" ::: "memory")
; #define BAR __builtin_amdgcn_s_barrier()
; template <int EPI>
; __device__ __forceinline__ void gemm_tile(const bf16* __restrict__ A, int lda, const bf16* __restrict__ Bt, int K,
;                                           int brow, int bcol, const EpiArgs& ea, char* shmc, bool has_next, int nbrow, int nbcol, bool first_tile) {
;     ...
;     LDA(At, 0, 1); WAIT_V(4); BAR; WAIT_L(0); MMA(1, 0, At, B0); MMA(1, 1, At, B1); BAR; }
;   { LDB(B0, 1, 0); LDA(At, 1, 0); WAIT_V(2); BAR; WAIT_L(0); MMA(0, 0, At, B0); BAR;
	s_nop 0
	ds_read_b128 v[80:83], v158 offset:16384
	ds_read_b128 v[84:87], v158 offset:17408
	ds_read_b128 v[184:187], v158 offset:18432
	ds_read_b128 v[188:191], v158 offset:19456
	ds_read_b128 v[192:195], v158 offset:20480
	ds_read_b128 v[196:199], v158 offset:21504
	ds_read_b128 v[200:203], v158 offset:22528
	ds_read_b128 v[204:207], v158 offset:23552
	s_waitcnt vmcnt(4)
	s_barrier
	s_waitcnt lgkmcnt(0)
	s_waitcnt lgkmcnt(0)
	v_mfma_f32_16x16x32_bf16 v[36:39], v[160:163], v[200:203], v[36:39]
	v_mfma_f32_16x16x32_bf16 v[32:35], v[168:171], v[200:203], v[32:35]
	v_mfma_f32_16x16x32_bf16 v[60:63], v[160:163], v[80:83], v[60:63]
	v_mfma_f32_16x16x32_bf16 v[56:59], v[168:171], v[80:83], v[56:59]
	v_mfma_f32_16x16x32_bf16 v[52:55], v[160:163], v[184:187], v[52:55]
	v_mfma_f32_16x16x32_bf16 v[48:51], v[168:171], v[184:187], v[48:51]
	v_mfma_f32_16x16x32_bf16 v[44:47], v[160:163], v[192:195], v[44:47]
	v_mfma_f32_16x16x32_bf16 v[40:43], v[168:171], v[192:195], v[40:43]
	v_mfma_f32_16x16x32_bf16 v[36:39], v[164:167], v[204:207], v[36:39]
	v_mfma_f32_16x16x32_bf16 v[32:35], v[172:175], v[204:207], v[32:35]
	v_mfma_f32_16x16x32_bf16 v[220:223], v[164:167], v[84:87], v[60:63]
	v_mfma_f32_16x16x32_bf16 v[224:227], v[172:175], v[84:87], v[56:59]
	v_mfma_f32_16x16x32_bf16 v[228:231], v[164:167], v[188:191], v[52:55]
	v_mfma_f32_16x16x32_bf16 v[232:235], v[172:175], v[188:191], v[48:51]
	v_mfma_f32_16x16x32_bf16 v[236:239], v[164:167], v[196:199], v[44:47]
	v_mfma_f32_16x16x32_bf16 v[240:243], v[172:175], v[196:199], v[40:43]
	v_mfma_f32_16x16x32_bf16 v[20:23], v[96:99], v[184:187], v[20:23]
	v_mfma_f32_16x16x32_bf16 v[16:19], v[112:115], v[184:187], v[16:19]
	v_mfma_f32_16x16x32_bf16 v[4:7], v[96:99], v[200:203], v[4:7]
	v_mfma_f32_16x16x32_bf16 v[28:31], v[96:99], v[80:83], v[28:31]
	v_mfma_f32_16x16x32_bf16 v[24:27], v[112:115], v[80:83], v[24:27]
	v_mfma_f32_16x16x32_bf16 v[20:23], v[100:103], v[188:191], v[20:23]
	v_mfma_f32_16x16x32_bf16 v[16:19], v[116:119], v[188:191], v[16:19]
	v_mfma_f32_16x16x32_bf16 v[12:15], v[96:99], v[192:195], v[12:15]
	v_mfma_f32_16x16x32_bf16 v[8:11], v[112:115], v[192:195], v[8:11]
	v_mfma_f32_16x16x32_bf16 v[4:7], v[100:103], v[204:207], v[4:7]
	v_mfma_f32_16x16x32_bf16 v[0:3], v[112:115], v[200:203], v[0:3]
	v_mfma_f32_16x16x32_bf16 v[160:163], v[100:103], v[84:87], v[28:31]
	v_mfma_f32_16x16x32_bf16 v[164:167], v[116:119], v[84:87], v[24:27]
	v_mfma_f32_16x16x32_bf16 v[168:171], v[100:103], v[196:199], v[12:15]
	v_mfma_f32_16x16x32_bf16 v[172:175], v[116:119], v[196:199], v[8:11]
	v_mfma_f32_16x16x32_bf16 v[184:187], v[116:119], v[204:207], v[0:3]
	s_barrier
	s_nop 0
	ds_read_b128 v[0:3], v146
	ds_read_b128 v[8:11], v147
	ds_read_b128 v[12:15], v148
	ds_read_b128 v[188:191], v149
	ds_read_b128 v[24:27], v158 offset:32768
	ds_read_b128 v[28:31], v158 offset:33792
	ds_read_b128 v[40:43], v158 offset:34816
	ds_read_b128 v[44:47], v158 offset:35840
	ds_read_b128 v[56:59], v158 offset:36864
	ds_read_b128 v[60:63], v158 offset:37888
	ds_read_b128 v[192:195], v158 offset:38912
	ds_read_b128 v[196:199], v158 offset:39936
	s_waitcnt vmcnt(2)
	s_barrier
	s_waitcnt lgkmcnt(0)
	s_waitcnt lgkmcnt(0)
	v_mfma_f32_16x16x32_bf16 v[48:51], v[0:3], v[24:27], v[124:127]
	v_mfma_f32_16x16x32_bf16 v[112:115], v[8:11], v[28:31], v[48:51]
	v_mfma_f32_16x16x32_bf16 v[48:51], v[12:15], v[24:27], v[120:123]
	v_mfma_f32_16x16x32_bf16 v[116:119], v[188:191], v[28:31], v[48:51]
	v_mfma_f32_16x16x32_bf16 v[48:51], v[0:3], v[40:43], v[134:137]
	v_mfma_f32_16x16x32_bf16 v[96:99], v[8:11], v[44:47], v[48:51]
	v_mfma_f32_16x16x32_bf16 v[48:51], v[12:15], v[40:43], v[208:211]
	v_mfma_f32_16x16x32_bf16 v[100:103], v[188:191], v[44:47], v[48:51]
	v_mfma_f32_16x16x32_bf16 v[48:51], v[0:3], v[56:59], v[108:111]
	v_mfma_f32_16x16x32_bf16 v[80:83], v[8:11], v[60:63], v[48:51]
	v_mfma_f32_16x16x32_bf16 v[48:51], v[12:15], v[56:59], v[104:107]
	v_mfma_f32_16x16x32_bf16 v[84:87], v[188:191], v[60:63], v[48:51]
	v_mfma_f32_16x16x32_bf16 v[48:51], v[0:3], v[192:195], v[212:215]
	v_mfma_f32_16x16x32_bf16 v[52:55], v[12:15], v[192:195], v[216:219]
	v_mfma_f32_16x16x32_bf16 v[48:51], v[8:11], v[196:199], v[48:51]
	v_mfma_f32_16x16x32_bf16 v[52:55], v[188:191], v[196:199], v[52:55]
	s_barrier
; #define LDA(dst, b, h) for (int m = 0; m < 4; ++m) for (int k = 0; k < 2; ++k) \
;     dst[m][k] = *reinterpret_cast<const bf16x8*>(aRd + (((b) * 2 + (h)) * G_HT * 2 + m * 2048 + k * 1024))
; #define LDB(dst, b, h) for (int n = 0; n < 2; ++n) for (int k = 0; k < 2; ++k) \
;     dst[n][k] = *reinterpret_cast<const bf16x8*>(bRd + (((b) * 2 + (h)) * G_HT * 2 + n * 2048 + k * 1024))
; #define MMA(ai, bj, At, Bx) do { __builtin_amdgcn_s_setprio(1); \
;     for (int m = 0; m < 4; ++m) for (int n = 0; n < 2; ++n) for (int k = 0; k < 2; ++k) \
;       acc[ai][bj][m][n] = __builtin_amdgcn_mfma_f32_16x16x32_bf16(Bx[n][k], At[m][k], acc[ai][bj][m][n], 0, 0, 0);     \
;     __builtin_amdgcn_s_setprio(0); } while (0)
; #define WAIT_V(n) asm volatile("s_waitcnt vmcnt(" #n ")" ::: "memory")
; #define WAIT_L(n) asm volatile("s_waitcnt lgkmcnt(" #n ")" ::: "memory")
; #define BAR __builtin_amdgcn_s_barrier()
; template <int EPI>
; __device__ __forceinline__ void gemm_tile(const bf16* __restrict__ A, int lda, const bf16* __restrict__ Bt, int K,
;                                           int brow, int bcol, const EpiArgs& ea, char* shmc, bool has_next, int nbrow, int nbcol, bool first_tile) {
;     ...
;     LDB(B1, 1, 1); WAIT_V(0); BAR; WAIT_L(0); MMA(0, 1, At, B1); BAR;
;     LDA(At, 1, 1); BAR; WAIT_L(0); MMA(1, 0, At, B0); MMA(1, 1, At, B1); BAR; }
;   if (wr == 0) BAR;
	ds_read_b128 v[134:137], v150
	ds_read_b128 v[200:203], v151
	ds_read_b128 v[204:207], v152
	ds_read_b128 v[208:211], v153
	s_waitcnt vmcnt(0)
	s_barrier
	s_waitcnt lgkmcnt(0)
	s_waitcnt lgkmcnt(0)
	v_mfma_f32_16x16x32_bf16 v[92:95], v[134:137], v[24:27], v[92:95]
	v_mfma_f32_16x16x32_bf16 v[24:27], v[204:207], v[24:27], v[88:91]
	v_mfma_f32_16x16x32_bf16 v[124:127], v[208:211], v[28:31], v[24:27]
	v_mfma_f32_16x16x32_bf16 v[24:27], v[134:137], v[40:43], v[176:179]
	v_mfma_f32_16x16x32_bf16 v[104:107], v[200:203], v[44:47], v[24:27]
	v_mfma_f32_16x16x32_bf16 v[24:27], v[204:207], v[40:43], v[180:183]
	v_mfma_f32_16x16x32_bf16 v[108:111], v[208:211], v[44:47], v[24:27]
	v_mfma_f32_16x16x32_bf16 v[24:27], v[134:137], v[56:59], v[76:79]
	v_mfma_f32_16x16x32_bf16 v[88:91], v[200:203], v[60:63], v[24:27]
	v_mfma_f32_16x16x32_bf16 v[24:27], v[204:207], v[56:59], v[72:75]
	v_mfma_f32_16x16x32_bf16 v[120:123], v[200:203], v[28:31], v[92:95]
	v_mfma_f32_16x16x32_bf16 v[92:95], v[208:211], v[60:63], v[24:27]
	v_mfma_f32_16x16x32_bf16 v[24:27], v[134:137], v[192:195], v[68:71]
	v_mfma_f32_16x16x32_bf16 v[56:59], v[200:203], v[196:199], v[24:27]
	v_mfma_f32_16x16x32_bf16 v[24:27], v[204:207], v[192:195], v[64:67]
	v_mfma_f32_16x16x32_bf16 v[60:63], v[208:211], v[196:199], v[24:27]
	s_barrier
	ds_read_b128 v[68:71], v158 offset:49152
	ds_read_b128 v[176:179], v158 offset:50176
	ds_read_b128 v[180:183], v158 offset:51200
	ds_read_b128 v[192:195], v158 offset:52224
	ds_read_b128 v[196:199], v158 offset:53248
	ds_read_b128 v[212:215], v158 offset:54272
	ds_read_b128 v[216:219], v158 offset:55296
	ds_read_b128 v[244:247], v158 offset:56320
	s_barrier
	s_waitcnt lgkmcnt(0)
	s_waitcnt lgkmcnt(0)
	v_mfma_f32_16x16x32_bf16 v[24:27], v[0:3], v[68:71], v[220:223]
	v_mfma_f32_16x16x32_bf16 v[72:75], v[8:11], v[176:179], v[24:27]
	v_mfma_f32_16x16x32_bf16 v[24:27], v[12:15], v[68:71], v[224:227]
	v_mfma_f32_16x16x32_bf16 v[76:79], v[188:191], v[176:179], v[24:27]
	v_mfma_f32_16x16x32_bf16 v[24:27], v[0:3], v[180:183], v[228:231]
	v_mfma_f32_16x16x32_bf16 v[40:43], v[8:11], v[192:195], v[24:27]
	v_mfma_f32_16x16x32_bf16 v[24:27], v[12:15], v[180:183], v[232:235]
	v_mfma_f32_16x16x32_bf16 v[44:47], v[188:191], v[192:195], v[24:27]
	v_mfma_f32_16x16x32_bf16 v[24:27], v[0:3], v[196:199], v[236:239]
	v_mfma_f32_16x16x32_bf16 v[0:3], v[0:3], v[216:219], v[36:39]
	v_mfma_f32_16x16x32_bf16 v[24:27], v[8:11], v[212:215], v[24:27]
	v_mfma_f32_16x16x32_bf16 v[28:31], v[12:15], v[196:199], v[240:243]
	v_mfma_f32_16x16x32_bf16 v[8:11], v[8:11], v[244:247], v[0:3]
	v_mfma_f32_16x16x32_bf16 v[0:3], v[12:15], v[216:219], v[32:35]
	v_mfma_f32_16x16x32_bf16 v[28:31], v[188:191], v[212:215], v[28:31]
	v_mfma_f32_16x16x32_bf16 v[12:15], v[188:191], v[244:247], v[0:3]
	v_mfma_f32_16x16x32_bf16 v[0:3], v[134:137], v[68:71], v[160:163]
	v_mfma_f32_16x16x32_bf16 v[64:67], v[200:203], v[176:179], v[0:3]
	v_mfma_f32_16x16x32_bf16 v[0:3], v[204:207], v[68:71], v[164:167]
	v_mfma_f32_16x16x32_bf16 v[68:71], v[208:211], v[176:179], v[0:3]
	v_mfma_f32_16x16x32_bf16 v[0:3], v[134:137], v[180:183], v[20:23]
	v_mfma_f32_16x16x32_bf16 v[32:35], v[200:203], v[192:195], v[0:3]
	v_mfma_f32_16x16x32_bf16 v[0:3], v[204:207], v[180:183], v[16:19]
	v_mfma_f32_16x16x32_bf16 v[36:39], v[208:211], v[192:195], v[0:3]
	v_mfma_f32_16x16x32_bf16 v[0:3], v[134:137], v[196:199], v[168:171]
	v_mfma_f32_16x16x32_bf16 v[16:19], v[200:203], v[212:215], v[0:3]
	v_mfma_f32_16x16x32_bf16 v[0:3], v[204:207], v[196:199], v[172:175]
	v_mfma_f32_16x16x32_bf16 v[20:23], v[208:211], v[212:215], v[0:3]
	v_mfma_f32_16x16x32_bf16 v[0:3], v[134:137], v[216:219], v[4:7]
	v_mfma_f32_16x16x32_bf16 v[4:7], v[204:207], v[216:219], v[184:187]
	v_mfma_f32_16x16x32_bf16 v[0:3], v[200:203], v[244:247], v[0:3]
	v_mfma_f32_16x16x32_bf16 v[4:7], v[208:211], v[244:247], v[4:7]
	s_barrier
	s_and_saveexec_b64 s[30:31], s[4:5]
	s_cbranch_execz .LBB0_313
	s_barrier

; #define STA(b, h, half, kt) STAGE(((b) * 2 + (h)) * G_HT * 2, pA, ((size_t)(half) * G_HALF * lda + (size_t)(kt) * G_BK) * 2, lda)
; #define STB(b, h, half, kt) STAGE((4 + (b) * 2 + (h)) * G_HT * 2, pB, ((size_t)(half) * G_HALF * K + (size_t)(kt) * G_BK) * 2, K)
; #define LDA(dst, b, h) for (int m = 0; m < 4; ++m) for (int k = 0; k < 2; ++k) \
;     dst[m][k] = *reinterpret_cast<const bf16x8*>(aRd + (((b) * 2 + (h)) * G_HT * 2 + m * 2048 + k * 1024))
; #define LDB(dst, b, h) for (int n = 0; n < 2; ++n) for (int k = 0; k < 2; ++k) \
;     dst[n][k] = *reinterpret_cast<const bf16x8*>(bRd + (((b) * 2 + (h)) * G_HT * 2 + n * 2048 + k * 1024))
; #define MMA(ai, bj, At, Bx) do { __builtin_amdgcn_s_setprio(1); \
;     for (int m = 0; m < 4; ++m) for (int n = 0; n < 2; ++n) for (int k = 0; k < 2; ++k) \
;       acc[ai][bj][m][n] = __builtin_amdgcn_mfma_f32_16x16x32_bf16(Bx[n][k], At[m][k], acc[ai][bj][m][n], 0, 0, 0);     \
;     __builtin_amdgcn_s_setprio(0); } while (0)
; #define WAIT_V(n) asm volatile("s_waitcnt vmcnt(" #n ")" ::: "memory")
; #define WAIT_L(n) asm volatile("s_waitcnt lgkmcnt(" #n ")" ::: "memory")
; #define BAR __builtin_amdgcn_s_barrier()
; #define SCHED __builtin_amdgcn_sched_barrier(0)
; template <int EPI>
; __device__ __forceinline__ void gemm_tile(const bf16* __restrict__ A, int lda, const bf16* __restrict__ Bt, int K,
;                                           int brow, int bcol, const EpiArgs& ea, char* shmc, bool has_next, int nbrow, int nbcol, bool first_tile) {
;     ...
;     LDB(B0, 0, 0); SCHED; LDA(At, 0, 0); STA(1, 1, 1, t + 1);
;     WAIT_L(8); BAR; WAIT_L(0); MMA(0, 0, At, B0); BAR; SCHED;
;     LDB(B1, 0, 1); STB(0, 0, 0, t + 2);
;     BAR; WAIT_L(0); MMA(0, 1, At, B1); BAR;
;     LDA(At, 0, 1); STA(0, 0, 0, t + 2);
;     BAR; WAIT_L(0); MMA(1, 0, At, B0); BAR; SCHED;
;     STB(0, 1, 1, t + 2);
;     WAIT_V(6); BAR; MMA(1, 1, At, B1); BAR;
.LBB0_654:
	ds_read_b128 v[140:143], v145
	ds_read_b128 v[166:169], v146
	ds_read_b128 v[170:173], v147
	ds_read_b128 v[174:177], v148
	s_add_u32 s42, s14, 0xffffff00
	s_addc_u32 s43, s15, -1
	s_mov_b32 m0, s29
	ds_read_b128 v[178:181], v164
	ds_read_b128 v[182:185], v164 offset:1024
	ds_read_b128 v[186:189], v164 offset:2048
	ds_read_b128 v[190:193], v164 offset:3072
	ds_read_b128 v[194:197], v164 offset:4096
	ds_read_b128 v[198:201], v164 offset:5120
	ds_read_b128 v[202:205], v164 offset:6144
	ds_read_b128 v[206:209], v164 offset:7168
	v_lshl_add_u64 v[210:211], v[136:137], 0, s[42:43]
	global_load_lds_dwordx4 v[210:211], off
	v_lshl_add_u64 v[210:211], v[210:211], 0, s[10:11]
	s_mov_b32 m0, s21
	s_nop 0
	global_load_lds_dwordx4 v[210:211], off
	s_waitcnt lgkmcnt(8)
	s_barrier
	s_waitcnt lgkmcnt(0)
	v_mfma_f32_16x16x32_bf16 v[124:127], v[140:143], v[178:181], v[124:127]
	v_mfma_f32_16x16x32_bf16 v[120:123], v[170:173], v[178:181], v[120:123]
	v_mfma_f32_16x16x32_bf16 v[116:119], v[140:143], v[186:189], v[116:119]
	v_mfma_f32_16x16x32_bf16 v[112:115], v[170:173], v[186:189], v[112:115]
	v_mfma_f32_16x16x32_bf16 v[108:111], v[140:143], v[194:197], v[108:111]
	v_mfma_f32_16x16x32_bf16 v[104:107], v[170:173], v[194:197], v[104:107]
	v_mfma_f32_16x16x32_bf16 v[100:103], v[140:143], v[202:205], v[100:103]
	v_mfma_f32_16x16x32_bf16 v[96:99], v[170:173], v[202:205], v[96:99]
	v_mfma_f32_16x16x32_bf16 v[124:127], v[166:169], v[182:185], v[124:127]
	v_mfma_f32_16x16x32_bf16 v[120:123], v[174:177], v[182:185], v[120:123]
	v_mfma_f32_16x16x32_bf16 v[116:119], v[166:169], v[190:193], v[116:119]
	v_mfma_f32_16x16x32_bf16 v[112:115], v[174:177], v[190:193], v[112:115]
	v_mfma_f32_16x16x32_bf16 v[108:111], v[166:169], v[198:201], v[108:111]
	v_mfma_f32_16x16x32_bf16 v[104:107], v[174:177], v[198:201], v[104:107]
	v_mfma_f32_16x16x32_bf16 v[100:103], v[166:169], v[206:209], v[100:103]
	v_mfma_f32_16x16x32_bf16 v[96:99], v[174:177], v[206:209], v[96:99]
	s_barrier
	s_add_u32 s42, s14, 0xffefff80
	s_addc_u32 s43, s15, -1
	s_mov_b64 s[48:49], s[42:43]
	s_mov_b32 m0, s24
	ds_read_b128 v[210:213], v149
	ds_read_b128 v[214:217], v150
	ds_read_b128 v[218:221], v151
	ds_read_b128 v[222:225], v152
	v_lshl_add_u64 v[226:227], v[138:139], 0, s[48:49]
	global_load_lds_dwordx4 v[226:227], off
	v_lshl_add_u64 v[226:227], v[226:227], 0, s[10:11]
	s_mov_b32 m0, s25
	s_nop 0
	global_load_lds_dwordx4 v[226:227], off
	s_barrier
	s_waitcnt lgkmcnt(0)
	v_mfma_f32_16x16x32_bf16 v[92:95], v[210:213], v[178:181], v[92:95]
	v_mfma_f32_16x16x32_bf16 v[88:91], v[218:221], v[178:181], v[88:91]
	v_mfma_f32_16x16x32_bf16 v[84:87], v[210:213], v[186:189], v[84:87]
	v_mfma_f32_16x16x32_bf16 v[80:83], v[218:221], v[186:189], v[80:83]
	v_mfma_f32_16x16x32_bf16 v[76:79], v[210:213], v[194:197], v[76:79]
	v_mfma_f32_16x16x32_bf16 v[72:75], v[218:221], v[194:197], v[72:75]
	v_mfma_f32_16x16x32_bf16 v[68:71], v[210:213], v[202:205], v[68:71]
	v_mfma_f32_16x16x32_bf16 v[64:67], v[218:221], v[202:205], v[64:67]
	v_mfma_f32_16x16x32_bf16 v[92:95], v[214:217], v[182:185], v[92:95]
	v_mfma_f32_16x16x32_bf16 v[88:91], v[222:225], v[182:185], v[88:91]
	v_mfma_f32_16x16x32_bf16 v[84:87], v[214:217], v[190:193], v[84:87]
	v_mfma_f32_16x16x32_bf16 v[80:83], v[222:225], v[190:193], v[80:83]
	v_mfma_f32_16x16x32_bf16 v[76:79], v[214:217], v[198:201], v[76:79]
	v_mfma_f32_16x16x32_bf16 v[72:75], v[222:225], v[198:201], v[72:75]
	v_mfma_f32_16x16x32_bf16 v[68:71], v[214:217], v[206:209], v[68:71]
	v_mfma_f32_16x16x32_bf16 v[64:67], v[222:225], v[206:209], v[64:67]
	s_mov_b32 m0, s1
	s_barrier
	ds_read_b128 v[178:181], v164 offset:16384
	ds_read_b128 v[182:185], v164 offset:17408
	ds_read_b128 v[186:189], v164 offset:18432
	ds_read_b128 v[190:193], v164 offset:19456
	ds_read_b128 v[194:197], v164 offset:20480
	ds_read_b128 v[198:201], v164 offset:21504
	ds_read_b128 v[202:205], v164 offset:22528
	ds_read_b128 v[206:209], v164 offset:23552
	v_lshl_add_u64 v[226:227], v[136:137], 0, s[42:43]
	global_load_lds_dwordx4 v[226:227], off
	v_lshl_add_u64 v[226:227], v[226:227], 0, s[10:11]
	s_mov_b32 m0, s30
	s_nop 0
	global_load_lds_dwordx4 v[226:227], off
	s_barrier
	s_waitcnt lgkmcnt(0)
	v_mfma_f32_16x16x32_bf16 v[60:63], v[140:143], v[178:181], v[60:63]
	v_mfma_f32_16x16x32_bf16 v[56:59], v[170:173], v[178:181], v[56:59]
	v_mfma_f32_16x16x32_bf16 v[52:55], v[140:143], v[186:189], v[52:55]
	v_mfma_f32_16x16x32_bf16 v[48:51], v[170:173], v[186:189], v[48:51]
	v_mfma_f32_16x16x32_bf16 v[44:47], v[140:143], v[194:197], v[44:47]
	v_mfma_f32_16x16x32_bf16 v[40:43], v[170:173], v[194:197], v[40:43]
	v_mfma_f32_16x16x32_bf16 v[36:39], v[140:143], v[202:205], v[36:39]
	v_mfma_f32_16x16x32_bf16 v[32:35], v[170:173], v[202:205], v[32:35]
	v_mfma_f32_16x16x32_bf16 v[60:63], v[166:169], v[182:185], v[60:63]
	v_mfma_f32_16x16x32_bf16 v[56:59], v[174:177], v[182:185], v[56:59]
	v_mfma_f32_16x16x32_bf16 v[52:55], v[166:169], v[190:193], v[52:55]
	v_mfma_f32_16x16x32_bf16 v[48:51], v[174:177], v[190:193], v[48:51]
	v_mfma_f32_16x16x32_bf16 v[44:47], v[166:169], v[198:201], v[44:47]
	v_mfma_f32_16x16x32_bf16 v[40:43], v[174:177], v[198:201], v[40:43]
	v_mfma_f32_16x16x32_bf16 v[36:39], v[166:169], v[206:209], v[36:39]
	v_mfma_f32_16x16x32_bf16 v[32:35], v[174:177], v[206:209], v[32:35]
	s_barrier
	s_add_u32 s42, s14, 0xffffff80
	s_addc_u32 s43, s15, -1
	s_mov_b64 s[48:49], s[42:43]
	s_mov_b32 m0, s26
	v_lshl_add_u64 v[140:141], v[138:139], 0, s[48:49]
	global_load_lds_dwordx4 v[140:141], off
	v_lshl_add_u64 v[140:141], v[140:141], 0, s[10:11]
	s_mov_b32 m0, s27
	s_nop 0
	global_load_lds_dwordx4 v[140:141], off
	s_waitcnt vmcnt(6)
	s_barrier
; #define STA(b, h, half, kt) STAGE(((b) * 2 + (h)) * G_HT * 2, pA, ((size_t)(half) * G_HALF * lda + (size_t)(kt) * G_BK) * 2, lda)
; #define STB(b, h, half, kt) STAGE((4 + (b) * 2 + (h)) * G_HT * 2, pB, ((size_t)(half) * G_HALF * K + (size_t)(kt) * G_BK) * 2, K)
; #define LDA(dst, b, h) for (int m = 0; m < 4; ++m) for (int k = 0; k < 2; ++k) \
;     dst[m][k] = *reinterpret_cast<const bf16x8*>(aRd + (((b) * 2 + (h)) * G_HT * 2 + m * 2048 + k * 1024))
; #define LDB(dst, b, h) for (int n = 0; n < 2; ++n) for (int k = 0; k < 2; ++k) \
;     dst[n][k] = *reinterpret_cast<const bf16x8*>(bRd + (((b) * 2 + (h)) * G_HT * 2 + n * 2048 + k * 1024))
; #define MMA(ai, bj, At, Bx) do { __builtin_amdgcn_s_setprio(1); \
;     for (int m = 0; m < 4; ++m) for (int n = 0; n < 2; ++n) for (int k = 0; k < 2; ++k) \
;       acc[ai][bj][m][n] = __builtin_amdgcn_mfma_f32_16x16x32_bf16(Bx[n][k], At[m][k], acc[ai][bj][m][n], 0, 0, 0);     \
;     __builtin_amdgcn_s_setprio(0); } while (0)
; #define WAIT_V(n) asm volatile("s_waitcnt vmcnt(" #n ")" ::: "memory")
; #define WAIT_L(n) asm volatile("s_waitcnt lgkmcnt(" #n ")" ::: "memory")
; #define BAR __builtin_amdgcn_s_barrier()
; #define SCHED __builtin_amdgcn_sched_barrier(0)
; template <int EPI>
; __device__ __forceinline__ void gemm_tile(const bf16* __restrict__ A, int lda, const bf16* __restrict__ Bt, int K,
;                                           int brow, int bcol, const EpiArgs& ea, char* shmc, bool has_next, int nbrow, int nbcol, bool first_tile) {
;     ...
;     WAIT_V(6); BAR; MMA(1, 1, At, B1); BAR;
;     LDB(B0, 1, 0); SCHED; LDA(At, 1, 0); STA(0, 1, 1, t + 2);
;     WAIT_L(8); BAR; WAIT_L(0); MMA(0, 0, At, B0); BAR; SCHED;
;     LDB(B1, 1, 1); STB(1, 0, 0, t + 3);
;     BAR; WAIT_L(0); MMA(0, 1, At, B1); BAR;
;     LDA(At, 1, 1); STA(1, 0, 0, t + 3);
	v_mfma_f32_16x16x32_bf16 v[28:31], v[210:213], v[178:181], v[28:31]
	v_mfma_f32_16x16x32_bf16 v[24:27], v[218:221], v[178:181], v[24:27]
	v_mfma_f32_16x16x32_bf16 v[20:23], v[210:213], v[186:189], v[20:23]
	v_mfma_f32_16x16x32_bf16 v[16:19], v[218:221], v[186:189], v[16:19]
	v_mfma_f32_16x16x32_bf16 v[12:15], v[210:213], v[194:197], v[12:15]
	v_mfma_f32_16x16x32_bf16 v[8:11], v[218:221], v[194:197], v[8:11]
	v_mfma_f32_16x16x32_bf16 v[4:7], v[210:213], v[202:205], v[4:7]
	v_mfma_f32_16x16x32_bf16 v[0:3], v[218:221], v[202:205], v[0:3]
	v_mfma_f32_16x16x32_bf16 v[28:31], v[214:217], v[182:185], v[28:31]
	v_mfma_f32_16x16x32_bf16 v[24:27], v[222:225], v[182:185], v[24:27]
	v_mfma_f32_16x16x32_bf16 v[20:23], v[214:217], v[190:193], v[20:23]
	v_mfma_f32_16x16x32_bf16 v[16:19], v[222:225], v[190:193], v[16:19]
	v_mfma_f32_16x16x32_bf16 v[12:15], v[214:217], v[198:201], v[12:15]
	v_mfma_f32_16x16x32_bf16 v[8:11], v[222:225], v[198:201], v[8:11]
	v_mfma_f32_16x16x32_bf16 v[4:7], v[214:217], v[206:209], v[4:7]
	v_mfma_f32_16x16x32_bf16 v[0:3], v[222:225], v[206:209], v[0:3]
	s_barrier
	ds_read_b128 v[140:143], v153
	ds_read_b128 v[166:169], v154
	ds_read_b128 v[170:173], v155
	ds_read_b128 v[174:177], v156
	s_mov_b32 m0, s31
	ds_read_b128 v[178:181], v164 offset:32768
	ds_read_b128 v[182:185], v164 offset:33792
	ds_read_b128 v[186:189], v164 offset:34816
	ds_read_b128 v[190:193], v164 offset:35840
	ds_read_b128 v[194:197], v164 offset:36864
	ds_read_b128 v[198:201], v164 offset:37888
	ds_read_b128 v[202:205], v164 offset:38912
	ds_read_b128 v[206:209], v164 offset:39936
	v_lshl_add_u64 v[210:211], v[136:137], 0, s[42:43]
	global_load_lds_dwordx4 v[210:211], off
	v_lshl_add_u64 v[210:211], v[210:211], 0, s[10:11]
	s_mov_b32 m0, s34
	s_nop 0
	global_load_lds_dwordx4 v[210:211], off
	s_waitcnt lgkmcnt(8)
	s_barrier
	s_waitcnt lgkmcnt(0)
	v_mfma_f32_16x16x32_bf16 v[124:127], v[140:143], v[178:181], v[124:127]
	v_mfma_f32_16x16x32_bf16 v[120:123], v[170:173], v[178:181], v[120:123]
	v_mfma_f32_16x16x32_bf16 v[116:119], v[140:143], v[186:189], v[116:119]
	v_mfma_f32_16x16x32_bf16 v[112:115], v[170:173], v[186:189], v[112:115]
	v_mfma_f32_16x16x32_bf16 v[108:111], v[140:143], v[194:197], v[108:111]
	v_mfma_f32_16x16x32_bf16 v[104:107], v[170:173], v[194:197], v[104:107]
	v_mfma_f32_16x16x32_bf16 v[100:103], v[140:143], v[202:205], v[100:103]
	v_mfma_f32_16x16x32_bf16 v[96:99], v[170:173], v[202:205], v[96:99]
	v_mfma_f32_16x16x32_bf16 v[124:127], v[166:169], v[182:185], v[124:127]
	v_mfma_f32_16x16x32_bf16 v[120:123], v[174:177], v[182:185], v[120:123]
	v_mfma_f32_16x16x32_bf16 v[116:119], v[166:169], v[190:193], v[116:119]
	v_mfma_f32_16x16x32_bf16 v[112:115], v[174:177], v[190:193], v[112:115]
	v_mfma_f32_16x16x32_bf16 v[108:111], v[166:169], v[198:201], v[108:111]
	v_mfma_f32_16x16x32_bf16 v[104:107], v[174:177], v[198:201], v[104:107]
	v_mfma_f32_16x16x32_bf16 v[100:103], v[166:169], v[206:209], v[100:103]
	v_mfma_f32_16x16x32_bf16 v[96:99], v[174:177], v[206:209], v[96:99]
	s_barrier
	s_add_u32 s42, s14, 0xfff00000
	s_addc_u32 s43, s15, -1
	s_mov_b64 s[48:49], s[42:43]
	s_mov_b32 m0, s13
	ds_read_b128 v[210:213], v158
	ds_read_b128 v[214:217], v159
	ds_read_b128 v[218:221], v160
	ds_read_b128 v[222:225], v161
	v_lshl_add_u64 v[226:227], v[138:139], 0, s[48:49]
	global_load_lds_dwordx4 v[226:227], off
	v_lshl_add_u64 v[226:227], v[226:227], 0, s[10:11]
	s_mov_b32 m0, s18
	s_nop 0
	global_load_lds_dwordx4 v[226:227], off
	s_barrier
	s_waitcnt lgkmcnt(0)
	v_mfma_f32_16x16x32_bf16 v[92:95], v[210:213], v[178:181], v[92:95]
	v_mfma_f32_16x16x32_bf16 v[88:91], v[218:221], v[178:181], v[88:91]
	v_mfma_f32_16x16x32_bf16 v[84:87], v[210:213], v[186:189], v[84:87]
	v_mfma_f32_16x16x32_bf16 v[80:83], v[218:221], v[186:189], v[80:83]
	v_mfma_f32_16x16x32_bf16 v[76:79], v[210:213], v[194:197], v[76:79]
	v_mfma_f32_16x16x32_bf16 v[72:75], v[218:221], v[194:197], v[72:75]
	v_mfma_f32_16x16x32_bf16 v[68:71], v[210:213], v[202:205], v[68:71]
	v_mfma_f32_16x16x32_bf16 v[64:67], v[218:221], v[202:205], v[64:67]
	v_mfma_f32_16x16x32_bf16 v[92:95], v[214:217], v[182:185], v[92:95]
	v_mfma_f32_16x16x32_bf16 v[88:91], v[222:225], v[182:185], v[88:91]
	v_mfma_f32_16x16x32_bf16 v[84:87], v[214:217], v[190:193], v[84:87]
	v_mfma_f32_16x16x32_bf16 v[80:83], v[222:225], v[190:193], v[80:83]
	v_mfma_f32_16x16x32_bf16 v[76:79], v[214:217], v[198:201], v[76:79]
	v_mfma_f32_16x16x32_bf16 v[72:75], v[222:225], v[198:201], v[72:75]
	v_mfma_f32_16x16x32_bf16 v[68:71], v[214:217], v[206:209], v[68:71]
	v_mfma_f32_16x16x32_bf16 v[64:67], v[222:225], v[206:209], v[64:67]
	s_mov_b32 m0, s19
	s_barrier
	ds_read_b128 v[178:181], v164 offset:49152
	ds_read_b128 v[182:185], v164 offset:50176
	ds_read_b128 v[186:189], v164 offset:51200
	ds_read_b128 v[190:193], v164 offset:52224
	ds_read_b128 v[194:197], v164 offset:53248
	ds_read_b128 v[198:201], v164 offset:54272
	ds_read_b128 v[202:205], v164 offset:55296
	ds_read_b128 v[206:209], v164 offset:56320
	v_lshl_add_u64 v[226:227], v[136:137], 0, s[42:43]
	global_load_lds_dwordx4 v[226:227], off
	v_lshl_add_u64 v[226:227], v[226:227], 0, s[10:11]
	s_mov_b32 m0, s20
	s_nop 0
	global_load_lds_dwordx4 v[226:227], off
	s_barrier
; #define STA(b, h, half, kt) STAGE(((b) * 2 + (h)) * G_HT * 2, pA, ((size_t)(half) * G_HALF * lda + (size_t)(kt) * G_BK) * 2, lda)
; #define STB(b, h, half, kt) STAGE((4 + (b) * 2 + (h)) * G_HT * 2, pB, ((size_t)(half) * G_HALF * K + (size_t)(kt) * G_BK) * 2, K)
; #define LDA(dst, b, h) for (int m = 0; m < 4; ++m) for (int k = 0; k < 2; ++k) \
;     dst[m][k] = *reinterpret_cast<const bf16x8*>(aRd + (((b) * 2 + (h)) * G_HT * 2 + m * 2048 + k * 1024))
; #define LDB(dst, b, h) for (int n = 0; n < 2; ++n) for (int k = 0; k < 2; ++k) \
;     dst[n][k] = *reinterpret_cast<const bf16x8*>(bRd + (((b) * 2 + (h)) * G_HT * 2 + n * 2048 + k * 1024))
; #define MMA(ai, bj, At, Bx) do { __builtin_amdgcn_s_setprio(1); \
;     for (int m = 0; m < 4; ++m) for (int n = 0; n < 2; ++n) for (int k = 0; k < 2; ++k) \
;       acc[ai][bj][m][n] = __builtin_amdgcn_mfma_f32_16x16x32_bf16(Bx[n][k], At[m][k], acc[ai][bj][m][n], 0, 0, 0);     \
;     __builtin_amdgcn_s_setprio(0); } while (0)
; #define WAIT_V(n) asm volatile("s_waitcnt vmcnt(" #n ")" ::: "memory")
; #define WAIT_L(n) asm volatile("s_waitcnt lgkmcnt(" #n ")" ::: "memory")
; #define BAR __builtin_amdgcn_s_barrier()
; #define SCHED __builtin_amdgcn_sched_barrier(0)
; template <int EPI>
; __device__ __forceinline__ void gemm_tile(const bf16* __restrict__ A, int lda, const bf16* __restrict__ Bt, int K,
;                                           int brow, int bcol, const EpiArgs& ea, char* shmc, bool has_next, int nbrow, int nbcol, bool first_tile) {
;     ...
;     BAR; WAIT_L(0); MMA(1, 0, At, B0); BAR; SCHED;
;     STB(1, 1, 1, t + 3);
;     WAIT_V(6); BAR; MMA(1, 1, At, B1); BAR;
;   }
;   { LDB(B0, 0, 0); LDA(At, 0, 0); STA(1, 1, 1, nt - 1);
;     BAR; WAIT_L(0); MMA(0, 0, At, B0); BAR;
;     LDB(B1, 0, 1); BAR; WAIT_L(0); MMA(0, 1, At, B1); BAR;
	s_waitcnt lgkmcnt(0)
	v_mfma_f32_16x16x32_bf16 v[60:63], v[140:143], v[178:181], v[60:63]
	v_mfma_f32_16x16x32_bf16 v[56:59], v[170:173], v[178:181], v[56:59]
	v_mfma_f32_16x16x32_bf16 v[52:55], v[140:143], v[186:189], v[52:55]
	v_mfma_f32_16x16x32_bf16 v[48:51], v[170:173], v[186:189], v[48:51]
	v_mfma_f32_16x16x32_bf16 v[44:47], v[140:143], v[194:197], v[44:47]
	v_mfma_f32_16x16x32_bf16 v[40:43], v[170:173], v[194:197], v[40:43]
	v_mfma_f32_16x16x32_bf16 v[36:39], v[140:143], v[202:205], v[36:39]
	v_mfma_f32_16x16x32_bf16 v[32:35], v[170:173], v[202:205], v[32:35]
	v_mfma_f32_16x16x32_bf16 v[60:63], v[166:169], v[182:185], v[60:63]
	v_mfma_f32_16x16x32_bf16 v[56:59], v[174:177], v[182:185], v[56:59]
	v_mfma_f32_16x16x32_bf16 v[52:55], v[166:169], v[190:193], v[52:55]
	v_mfma_f32_16x16x32_bf16 v[48:51], v[174:177], v[190:193], v[48:51]
	v_mfma_f32_16x16x32_bf16 v[44:47], v[166:169], v[198:201], v[44:47]
	v_mfma_f32_16x16x32_bf16 v[40:43], v[174:177], v[198:201], v[40:43]
	v_mfma_f32_16x16x32_bf16 v[36:39], v[166:169], v[206:209], v[36:39]
	v_mfma_f32_16x16x32_bf16 v[32:35], v[174:177], v[206:209], v[32:35]
	s_barrier
	s_mov_b64 s[42:43], s[14:15]
	s_mov_b32 m0, s22
	v_lshl_add_u64 v[140:141], v[138:139], 0, s[42:43]
	global_load_lds_dwordx4 v[140:141], off
	v_lshl_add_u64 v[140:141], v[140:141], 0, s[10:11]
	s_mov_b32 m0, s23
	s_nop 0
	global_load_lds_dwordx4 v[140:141], off
	s_waitcnt vmcnt(6)
	s_barrier
	v_mfma_f32_16x16x32_bf16 v[28:31], v[210:213], v[178:181], v[28:31]
	v_mfma_f32_16x16x32_bf16 v[24:27], v[218:221], v[178:181], v[24:27]
	v_mfma_f32_16x16x32_bf16 v[20:23], v[210:213], v[186:189], v[20:23]
	v_mfma_f32_16x16x32_bf16 v[16:19], v[218:221], v[186:189], v[16:19]
	v_mfma_f32_16x16x32_bf16 v[12:15], v[210:213], v[194:197], v[12:15]
	v_mfma_f32_16x16x32_bf16 v[8:11], v[218:221], v[194:197], v[8:11]
	v_mfma_f32_16x16x32_bf16 v[4:7], v[210:213], v[202:205], v[4:7]
	v_mfma_f32_16x16x32_bf16 v[0:3], v[218:221], v[202:205], v[0:3]
	v_mfma_f32_16x16x32_bf16 v[28:31], v[214:217], v[182:185], v[28:31]
	v_mfma_f32_16x16x32_bf16 v[24:27], v[222:225], v[182:185], v[24:27]
	v_mfma_f32_16x16x32_bf16 v[20:23], v[214:217], v[190:193], v[20:23]
	v_mfma_f32_16x16x32_bf16 v[16:19], v[222:225], v[190:193], v[16:19]
	v_mfma_f32_16x16x32_bf16 v[12:15], v[214:217], v[198:201], v[12:15]
	v_mfma_f32_16x16x32_bf16 v[8:11], v[222:225], v[198:201], v[8:11]
	v_mfma_f32_16x16x32_bf16 v[4:7], v[214:217], v[206:209], v[4:7]
	v_mfma_f32_16x16x32_bf16 v[0:3], v[222:225], v[206:209], v[0:3]
	s_add_i32 s28, s28, 2
	s_add_u32 s14, s14, 0x100
	s_addc_u32 s15, s15, 0
	s_cmp_lt_u32 s28, 60
	s_barrier
	s_cbranch_scc1 .LBB0_654
	s_mov_b64 s[14:15], 0x101f80
	s_mov_b32 m0, s29
	ds_read_b128 v[138:141], v145
	ds_read_b128 v[166:169], v146
	ds_read_b128 v[170:173], v147
	ds_read_b128 v[174:177], v148
	ds_read_b128 v[178:181], v164
	ds_read_b128 v[182:185], v164 offset:1024
	ds_read_b128 v[186:189], v164 offset:2048
	ds_read_b128 v[190:193], v164 offset:3072
	ds_read_b128 v[194:197], v164 offset:4096
	ds_read_b128 v[198:201], v164 offset:5120
	ds_read_b128 v[202:205], v164 offset:6144
	ds_read_b128 v[206:209], v164 offset:7168
	s_nop 0
	v_lshl_add_u64 v[136:137], v[136:137], 0, s[14:15]
	global_load_lds_dwordx4 v[136:137], off
	v_lshl_add_u64 v[136:137], v[136:137], 0, s[10:11]
	s_mov_b32 m0, s21
	s_nop 0
	global_load_lds_dwordx4 v[136:137], off
	s_barrier
	s_waitcnt lgkmcnt(0)
	s_waitcnt lgkmcnt(0)
	v_mfma_f32_16x16x32_bf16 v[124:127], v[138:141], v[178:181], v[124:127]
	v_mfma_f32_16x16x32_bf16 v[116:119], v[138:141], v[186:189], v[116:119]
	v_mfma_f32_16x16x32_bf16 v[112:115], v[170:173], v[186:189], v[112:115]
	v_mfma_f32_16x16x32_bf16 v[100:103], v[138:141], v[202:205], v[100:103]
	v_mfma_f32_16x16x32_bf16 v[96:99], v[170:173], v[202:205], v[96:99]
	v_mfma_f32_16x16x32_bf16 v[124:127], v[166:169], v[182:185], v[124:127]
	v_mfma_f32_16x16x32_bf16 v[120:123], v[170:173], v[178:181], v[120:123]
	v_mfma_f32_16x16x32_bf16 v[116:119], v[166:169], v[190:193], v[116:119]
	v_mfma_f32_16x16x32_bf16 v[112:115], v[174:177], v[190:193], v[112:115]
	v_mfma_f32_16x16x32_bf16 v[108:111], v[138:141], v[194:197], v[108:111]
	v_mfma_f32_16x16x32_bf16 v[104:107], v[170:173], v[194:197], v[104:107]
	v_mfma_f32_16x16x32_bf16 v[100:103], v[166:169], v[206:209], v[100:103]
	v_mfma_f32_16x16x32_bf16 v[96:99], v[174:177], v[206:209], v[96:99]
	v_mfma_f32_16x16x32_bf16 v[210:213], v[174:177], v[182:185], v[120:123]
	v_mfma_f32_16x16x32_bf16 v[214:217], v[166:169], v[198:201], v[108:111]
	v_mfma_f32_16x16x32_bf16 v[218:221], v[174:177], v[198:201], v[104:107]
	s_barrier
	s_nop 0
	ds_read_b128 v[104:107], v149
	ds_read_b128 v[108:111], v150
	ds_read_b128 v[120:123], v151
	ds_read_b128 v[222:225], v152
	s_barrier
	s_waitcnt lgkmcnt(0)
	s_waitcnt lgkmcnt(0)
	v_mfma_f32_16x16x32_bf16 v[84:87], v[104:107], v[186:189], v[84:87]
	v_mfma_f32_16x16x32_bf16 v[80:83], v[120:123], v[186:189], v[80:83]
	v_mfma_f32_16x16x32_bf16 v[68:71], v[104:107], v[202:205], v[68:71]
	v_mfma_f32_16x16x32_bf16 v[92:95], v[104:107], v[178:181], v[92:95]
	v_mfma_f32_16x16x32_bf16 v[88:91], v[120:123], v[178:181], v[88:91]
	v_mfma_f32_16x16x32_bf16 v[84:87], v[108:111], v[190:193], v[84:87]
	v_mfma_f32_16x16x32_bf16 v[80:83], v[222:225], v[190:193], v[80:83]
	v_mfma_f32_16x16x32_bf16 v[76:79], v[104:107], v[194:197], v[76:79]
	v_mfma_f32_16x16x32_bf16 v[72:75], v[120:123], v[194:197], v[72:75]
	v_mfma_f32_16x16x32_bf16 v[68:71], v[108:111], v[206:209], v[68:71]
	v_mfma_f32_16x16x32_bf16 v[64:67], v[120:123], v[202:205], v[64:67]
	v_mfma_f32_16x16x32_bf16 v[226:229], v[108:111], v[182:185], v[92:95]
	v_mfma_f32_16x16x32_bf16 v[178:181], v[222:225], v[182:185], v[88:91]
	v_mfma_f32_16x16x32_bf16 v[182:185], v[108:111], v[198:201], v[76:79]
	v_mfma_f32_16x16x32_bf16 v[186:189], v[222:225], v[198:201], v[72:75]
	v_mfma_f32_16x16x32_bf16 v[190:193], v[222:225], v[206:209], v[64:67]
	s_barrier
; #define LDA(dst, b, h) for (int m = 0; m < 4; ++m) for (int k = 0; k < 2; ++k) \
;     dst[m][k] = *reinterpret_cast<const bf16x8*>(aRd + (((b) * 2 + (h)) * G_HT * 2 + m * 2048 + k * 1024))
; #define LDB(dst, b, h) for (int n = 0; n < 2; ++n) for (int k = 0; k < 2; ++k) \
;     dst[n][k] = *reinterpret_cast<const bf16x8*>(bRd + (((b) * 2 + (h)) * G_HT * 2 + n * 2048 + k * 1024))
; #define MMA(ai, bj, At, Bx) do { __builtin_amdgcn_s_setprio(1); \
;     for (int m = 0; m < 4; ++m) for (int n = 0; n < 2; ++n) for (int k = 0; k < 2; ++k) \
;       acc[ai][bj][m][n] = __builtin_amdgcn_mfma_f32_16x16x32_bf16(Bx[n][k], At[m][k], acc[ai][bj][m][n], 0, 0, 0);     \
;     __builtin_amdgcn_s_setprio(0); } while (0)
; #define WAIT_V(n) asm volatile("s_waitcnt vmcnt(" #n ")" ::: "memory")
; #define WAIT_L(n) asm volatile("s_waitcnt lgkmcnt(" #n ")" ::: "memory")
; #define BAR __builtin_amdgcn_s_barrier()
; template <int EPI>
; __device__ __forceinline__ void gemm_tile(const bf16* __restrict__ A, int lda, const bf16* __restrict__ Bt, int K,
;                                           int brow, int bcol, const EpiArgs& ea, char* shmc, bool has_next, int nbrow, int nbcol, bool first_tile) {
;     ...
;     LDA(At, 0, 1); WAIT_V(4); BAR; WAIT_L(0); MMA(1, 0, At, B0); MMA(1, 1, At, B1); BAR; }
;   { LDB(B0, 1, 0); LDA(At, 1, 0); WAIT_V(2); BAR; WAIT_L(0); MMA(0, 0, At, B0); BAR;
	s_nop 0
	ds_read_b128 v[64:67], v164 offset:16384
	ds_read_b128 v[72:75], v164 offset:17408
	ds_read_b128 v[76:79], v164 offset:18432
	ds_read_b128 v[88:91], v164 offset:19456
	ds_read_b128 v[92:95], v164 offset:20480
	ds_read_b128 v[194:197], v164 offset:21504
	ds_read_b128 v[198:201], v164 offset:22528
	ds_read_b128 v[202:205], v164 offset:23552
	s_waitcnt vmcnt(4)
	s_barrier
	s_waitcnt lgkmcnt(0)
	s_waitcnt lgkmcnt(0)
	v_mfma_f32_16x16x32_bf16 v[60:63], v[138:141], v[64:67], v[60:63]
	v_mfma_f32_16x16x32_bf16 v[52:55], v[138:141], v[76:79], v[52:55]
	v_mfma_f32_16x16x32_bf16 v[48:51], v[170:173], v[76:79], v[48:51]
	v_mfma_f32_16x16x32_bf16 v[36:39], v[138:141], v[198:201], v[36:39]
	v_mfma_f32_16x16x32_bf16 v[32:35], v[170:173], v[198:201], v[32:35]
	v_mfma_f32_16x16x32_bf16 v[60:63], v[166:169], v[72:75], v[60:63]
	v_mfma_f32_16x16x32_bf16 v[56:59], v[170:173], v[64:67], v[56:59]
	v_mfma_f32_16x16x32_bf16 v[52:55], v[166:169], v[88:91], v[52:55]
	v_mfma_f32_16x16x32_bf16 v[48:51], v[174:177], v[88:91], v[48:51]
	v_mfma_f32_16x16x32_bf16 v[44:47], v[138:141], v[92:95], v[44:47]
	v_mfma_f32_16x16x32_bf16 v[40:43], v[170:173], v[92:95], v[40:43]
	v_mfma_f32_16x16x32_bf16 v[36:39], v[166:169], v[202:205], v[36:39]
	v_mfma_f32_16x16x32_bf16 v[32:35], v[174:177], v[202:205], v[32:35]
	v_mfma_f32_16x16x32_bf16 v[206:209], v[174:177], v[72:75], v[56:59]
	v_mfma_f32_16x16x32_bf16 v[230:233], v[166:169], v[194:197], v[44:47]
	v_mfma_f32_16x16x32_bf16 v[234:237], v[174:177], v[194:197], v[40:43]
	v_mfma_f32_16x16x32_bf16 v[20:23], v[104:107], v[76:79], v[20:23]
	v_mfma_f32_16x16x32_bf16 v[16:19], v[120:123], v[76:79], v[16:19]
	v_mfma_f32_16x16x32_bf16 v[4:7], v[104:107], v[198:201], v[4:7]
	v_mfma_f32_16x16x32_bf16 v[28:31], v[104:107], v[64:67], v[28:31]
	v_mfma_f32_16x16x32_bf16 v[24:27], v[120:123], v[64:67], v[24:27]
	v_mfma_f32_16x16x32_bf16 v[20:23], v[108:111], v[88:91], v[20:23]
	v_mfma_f32_16x16x32_bf16 v[16:19], v[222:225], v[88:91], v[16:19]
	v_mfma_f32_16x16x32_bf16 v[12:15], v[104:107], v[92:95], v[12:15]
	v_mfma_f32_16x16x32_bf16 v[8:11], v[120:123], v[92:95], v[8:11]
	v_mfma_f32_16x16x32_bf16 v[4:7], v[108:111], v[202:205], v[4:7]
	v_mfma_f32_16x16x32_bf16 v[0:3], v[120:123], v[198:201], v[0:3]
	v_mfma_f32_16x16x32_bf16 v[136:139], v[108:111], v[72:75], v[28:31]
	v_mfma_f32_16x16x32_bf16 v[140:143], v[222:225], v[72:75], v[24:27]
	v_mfma_f32_16x16x32_bf16 v[166:169], v[108:111], v[194:197], v[12:15]
	v_mfma_f32_16x16x32_bf16 v[170:173], v[222:225], v[194:197], v[8:11]
	v_mfma_f32_16x16x32_bf16 v[174:177], v[222:225], v[202:205], v[0:3]
	s_barrier
	s_nop 0
	ds_read_b128 v[0:3], v153
	ds_read_b128 v[8:11], v154
	ds_read_b128 v[12:15], v155
	ds_read_b128 v[194:197], v156
	ds_read_b128 v[24:27], v164 offset:32768
	ds_read_b128 v[28:31], v164 offset:33792
	ds_read_b128 v[40:43], v164 offset:34816
	ds_read_b128 v[44:47], v164 offset:35840
	ds_read_b128 v[56:59], v164 offset:36864
	ds_read_b128 v[64:67], v164 offset:37888
	ds_read_b128 v[198:201], v164 offset:38912
	ds_read_b128 v[202:205], v164 offset:39936
	s_waitcnt vmcnt(2)
	s_barrier
	s_waitcnt lgkmcnt(0)
	s_waitcnt lgkmcnt(0)
	v_mfma_f32_16x16x32_bf16 v[72:75], v[0:3], v[24:27], v[124:127]
	v_mfma_f32_16x16x32_bf16 v[120:123], v[8:11], v[28:31], v[72:75]
	v_mfma_f32_16x16x32_bf16 v[72:75], v[12:15], v[24:27], v[210:213]
	v_mfma_f32_16x16x32_bf16 v[124:127], v[194:197], v[28:31], v[72:75]
	v_mfma_f32_16x16x32_bf16 v[72:75], v[0:3], v[40:43], v[116:119]
	v_mfma_f32_16x16x32_bf16 v[104:107], v[8:11], v[44:47], v[72:75]
	v_mfma_f32_16x16x32_bf16 v[72:75], v[12:15], v[40:43], v[112:115]
	v_mfma_f32_16x16x32_bf16 v[108:111], v[194:197], v[44:47], v[72:75]
	v_mfma_f32_16x16x32_bf16 v[72:75], v[0:3], v[56:59], v[214:217]
	v_mfma_f32_16x16x32_bf16 v[88:91], v[8:11], v[64:67], v[72:75]
	v_mfma_f32_16x16x32_bf16 v[72:75], v[12:15], v[56:59], v[218:221]
	v_mfma_f32_16x16x32_bf16 v[92:95], v[194:197], v[64:67], v[72:75]
	v_mfma_f32_16x16x32_bf16 v[72:75], v[0:3], v[198:201], v[100:103]
	v_mfma_f32_16x16x32_bf16 v[76:79], v[12:15], v[198:201], v[96:99]
	v_mfma_f32_16x16x32_bf16 v[72:75], v[8:11], v[202:205], v[72:75]
	v_mfma_f32_16x16x32_bf16 v[76:79], v[194:197], v[202:205], v[76:79]
	s_barrier
; #define LDA(dst, b, h) for (int m = 0; m < 4; ++m) for (int k = 0; k < 2; ++k) \
;     dst[m][k] = *reinterpret_cast<const bf16x8*>(aRd + (((b) * 2 + (h)) * G_HT * 2 + m * 2048 + k * 1024))
; #define LDB(dst, b, h) for (int n = 0; n < 2; ++n) for (int k = 0; k < 2; ++k) \
;     dst[n][k] = *reinterpret_cast<const bf16x8*>(bRd + (((b) * 2 + (h)) * G_HT * 2 + n * 2048 + k * 1024))
; #define MMA(ai, bj, At, Bx) do { __builtin_amdgcn_s_setprio(1); \
;     for (int m = 0; m < 4; ++m) for (int n = 0; n < 2; ++n) for (int k = 0; k < 2; ++k) \
;       acc[ai][bj][m][n] = __builtin_amdgcn_mfma_f32_16x16x32_bf16(Bx[n][k], At[m][k], acc[ai][bj][m][n], 0, 0, 0);     \
;     __builtin_amdgcn_s_setprio(0); } while (0)
; #define WAIT_V(n) asm volatile("s_waitcnt vmcnt(" #n ")" ::: "memory")
; #define WAIT_L(n) asm volatile("s_waitcnt lgkmcnt(" #n ")" ::: "memory")
; #define BAR __builtin_amdgcn_s_barrier()
; template <int EPI>
; __device__ __forceinline__ void gemm_tile(const bf16* __restrict__ A, int lda, const bf16* __restrict__ Bt, int K,
;                                           int brow, int bcol, const EpiArgs& ea, char* shmc, bool has_next, int nbrow, int nbcol, bool first_tile) {
;     ...
;     LDB(B1, 1, 1); WAIT_V(0); BAR; WAIT_L(0); MMA(0, 1, At, B1); BAR;
;     LDA(At, 1, 1); BAR; WAIT_L(0); MMA(1, 0, At, B0); MMA(1, 1, At, B1); BAR; }
;   if (wr == 0) BAR;
	ds_read_b128 v[210:213], v158
	ds_read_b128 v[214:217], v159
	ds_read_b128 v[218:221], v160
	ds_read_b128 v[222:225], v161
	s_waitcnt vmcnt(0)
	s_barrier
	s_waitcnt lgkmcnt(0)
	s_waitcnt lgkmcnt(0)
	v_mfma_f32_16x16x32_bf16 v[96:99], v[210:213], v[24:27], v[226:229]
	v_mfma_f32_16x16x32_bf16 v[24:27], v[218:221], v[24:27], v[178:181]
	v_mfma_f32_16x16x32_bf16 v[116:119], v[222:225], v[28:31], v[24:27]
	v_mfma_f32_16x16x32_bf16 v[24:27], v[210:213], v[40:43], v[84:87]
	v_mfma_f32_16x16x32_bf16 v[112:115], v[214:217], v[28:31], v[96:99]
	v_mfma_f32_16x16x32_bf16 v[96:99], v[214:217], v[44:47], v[24:27]
	v_mfma_f32_16x16x32_bf16 v[24:27], v[218:221], v[40:43], v[80:83]
	v_mfma_f32_16x16x32_bf16 v[100:103], v[222:225], v[44:47], v[24:27]
	v_mfma_f32_16x16x32_bf16 v[24:27], v[210:213], v[56:59], v[182:185]
	v_mfma_f32_16x16x32_bf16 v[80:83], v[214:217], v[64:67], v[24:27]
	v_mfma_f32_16x16x32_bf16 v[24:27], v[218:221], v[56:59], v[186:189]
	v_mfma_f32_16x16x32_bf16 v[84:87], v[222:225], v[64:67], v[24:27]
	v_mfma_f32_16x16x32_bf16 v[24:27], v[210:213], v[198:201], v[68:71]
	v_mfma_f32_16x16x32_bf16 v[64:67], v[214:217], v[202:205], v[24:27]
	v_mfma_f32_16x16x32_bf16 v[24:27], v[218:221], v[198:201], v[190:193]
	v_mfma_f32_16x16x32_bf16 v[68:71], v[222:225], v[202:205], v[24:27]
	s_barrier
	ds_read_b128 v[178:181], v164 offset:49152
	ds_read_b128 v[182:185], v164 offset:50176
	ds_read_b128 v[186:189], v164 offset:51200
	ds_read_b128 v[190:193], v164 offset:52224
	ds_read_b128 v[198:201], v164 offset:53248
	ds_read_b128 v[202:205], v164 offset:54272
	ds_read_b128 v[226:229], v164 offset:55296
	ds_read_b128 v[238:241], v164 offset:56320
	s_barrier
	s_waitcnt lgkmcnt(0)
	s_waitcnt lgkmcnt(0)
	v_mfma_f32_16x16x32_bf16 v[24:27], v[0:3], v[178:181], v[60:63]
	v_mfma_f32_16x16x32_bf16 v[56:59], v[8:11], v[182:185], v[24:27]
	v_mfma_f32_16x16x32_bf16 v[24:27], v[12:15], v[178:181], v[206:209]
	v_mfma_f32_16x16x32_bf16 v[60:63], v[194:197], v[182:185], v[24:27]
	v_mfma_f32_16x16x32_bf16 v[24:27], v[0:3], v[186:189], v[52:55]
	v_mfma_f32_16x16x32_bf16 v[40:43], v[8:11], v[190:193], v[24:27]
	v_mfma_f32_16x16x32_bf16 v[24:27], v[12:15], v[186:189], v[48:51]
	v_mfma_f32_16x16x32_bf16 v[44:47], v[194:197], v[190:193], v[24:27]
	v_mfma_f32_16x16x32_bf16 v[24:27], v[0:3], v[198:201], v[230:233]
	v_mfma_f32_16x16x32_bf16 v[0:3], v[0:3], v[226:229], v[36:39]
	v_mfma_f32_16x16x32_bf16 v[24:27], v[8:11], v[202:205], v[24:27]
	v_mfma_f32_16x16x32_bf16 v[28:31], v[12:15], v[198:201], v[234:237]
	v_mfma_f32_16x16x32_bf16 v[8:11], v[8:11], v[238:241], v[0:3]
	v_mfma_f32_16x16x32_bf16 v[0:3], v[12:15], v[226:229], v[32:35]
	v_mfma_f32_16x16x32_bf16 v[28:31], v[194:197], v[202:205], v[28:31]
	v_mfma_f32_16x16x32_bf16 v[12:15], v[194:197], v[238:241], v[0:3]
	v_mfma_f32_16x16x32_bf16 v[0:3], v[210:213], v[178:181], v[136:139]
	v_mfma_f32_16x16x32_bf16 v[48:51], v[214:217], v[182:185], v[0:3]
	v_mfma_f32_16x16x32_bf16 v[0:3], v[218:221], v[178:181], v[140:143]
	v_mfma_f32_16x16x32_bf16 v[52:55], v[222:225], v[182:185], v[0:3]
	v_mfma_f32_16x16x32_bf16 v[0:3], v[210:213], v[186:189], v[20:23]
	v_mfma_f32_16x16x32_bf16 v[32:35], v[214:217], v[190:193], v[0:3]
	v_mfma_f32_16x16x32_bf16 v[0:3], v[218:221], v[186:189], v[16:19]
	v_mfma_f32_16x16x32_bf16 v[36:39], v[222:225], v[190:193], v[0:3]
	v_mfma_f32_16x16x32_bf16 v[0:3], v[210:213], v[198:201], v[166:169]
	v_mfma_f32_16x16x32_bf16 v[16:19], v[214:217], v[202:205], v[0:3]
	v_mfma_f32_16x16x32_bf16 v[0:3], v[218:221], v[198:201], v[170:173]
	v_mfma_f32_16x16x32_bf16 v[20:23], v[222:225], v[202:205], v[0:3]
	v_mfma_f32_16x16x32_bf16 v[0:3], v[210:213], v[226:229], v[4:7]
	v_mfma_f32_16x16x32_bf16 v[4:7], v[218:221], v[226:229], v[174:177]
	v_mfma_f32_16x16x32_bf16 v[0:3], v[214:217], v[238:241], v[0:3]
	v_mfma_f32_16x16x32_bf16 v[4:7], v[222:225], v[238:241], v[4:7]
	s_barrier
	s_and_saveexec_b64 s[14:15], s[4:5]
	s_cbranch_execz .LBB0_657
	s_barrier

; #define STA(b, h, half, kt) STAGE(((b) * 2 + (h)) * G_HT * 2, pA, ((size_t)(half) * G_HALF * lda + (size_t)(kt) * G_BK) * 2, lda)
; #define STB(b, h, half, kt) STAGE((4 + (b) * 2 + (h)) * G_HT * 2, pB, ((size_t)(half) * G_HALF * K + (size_t)(kt) * G_BK) * 2, K)
; #define LDA(dst, b, h) for (int m = 0; m < 4; ++m) for (int k = 0; k < 2; ++k) \
;     dst[m][k] = *reinterpret_cast<const bf16x8*>(aRd + (((b) * 2 + (h)) * G_HT * 2 + m * 2048 + k * 1024))
; #define LDB(dst, b, h) for (int n = 0; n < 2; ++n) for (int k = 0; k < 2; ++k) \
;     dst[n][k] = *reinterpret_cast<const bf16x8*>(bRd + (((b) * 2 + (h)) * G_HT * 2 + n * 2048 + k * 1024))
; #define MMA(ai, bj, At, Bx) do { __builtin_amdgcn_s_setprio(1); \
;     for (int m = 0; m < 4; ++m) for (int n = 0; n < 2; ++n) for (int k = 0; k < 2; ++k) \
;       acc[ai][bj][m][n] = __builtin_amdgcn_mfma_f32_16x16x32_bf16(Bx[n][k], At[m][k], acc[ai][bj][m][n], 0, 0, 0);     \
;     __builtin_amdgcn_s_setprio(0); } while (0)
; #define WAIT_V(n) asm volatile("s_waitcnt vmcnt(" #n ")" ::: "memory")
; #define WAIT_L(n) asm volatile("s_waitcnt lgkmcnt(" #n ")" ::: "memory")
; #define BAR __builtin_amdgcn_s_barrier()
; #define SCHED __builtin_amdgcn_sched_barrier(0)
; template <int EPI>
; __device__ __forceinline__ void gemm_tile(const bf16* __restrict__ A, int lda, const bf16* __restrict__ Bt, int K,
;                                           int brow, int bcol, const EpiArgs& ea, char* shmc, bool has_next, int nbrow, int nbcol, bool first_tile) {
;     ...
;     LDB(B0, 0, 0); SCHED; LDA(At, 0, 0); STA(1, 1, 1, t + 1);
;     WAIT_L(8); BAR; WAIT_L(0); MMA(0, 0, At, B0); BAR; SCHED;
;     LDB(B1, 0, 1); STB(0, 0, 0, t + 2);
;     BAR; WAIT_L(0); MMA(0, 1, At, B1); BAR;
;     LDA(At, 0, 1); STA(0, 0, 0, t + 2);
;     BAR; WAIT_L(0); MMA(1, 0, At, B0); BAR; SCHED;
;     STB(0, 1, 1, t + 2);
;     WAIT_V(6); BAR; MMA(1, 1, At, B1); BAR;
.LBB0_727:
	ds_read_b128 v[136:139], v141
	ds_read_b128 v[162:165], v142
	ds_read_b128 v[166:169], v143
	ds_read_b128 v[170:173], v144
	s_add_u32 s52, s20, 0xffffff00
	s_addc_u32 s53, s21, -1
	s_mov_b32 m0, s50
	ds_read_b128 v[174:177], v160
	ds_read_b128 v[178:181], v160 offset:1024
	ds_read_b128 v[182:185], v160 offset:2048
	ds_read_b128 v[186:189], v160 offset:3072
	ds_read_b128 v[190:193], v160 offset:4096
	ds_read_b128 v[194:197], v160 offset:5120
	ds_read_b128 v[198:201], v160 offset:6144
	ds_read_b128 v[202:205], v160 offset:7168
	v_lshl_add_u64 v[206:207], v[132:133], 0, s[52:53]
	global_load_lds_dwordx4 v[206:207], off
	v_lshl_add_u64 v[206:207], v[206:207], 0, s[10:11]
	s_mov_b32 m0, s34
	s_nop 0
	global_load_lds_dwordx4 v[206:207], off
	s_waitcnt lgkmcnt(8)
	s_barrier
	s_waitcnt lgkmcnt(0)
	v_mfma_f32_16x16x32_bf16 v[124:127], v[136:139], v[174:177], v[124:127]
	v_mfma_f32_16x16x32_bf16 v[120:123], v[166:169], v[174:177], v[120:123]
	v_mfma_f32_16x16x32_bf16 v[116:119], v[136:139], v[182:185], v[116:119]
	v_mfma_f32_16x16x32_bf16 v[112:115], v[166:169], v[182:185], v[112:115]
	v_mfma_f32_16x16x32_bf16 v[108:111], v[136:139], v[190:193], v[108:111]
	v_mfma_f32_16x16x32_bf16 v[104:107], v[166:169], v[190:193], v[104:107]
	v_mfma_f32_16x16x32_bf16 v[100:103], v[136:139], v[198:201], v[100:103]
	v_mfma_f32_16x16x32_bf16 v[96:99], v[166:169], v[198:201], v[96:99]
	v_mfma_f32_16x16x32_bf16 v[124:127], v[162:165], v[178:181], v[124:127]
	v_mfma_f32_16x16x32_bf16 v[120:123], v[170:173], v[178:181], v[120:123]
	v_mfma_f32_16x16x32_bf16 v[116:119], v[162:165], v[186:189], v[116:119]
	v_mfma_f32_16x16x32_bf16 v[112:115], v[170:173], v[186:189], v[112:115]
	v_mfma_f32_16x16x32_bf16 v[108:111], v[162:165], v[194:197], v[108:111]
	v_mfma_f32_16x16x32_bf16 v[104:107], v[170:173], v[194:197], v[104:107]
	v_mfma_f32_16x16x32_bf16 v[100:103], v[162:165], v[202:205], v[100:103]
	v_mfma_f32_16x16x32_bf16 v[96:99], v[170:173], v[202:205], v[96:99]
	s_barrier
	s_add_u32 s52, s20, 0xffefff80
	s_addc_u32 s53, s21, -1
	s_mov_b64 s[54:55], s[52:53]
	s_mov_b32 m0, s41
	ds_read_b128 v[206:209], v145
	ds_read_b128 v[210:213], v146
	ds_read_b128 v[214:217], v147
	ds_read_b128 v[218:221], v148
	v_lshl_add_u64 v[222:223], v[134:135], 0, s[54:55]
	global_load_lds_dwordx4 v[222:223], off
	v_lshl_add_u64 v[222:223], v[222:223], 0, s[10:11]
	s_mov_b32 m0, s42
	s_nop 0
	global_load_lds_dwordx4 v[222:223], off
	s_barrier
	s_waitcnt lgkmcnt(0)
	v_mfma_f32_16x16x32_bf16 v[92:95], v[206:209], v[174:177], v[92:95]
	v_mfma_f32_16x16x32_bf16 v[88:91], v[214:217], v[174:177], v[88:91]
	v_mfma_f32_16x16x32_bf16 v[84:87], v[206:209], v[182:185], v[84:87]
	v_mfma_f32_16x16x32_bf16 v[80:83], v[214:217], v[182:185], v[80:83]
	v_mfma_f32_16x16x32_bf16 v[76:79], v[206:209], v[190:193], v[76:79]
	v_mfma_f32_16x16x32_bf16 v[72:75], v[214:217], v[190:193], v[72:75]
	v_mfma_f32_16x16x32_bf16 v[68:71], v[206:209], v[198:201], v[68:71]
	v_mfma_f32_16x16x32_bf16 v[64:67], v[214:217], v[198:201], v[64:67]
	v_mfma_f32_16x16x32_bf16 v[92:95], v[210:213], v[178:181], v[92:95]
	v_mfma_f32_16x16x32_bf16 v[88:91], v[218:221], v[178:181], v[88:91]
	v_mfma_f32_16x16x32_bf16 v[84:87], v[210:213], v[186:189], v[84:87]
	v_mfma_f32_16x16x32_bf16 v[80:83], v[218:221], v[186:189], v[80:83]
	v_mfma_f32_16x16x32_bf16 v[76:79], v[210:213], v[194:197], v[76:79]
	v_mfma_f32_16x16x32_bf16 v[72:75], v[218:221], v[194:197], v[72:75]
	v_mfma_f32_16x16x32_bf16 v[68:71], v[210:213], v[202:205], v[68:71]
	v_mfma_f32_16x16x32_bf16 v[64:67], v[218:221], v[202:205], v[64:67]
	s_mov_b32 m0, s1
	s_barrier
	ds_read_b128 v[174:177], v160 offset:16384
	ds_read_b128 v[178:181], v160 offset:17408
	ds_read_b128 v[182:185], v160 offset:18432
	ds_read_b128 v[186:189], v160 offset:19456
	ds_read_b128 v[190:193], v160 offset:20480
	ds_read_b128 v[194:197], v160 offset:21504
	ds_read_b128 v[198:201], v160 offset:22528
	ds_read_b128 v[202:205], v160 offset:23552
	v_lshl_add_u64 v[222:223], v[132:133], 0, s[52:53]
	global_load_lds_dwordx4 v[222:223], off
	v_lshl_add_u64 v[222:223], v[222:223], 0, s[10:11]
	s_add_i32 m0, s1, 0x2000
	s_nop 0
	global_load_lds_dwordx4 v[222:223], off
	s_barrier
	s_waitcnt lgkmcnt(0)
	v_mfma_f32_16x16x32_bf16 v[60:63], v[136:139], v[174:177], v[60:63]
	v_mfma_f32_16x16x32_bf16 v[56:59], v[166:169], v[174:177], v[56:59]
	v_mfma_f32_16x16x32_bf16 v[52:55], v[136:139], v[182:185], v[52:55]
	v_mfma_f32_16x16x32_bf16 v[48:51], v[166:169], v[182:185], v[48:51]
	v_mfma_f32_16x16x32_bf16 v[44:47], v[136:139], v[190:193], v[44:47]
	v_mfma_f32_16x16x32_bf16 v[40:43], v[166:169], v[190:193], v[40:43]
	v_mfma_f32_16x16x32_bf16 v[36:39], v[136:139], v[198:201], v[36:39]
	v_mfma_f32_16x16x32_bf16 v[32:35], v[166:169], v[198:201], v[32:35]
	v_mfma_f32_16x16x32_bf16 v[60:63], v[162:165], v[178:181], v[60:63]
	v_mfma_f32_16x16x32_bf16 v[56:59], v[170:173], v[178:181], v[56:59]
	v_mfma_f32_16x16x32_bf16 v[52:55], v[162:165], v[186:189], v[52:55]
	v_mfma_f32_16x16x32_bf16 v[48:51], v[170:173], v[186:189], v[48:51]
	v_mfma_f32_16x16x32_bf16 v[44:47], v[162:165], v[194:197], v[44:47]
	v_mfma_f32_16x16x32_bf16 v[40:43], v[170:173], v[194:197], v[40:43]
	v_mfma_f32_16x16x32_bf16 v[36:39], v[162:165], v[202:205], v[36:39]
	v_mfma_f32_16x16x32_bf16 v[32:35], v[170:173], v[202:205], v[32:35]
	s_barrier
	s_add_u32 s52, s20, 0xffffff80
	s_addc_u32 s53, s21, -1
	s_mov_b64 s[54:55], s[52:53]
	s_mov_b32 m0, s43
	v_lshl_add_u64 v[136:137], v[134:135], 0, s[54:55]
	global_load_lds_dwordx4 v[136:137], off
	v_lshl_add_u64 v[136:137], v[136:137], 0, s[10:11]
	s_mov_b32 m0, s48
	s_nop 0
	global_load_lds_dwordx4 v[136:137], off
	s_waitcnt vmcnt(6)
	s_barrier
; #define STA(b, h, half, kt) STAGE(((b) * 2 + (h)) * G_HT * 2, pA, ((size_t)(half) * G_HALF * lda + (size_t)(kt) * G_BK) * 2, lda)
; #define STB(b, h, half, kt) STAGE((4 + (b) * 2 + (h)) * G_HT * 2, pB, ((size_t)(half) * G_HALF * K + (size_t)(kt) * G_BK) * 2, K)
; #define LDA(dst, b, h) for (int m = 0; m < 4; ++m) for (int k = 0; k < 2; ++k) \
;     dst[m][k] = *reinterpret_cast<const bf16x8*>(aRd + (((b) * 2 + (h)) * G_HT * 2 + m * 2048 + k * 1024))
; #define LDB(dst, b, h) for (int n = 0; n < 2; ++n) for (int k = 0; k < 2; ++k) \
;     dst[n][k] = *reinterpret_cast<const bf16x8*>(bRd + (((b) * 2 + (h)) * G_HT * 2 + n * 2048 + k * 1024))
; #define MMA(ai, bj, At, Bx) do { __builtin_amdgcn_s_setprio(1); \
;     for (int m = 0; m < 4; ++m) for (int n = 0; n < 2; ++n) for (int k = 0; k < 2; ++k) \
;       acc[ai][bj][m][n] = __builtin_amdgcn_mfma_f32_16x16x32_bf16(Bx[n][k], At[m][k], acc[ai][bj][m][n], 0, 0, 0);     \
;     __builtin_amdgcn_s_setprio(0); } while (0)
; #define WAIT_V(n) asm volatile("s_waitcnt vmcnt(" #n ")" ::: "memory")
; #define WAIT_L(n) asm volatile("s_waitcnt lgkmcnt(" #n ")" ::: "memory")
; #define BAR __builtin_amdgcn_s_barrier()
; #define SCHED __builtin_amdgcn_sched_barrier(0)
; template <int EPI>
; __device__ __forceinline__ void gemm_tile(const bf16* __restrict__ A, int lda, const bf16* __restrict__ Bt, int K,
;                                           int brow, int bcol, const EpiArgs& ea, char* shmc, bool has_next, int nbrow, int nbcol, bool first_tile) {
;     ...
;     WAIT_V(6); BAR; MMA(1, 1, At, B1); BAR;
;     LDB(B0, 1, 0); SCHED; LDA(At, 1, 0); STA(0, 1, 1, t + 2);
;     WAIT_L(8); BAR; WAIT_L(0); MMA(0, 0, At, B0); BAR; SCHED;
;     LDB(B1, 1, 1); STB(1, 0, 0, t + 3);
;     BAR; WAIT_L(0); MMA(0, 1, At, B1); BAR;
;     LDA(At, 1, 1); STA(1, 0, 0, t + 3);
	v_mfma_f32_16x16x32_bf16 v[28:31], v[206:209], v[174:177], v[28:31]
	v_mfma_f32_16x16x32_bf16 v[24:27], v[214:217], v[174:177], v[24:27]
	v_mfma_f32_16x16x32_bf16 v[20:23], v[206:209], v[182:185], v[20:23]
	v_mfma_f32_16x16x32_bf16 v[16:19], v[214:217], v[182:185], v[16:19]
	v_mfma_f32_16x16x32_bf16 v[12:15], v[206:209], v[190:193], v[12:15]
	v_mfma_f32_16x16x32_bf16 v[8:11], v[214:217], v[190:193], v[8:11]
	v_mfma_f32_16x16x32_bf16 v[4:7], v[206:209], v[198:201], v[4:7]
	v_mfma_f32_16x16x32_bf16 v[0:3], v[214:217], v[198:201], v[0:3]
	v_mfma_f32_16x16x32_bf16 v[28:31], v[210:213], v[178:181], v[28:31]
	v_mfma_f32_16x16x32_bf16 v[24:27], v[218:221], v[178:181], v[24:27]
	v_mfma_f32_16x16x32_bf16 v[20:23], v[210:213], v[186:189], v[20:23]
	v_mfma_f32_16x16x32_bf16 v[16:19], v[218:221], v[186:189], v[16:19]
	v_mfma_f32_16x16x32_bf16 v[12:15], v[210:213], v[194:197], v[12:15]
	v_mfma_f32_16x16x32_bf16 v[8:11], v[218:221], v[194:197], v[8:11]
	v_mfma_f32_16x16x32_bf16 v[4:7], v[210:213], v[202:205], v[4:7]
	v_mfma_f32_16x16x32_bf16 v[0:3], v[218:221], v[202:205], v[0:3]
	s_barrier
	ds_read_b128 v[136:139], v149
	ds_read_b128 v[162:165], v150
	ds_read_b128 v[166:169], v151
	ds_read_b128 v[170:173], v152
	ds_read_b128 v[174:177], v160 offset:32768
	ds_read_b128 v[178:181], v160 offset:33792
	ds_read_b128 v[182:185], v160 offset:34816
	ds_read_b128 v[186:189], v160 offset:35840
	ds_read_b128 v[190:193], v160 offset:36864
	ds_read_b128 v[194:197], v160 offset:37888
	ds_read_b128 v[198:201], v160 offset:38912
	ds_read_b128 v[202:205], v160 offset:39936
	s_add_i32 m0, s1, 0x4000
	v_lshl_add_u64 v[206:207], v[132:133], 0, s[52:53]
	global_load_lds_dwordx4 v[206:207], off
	v_lshl_add_u64 v[206:207], v[206:207], 0, s[10:11]
	s_add_i32 m0, s1, 0x6000
	s_nop 0
	global_load_lds_dwordx4 v[206:207], off
	s_waitcnt lgkmcnt(8)
	s_barrier
	s_waitcnt lgkmcnt(0)
	v_mfma_f32_16x16x32_bf16 v[124:127], v[136:139], v[174:177], v[124:127]
	v_mfma_f32_16x16x32_bf16 v[120:123], v[166:169], v[174:177], v[120:123]
	v_mfma_f32_16x16x32_bf16 v[116:119], v[136:139], v[182:185], v[116:119]
	v_mfma_f32_16x16x32_bf16 v[112:115], v[166:169], v[182:185], v[112:115]
	v_mfma_f32_16x16x32_bf16 v[108:111], v[136:139], v[190:193], v[108:111]
	v_mfma_f32_16x16x32_bf16 v[104:107], v[166:169], v[190:193], v[104:107]
	v_mfma_f32_16x16x32_bf16 v[100:103], v[136:139], v[198:201], v[100:103]
	v_mfma_f32_16x16x32_bf16 v[96:99], v[166:169], v[198:201], v[96:99]
	v_mfma_f32_16x16x32_bf16 v[124:127], v[162:165], v[178:181], v[124:127]
	v_mfma_f32_16x16x32_bf16 v[120:123], v[170:173], v[178:181], v[120:123]
	v_mfma_f32_16x16x32_bf16 v[116:119], v[162:165], v[186:189], v[116:119]
	v_mfma_f32_16x16x32_bf16 v[112:115], v[170:173], v[186:189], v[112:115]
	v_mfma_f32_16x16x32_bf16 v[108:111], v[162:165], v[194:197], v[108:111]
	v_mfma_f32_16x16x32_bf16 v[104:107], v[170:173], v[194:197], v[104:107]
	v_mfma_f32_16x16x32_bf16 v[100:103], v[162:165], v[202:205], v[100:103]
	v_mfma_f32_16x16x32_bf16 v[96:99], v[170:173], v[202:205], v[96:99]
	s_barrier
	s_add_u32 s52, s20, 0xfff00000
	s_addc_u32 s53, s21, -1
	s_mov_b64 s[54:55], s[52:53]
	s_mov_b32 m0, s7
	ds_read_b128 v[206:209], v153
	ds_read_b128 v[210:213], v154
	ds_read_b128 v[214:217], v155
	ds_read_b128 v[218:221], v156
	v_lshl_add_u64 v[222:223], v[134:135], 0, s[54:55]
	global_load_lds_dwordx4 v[222:223], off
	v_lshl_add_u64 v[222:223], v[222:223], 0, s[10:11]
	s_mov_b32 m0, s29
	s_nop 0
	global_load_lds_dwordx4 v[222:223], off
	s_barrier
	s_waitcnt lgkmcnt(0)
	v_mfma_f32_16x16x32_bf16 v[92:95], v[206:209], v[174:177], v[92:95]
	v_mfma_f32_16x16x32_bf16 v[88:91], v[214:217], v[174:177], v[88:91]
	v_mfma_f32_16x16x32_bf16 v[84:87], v[206:209], v[182:185], v[84:87]
	v_mfma_f32_16x16x32_bf16 v[80:83], v[214:217], v[182:185], v[80:83]
	v_mfma_f32_16x16x32_bf16 v[76:79], v[206:209], v[190:193], v[76:79]
	v_mfma_f32_16x16x32_bf16 v[72:75], v[214:217], v[190:193], v[72:75]
	v_mfma_f32_16x16x32_bf16 v[68:71], v[206:209], v[198:201], v[68:71]
	v_mfma_f32_16x16x32_bf16 v[64:67], v[214:217], v[198:201], v[64:67]
	v_mfma_f32_16x16x32_bf16 v[92:95], v[210:213], v[178:181], v[92:95]
	v_mfma_f32_16x16x32_bf16 v[88:91], v[218:221], v[178:181], v[88:91]
	v_mfma_f32_16x16x32_bf16 v[84:87], v[210:213], v[186:189], v[84:87]
	v_mfma_f32_16x16x32_bf16 v[80:83], v[218:221], v[186:189], v[80:83]
	v_mfma_f32_16x16x32_bf16 v[76:79], v[210:213], v[194:197], v[76:79]
	v_mfma_f32_16x16x32_bf16 v[72:75], v[218:221], v[194:197], v[72:75]
	v_mfma_f32_16x16x32_bf16 v[68:71], v[210:213], v[202:205], v[68:71]
	v_mfma_f32_16x16x32_bf16 v[64:67], v[218:221], v[202:205], v[64:67]
	s_mov_b32 m0, s30
	s_barrier
	ds_read_b128 v[174:177], v160 offset:49152
	ds_read_b128 v[178:181], v160 offset:50176
	ds_read_b128 v[182:185], v160 offset:51200
	ds_read_b128 v[186:189], v160 offset:52224
	ds_read_b128 v[190:193], v160 offset:53248
	ds_read_b128 v[194:197], v160 offset:54272
	ds_read_b128 v[198:201], v160 offset:55296
	ds_read_b128 v[202:205], v160 offset:56320
	v_lshl_add_u64 v[222:223], v[132:133], 0, s[52:53]
	global_load_lds_dwordx4 v[222:223], off
	v_lshl_add_u64 v[222:223], v[222:223], 0, s[10:11]
	s_mov_b32 m0, s31
	s_nop 0
	global_load_lds_dwordx4 v[222:223], off
	s_barrier
; #define STA(b, h, half, kt) STAGE(((b) * 2 + (h)) * G_HT * 2, pA, ((size_t)(half) * G_HALF * lda + (size_t)(kt) * G_BK) * 2, lda)
; #define STB(b, h, half, kt) STAGE((4 + (b) * 2 + (h)) * G_HT * 2, pB, ((size_t)(half) * G_HALF * K + (size_t)(kt) * G_BK) * 2, K)
; #define LDA(dst, b, h) for (int m = 0; m < 4; ++m) for (int k = 0; k < 2; ++k) \
;     dst[m][k] = *reinterpret_cast<const bf16x8*>(aRd + (((b) * 2 + (h)) * G_HT * 2 + m * 2048 + k * 1024))
; #define LDB(dst, b, h) for (int n = 0; n < 2; ++n) for (int k = 0; k < 2; ++k) \
;     dst[n][k] = *reinterpret_cast<const bf16x8*>(bRd + (((b) * 2 + (h)) * G_HT * 2 + n * 2048 + k * 1024))
; #define MMA(ai, bj, At, Bx) do { __builtin_amdgcn_s_setprio(1); \
;     for (int m = 0; m < 4; ++m) for (int n = 0; n < 2; ++n) for (int k = 0; k < 2; ++k) \
;       acc[ai][bj][m][n] = __builtin_amdgcn_mfma_f32_16x16x32_bf16(Bx[n][k], At[m][k], acc[ai][bj][m][n], 0, 0, 0);     \
;     __builtin_amdgcn_s_setprio(0); } while (0)
; #define WAIT_V(n) asm volatile("s_waitcnt vmcnt(" #n ")" ::: "memory")
; #define WAIT_L(n) asm volatile("s_waitcnt lgkmcnt(" #n ")" ::: "memory")
; #define BAR __builtin_amdgcn_s_barrier()
; #define SCHED __builtin_amdgcn_sched_barrier(0)
; template <int EPI>
; __device__ __forceinline__ void gemm_tile(const bf16* __restrict__ A, int lda, const bf16* __restrict__ Bt, int K,
;                                           int brow, int bcol, const EpiArgs& ea, char* shmc, bool has_next, int nbrow, int nbcol, bool first_tile) {
;     ...
;     BAR; WAIT_L(0); MMA(1, 0, At, B0); BAR; SCHED;
;     STB(1, 1, 1, t + 3);
;     WAIT_V(6); BAR; MMA(1, 1, At, B1); BAR;
;   }
;   { LDB(B0, 0, 0); LDA(At, 0, 0); STA(1, 1, 1, nt - 1);
;     BAR; WAIT_L(0); MMA(0, 0, At, B0); BAR;
;     LDB(B1, 0, 1); BAR; WAIT_L(0); MMA(0, 1, At, B1); BAR;
	s_waitcnt lgkmcnt(0)
	v_mfma_f32_16x16x32_bf16 v[60:63], v[136:139], v[174:177], v[60:63]
	v_mfma_f32_16x16x32_bf16 v[56:59], v[166:169], v[174:177], v[56:59]
	v_mfma_f32_16x16x32_bf16 v[52:55], v[136:139], v[182:185], v[52:55]
	v_mfma_f32_16x16x32_bf16 v[48:51], v[166:169], v[182:185], v[48:51]
	v_mfma_f32_16x16x32_bf16 v[44:47], v[136:139], v[190:193], v[44:47]
	v_mfma_f32_16x16x32_bf16 v[40:43], v[166:169], v[190:193], v[40:43]
	v_mfma_f32_16x16x32_bf16 v[36:39], v[136:139], v[198:201], v[36:39]
	v_mfma_f32_16x16x32_bf16 v[32:35], v[166:169], v[198:201], v[32:35]
	v_mfma_f32_16x16x32_bf16 v[60:63], v[162:165], v[178:181], v[60:63]
	v_mfma_f32_16x16x32_bf16 v[56:59], v[170:173], v[178:181], v[56:59]
	v_mfma_f32_16x16x32_bf16 v[52:55], v[162:165], v[186:189], v[52:55]
	v_mfma_f32_16x16x32_bf16 v[48:51], v[170:173], v[186:189], v[48:51]
	v_mfma_f32_16x16x32_bf16 v[44:47], v[162:165], v[194:197], v[44:47]
	v_mfma_f32_16x16x32_bf16 v[40:43], v[170:173], v[194:197], v[40:43]
	v_mfma_f32_16x16x32_bf16 v[36:39], v[162:165], v[202:205], v[36:39]
	v_mfma_f32_16x16x32_bf16 v[32:35], v[170:173], v[202:205], v[32:35]
	s_barrier
	s_mov_b64 s[52:53], s[20:21]
	s_mov_b32 m0, s35
	v_lshl_add_u64 v[136:137], v[134:135], 0, s[52:53]
	global_load_lds_dwordx4 v[136:137], off
	v_lshl_add_u64 v[136:137], v[136:137], 0, s[10:11]
	s_mov_b32 m0, s40
	s_nop 0
	global_load_lds_dwordx4 v[136:137], off
	s_waitcnt vmcnt(6)
	s_barrier
	v_mfma_f32_16x16x32_bf16 v[28:31], v[206:209], v[174:177], v[28:31]
	v_mfma_f32_16x16x32_bf16 v[24:27], v[214:217], v[174:177], v[24:27]
	v_mfma_f32_16x16x32_bf16 v[20:23], v[206:209], v[182:185], v[20:23]
	v_mfma_f32_16x16x32_bf16 v[16:19], v[214:217], v[182:185], v[16:19]
	v_mfma_f32_16x16x32_bf16 v[12:15], v[206:209], v[190:193], v[12:15]
	v_mfma_f32_16x16x32_bf16 v[8:11], v[214:217], v[190:193], v[8:11]
	v_mfma_f32_16x16x32_bf16 v[4:7], v[206:209], v[198:201], v[4:7]
	v_mfma_f32_16x16x32_bf16 v[0:3], v[214:217], v[198:201], v[0:3]
	v_mfma_f32_16x16x32_bf16 v[28:31], v[210:213], v[178:181], v[28:31]
	v_mfma_f32_16x16x32_bf16 v[24:27], v[218:221], v[178:181], v[24:27]
	v_mfma_f32_16x16x32_bf16 v[20:23], v[210:213], v[186:189], v[20:23]
	v_mfma_f32_16x16x32_bf16 v[16:19], v[218:221], v[186:189], v[16:19]
	v_mfma_f32_16x16x32_bf16 v[12:15], v[210:213], v[194:197], v[12:15]
	v_mfma_f32_16x16x32_bf16 v[8:11], v[218:221], v[194:197], v[8:11]
	v_mfma_f32_16x16x32_bf16 v[4:7], v[210:213], v[202:205], v[4:7]
	v_mfma_f32_16x16x32_bf16 v[0:3], v[218:221], v[202:205], v[0:3]
	s_add_i32 s49, s49, 2
	s_add_u32 s20, s20, 0x100
	s_addc_u32 s21, s21, 0
	s_cmp_lt_u32 s49, 60
	s_barrier
	s_cbranch_scc1 .LBB0_727
	s_mov_b64 s[20:21], 0x101f80
	s_mov_b32 m0, s50
	ds_read_b128 v[134:137], v141
	ds_read_b128 v[162:165], v142
	ds_read_b128 v[166:169], v143
	ds_read_b128 v[170:173], v144
	ds_read_b128 v[174:177], v160
	ds_read_b128 v[178:181], v160 offset:1024
	ds_read_b128 v[182:185], v160 offset:2048
	ds_read_b128 v[186:189], v160 offset:3072
	ds_read_b128 v[190:193], v160 offset:4096
	ds_read_b128 v[194:197], v160 offset:5120
	ds_read_b128 v[198:201], v160 offset:6144
	ds_read_b128 v[202:205], v160 offset:7168
	s_nop 0
	v_lshl_add_u64 v[132:133], v[132:133], 0, s[20:21]
	global_load_lds_dwordx4 v[132:133], off
	v_lshl_add_u64 v[132:133], v[132:133], 0, s[10:11]
	s_mov_b32 m0, s34
	s_nop 0
	global_load_lds_dwordx4 v[132:133], off
	s_barrier
	s_waitcnt lgkmcnt(0)
	s_waitcnt lgkmcnt(0)
	v_mfma_f32_16x16x32_bf16 v[124:127], v[134:137], v[174:177], v[124:127]
	v_mfma_f32_16x16x32_bf16 v[120:123], v[166:169], v[174:177], v[120:123]
	v_mfma_f32_16x16x32_bf16 v[108:111], v[134:137], v[190:193], v[108:111]
	v_mfma_f32_16x16x32_bf16 v[104:107], v[166:169], v[190:193], v[104:107]
	v_mfma_f32_16x16x32_bf16 v[124:127], v[162:165], v[178:181], v[124:127]
	v_mfma_f32_16x16x32_bf16 v[120:123], v[170:173], v[178:181], v[120:123]
	v_mfma_f32_16x16x32_bf16 v[116:119], v[134:137], v[182:185], v[116:119]
	v_mfma_f32_16x16x32_bf16 v[112:115], v[166:169], v[182:185], v[112:115]
	v_mfma_f32_16x16x32_bf16 v[108:111], v[162:165], v[194:197], v[108:111]
	v_mfma_f32_16x16x32_bf16 v[104:107], v[170:173], v[194:197], v[104:107]
	v_mfma_f32_16x16x32_bf16 v[100:103], v[134:137], v[198:201], v[100:103]
	v_mfma_f32_16x16x32_bf16 v[96:99], v[166:169], v[198:201], v[96:99]
	v_mfma_f32_16x16x32_bf16 v[206:209], v[162:165], v[186:189], v[116:119]
	v_mfma_f32_16x16x32_bf16 v[210:213], v[170:173], v[186:189], v[112:115]
	v_mfma_f32_16x16x32_bf16 v[214:217], v[162:165], v[202:205], v[100:103]
	v_mfma_f32_16x16x32_bf16 v[218:221], v[170:173], v[202:205], v[96:99]
	s_barrier
	s_nop 1
	ds_read_b128 v[96:99], v145
	ds_read_b128 v[100:103], v146
	ds_read_b128 v[112:115], v147
	ds_read_b128 v[116:119], v148
	s_barrier
	s_waitcnt lgkmcnt(0)
	s_waitcnt lgkmcnt(0)
	v_mfma_f32_16x16x32_bf16 v[92:95], v[96:99], v[174:177], v[92:95]
	v_mfma_f32_16x16x32_bf16 v[88:91], v[112:115], v[174:177], v[88:91]
	v_mfma_f32_16x16x32_bf16 v[76:79], v[96:99], v[190:193], v[76:79]
	v_mfma_f32_16x16x32_bf16 v[72:75], v[112:115], v[190:193], v[72:75]
	v_mfma_f32_16x16x32_bf16 v[92:95], v[100:103], v[178:181], v[92:95]
	v_mfma_f32_16x16x32_bf16 v[88:91], v[116:119], v[178:181], v[88:91]
	v_mfma_f32_16x16x32_bf16 v[84:87], v[96:99], v[182:185], v[84:87]
	v_mfma_f32_16x16x32_bf16 v[80:83], v[112:115], v[182:185], v[80:83]
	v_mfma_f32_16x16x32_bf16 v[76:79], v[100:103], v[194:197], v[76:79]
	v_mfma_f32_16x16x32_bf16 v[72:75], v[116:119], v[194:197], v[72:75]
	v_mfma_f32_16x16x32_bf16 v[68:71], v[96:99], v[198:201], v[68:71]
	v_mfma_f32_16x16x32_bf16 v[64:67], v[112:115], v[198:201], v[64:67]
	v_mfma_f32_16x16x32_bf16 v[174:177], v[100:103], v[186:189], v[84:87]
	v_mfma_f32_16x16x32_bf16 v[178:181], v[116:119], v[186:189], v[80:83]
	v_mfma_f32_16x16x32_bf16 v[182:185], v[100:103], v[202:205], v[68:71]
	v_mfma_f32_16x16x32_bf16 v[186:189], v[116:119], v[202:205], v[64:67]
	s_barrier
; #define LDA(dst, b, h) for (int m = 0; m < 4; ++m) for (int k = 0; k < 2; ++k) \
;     dst[m][k] = *reinterpret_cast<const bf16x8*>(aRd + (((b) * 2 + (h)) * G_HT * 2 + m * 2048 + k * 1024))
; #define LDB(dst, b, h) for (int n = 0; n < 2; ++n) for (int k = 0; k < 2; ++k) \
;     dst[n][k] = *reinterpret_cast<const bf16x8*>(bRd + (((b) * 2 + (h)) * G_HT * 2 + n * 2048 + k * 1024))
; #define MMA(ai, bj, At, Bx) do { __builtin_amdgcn_s_setprio(1); \
;     for (int m = 0; m < 4; ++m) for (int n = 0; n < 2; ++n) for (int k = 0; k < 2; ++k) \
;       acc[ai][bj][m][n] = __builtin_amdgcn_mfma_f32_16x16x32_bf16(Bx[n][k], At[m][k], acc[ai][bj][m][n], 0, 0, 0);     \
;     __builtin_amdgcn_s_setprio(0); } while (0)
; #define WAIT_V(n) asm volatile("s_waitcnt vmcnt(" #n ")" ::: "memory")
; #define WAIT_L(n) asm volatile("s_waitcnt lgkmcnt(" #n ")" ::: "memory")
; #define BAR __builtin_amdgcn_s_barrier()
; template <int EPI>
; __device__ __forceinline__ void gemm_tile(const bf16* __restrict__ A, int lda, const bf16* __restrict__ Bt, int K,
;                                           int brow, int bcol, const EpiArgs& ea, char* shmc, bool has_next, int nbrow, int nbcol, bool first_tile) {
;     ...
;     LDA(At, 0, 1); WAIT_V(4); BAR; WAIT_L(0); MMA(1, 0, At, B0); MMA(1, 1, At, B1); BAR; }
;   { LDB(B0, 1, 0); LDA(At, 1, 0); WAIT_V(2); BAR; WAIT_L(0); MMA(0, 0, At, B0); BAR;
	s_nop 1
	ds_read_b128 v[64:67], v160 offset:16384
	ds_read_b128 v[68:71], v160 offset:17408
	ds_read_b128 v[80:83], v160 offset:18432
	ds_read_b128 v[84:87], v160 offset:19456
	ds_read_b128 v[190:193], v160 offset:20480
	ds_read_b128 v[194:197], v160 offset:21504
	ds_read_b128 v[198:201], v160 offset:22528
	ds_read_b128 v[202:205], v160 offset:23552
	s_waitcnt vmcnt(4)
	s_barrier
	s_waitcnt lgkmcnt(0)
	s_waitcnt lgkmcnt(0)
	v_mfma_f32_16x16x32_bf16 v[60:63], v[134:137], v[64:67], v[60:63]
	v_mfma_f32_16x16x32_bf16 v[52:55], v[134:137], v[80:83], v[52:55]
	v_mfma_f32_16x16x32_bf16 v[48:51], v[166:169], v[80:83], v[48:51]
	v_mfma_f32_16x16x32_bf16 v[36:39], v[134:137], v[198:201], v[36:39]
	v_mfma_f32_16x16x32_bf16 v[32:35], v[166:169], v[198:201], v[32:35]
	v_mfma_f32_16x16x32_bf16 v[60:63], v[162:165], v[68:71], v[60:63]
	v_mfma_f32_16x16x32_bf16 v[56:59], v[166:169], v[64:67], v[56:59]
	v_mfma_f32_16x16x32_bf16 v[52:55], v[162:165], v[84:87], v[52:55]
	v_mfma_f32_16x16x32_bf16 v[48:51], v[170:173], v[84:87], v[48:51]
	v_mfma_f32_16x16x32_bf16 v[44:47], v[134:137], v[190:193], v[44:47]
	v_mfma_f32_16x16x32_bf16 v[40:43], v[166:169], v[190:193], v[40:43]
	v_mfma_f32_16x16x32_bf16 v[36:39], v[162:165], v[202:205], v[36:39]
	v_mfma_f32_16x16x32_bf16 v[32:35], v[170:173], v[202:205], v[32:35]
	v_mfma_f32_16x16x32_bf16 v[222:225], v[170:173], v[68:71], v[56:59]
	v_mfma_f32_16x16x32_bf16 v[226:229], v[162:165], v[194:197], v[44:47]
	v_mfma_f32_16x16x32_bf16 v[230:233], v[170:173], v[194:197], v[40:43]
	v_mfma_f32_16x16x32_bf16 v[20:23], v[96:99], v[80:83], v[20:23]
	v_mfma_f32_16x16x32_bf16 v[16:19], v[112:115], v[80:83], v[16:19]
	v_mfma_f32_16x16x32_bf16 v[12:15], v[96:99], v[190:193], v[12:15]
	v_mfma_f32_16x16x32_bf16 v[8:11], v[112:115], v[190:193], v[8:11]
	v_mfma_f32_16x16x32_bf16 v[28:31], v[96:99], v[64:67], v[28:31]
	v_mfma_f32_16x16x32_bf16 v[24:27], v[112:115], v[64:67], v[24:27]
	v_mfma_f32_16x16x32_bf16 v[20:23], v[100:103], v[84:87], v[20:23]
	v_mfma_f32_16x16x32_bf16 v[16:19], v[116:119], v[84:87], v[16:19]
	v_mfma_f32_16x16x32_bf16 v[12:15], v[100:103], v[194:197], v[12:15]
	v_mfma_f32_16x16x32_bf16 v[8:11], v[116:119], v[194:197], v[8:11]
	v_mfma_f32_16x16x32_bf16 v[4:7], v[96:99], v[198:201], v[4:7]
	v_mfma_f32_16x16x32_bf16 v[0:3], v[112:115], v[198:201], v[0:3]
	v_mfma_f32_16x16x32_bf16 v[132:135], v[100:103], v[68:71], v[28:31]
	v_mfma_f32_16x16x32_bf16 v[136:139], v[116:119], v[68:71], v[24:27]
	v_mfma_f32_16x16x32_bf16 v[162:165], v[100:103], v[202:205], v[4:7]
	v_mfma_f32_16x16x32_bf16 v[166:169], v[116:119], v[202:205], v[0:3]
	s_barrier
	s_nop 1
	ds_read_b128 v[0:3], v149
	ds_read_b128 v[4:7], v150
	ds_read_b128 v[170:173], v151
	ds_read_b128 v[190:193], v152
	ds_read_b128 v[24:27], v160 offset:32768
	ds_read_b128 v[28:31], v160 offset:33792
	ds_read_b128 v[40:43], v160 offset:34816
	ds_read_b128 v[44:47], v160 offset:35840
	ds_read_b128 v[56:59], v160 offset:36864
	ds_read_b128 v[194:197], v160 offset:37888
	ds_read_b128 v[198:201], v160 offset:38912
	ds_read_b128 v[202:205], v160 offset:39936
	s_waitcnt vmcnt(2)
	s_barrier
	s_waitcnt lgkmcnt(0)
	s_waitcnt lgkmcnt(0)
	v_mfma_f32_16x16x32_bf16 v[64:67], v[0:3], v[24:27], v[124:127]
	v_mfma_f32_16x16x32_bf16 v[112:115], v[4:7], v[28:31], v[64:67]
	v_mfma_f32_16x16x32_bf16 v[64:67], v[170:173], v[24:27], v[120:123]
	v_mfma_f32_16x16x32_bf16 v[116:119], v[190:193], v[28:31], v[64:67]
	v_mfma_f32_16x16x32_bf16 v[64:67], v[0:3], v[40:43], v[206:209]
	v_mfma_f32_16x16x32_bf16 v[96:99], v[4:7], v[44:47], v[64:67]
	v_mfma_f32_16x16x32_bf16 v[64:67], v[170:173], v[40:43], v[210:213]
	v_mfma_f32_16x16x32_bf16 v[100:103], v[190:193], v[44:47], v[64:67]
	v_mfma_f32_16x16x32_bf16 v[64:67], v[0:3], v[56:59], v[108:111]
	v_mfma_f32_16x16x32_bf16 v[80:83], v[4:7], v[194:197], v[64:67]
	v_mfma_f32_16x16x32_bf16 v[64:67], v[170:173], v[56:59], v[104:107]
	v_mfma_f32_16x16x32_bf16 v[84:87], v[190:193], v[194:197], v[64:67]
	v_mfma_f32_16x16x32_bf16 v[64:67], v[0:3], v[198:201], v[214:217]
	v_mfma_f32_16x16x32_bf16 v[68:71], v[170:173], v[198:201], v[218:221]
	v_mfma_f32_16x16x32_bf16 v[64:67], v[4:7], v[202:205], v[64:67]
	v_mfma_f32_16x16x32_bf16 v[68:71], v[190:193], v[202:205], v[68:71]
	s_barrier
; #define LDA(dst, b, h) for (int m = 0; m < 4; ++m) for (int k = 0; k < 2; ++k) \
;     dst[m][k] = *reinterpret_cast<const bf16x8*>(aRd + (((b) * 2 + (h)) * G_HT * 2 + m * 2048 + k * 1024))
; #define LDB(dst, b, h) for (int n = 0; n < 2; ++n) for (int k = 0; k < 2; ++k) \
;     dst[n][k] = *reinterpret_cast<const bf16x8*>(bRd + (((b) * 2 + (h)) * G_HT * 2 + n * 2048 + k * 1024))
; #define MMA(ai, bj, At, Bx) do { __builtin_amdgcn_s_setprio(1); \
;     for (int m = 0; m < 4; ++m) for (int n = 0; n < 2; ++n) for (int k = 0; k < 2; ++k) \
;       acc[ai][bj][m][n] = __builtin_amdgcn_mfma_f32_16x16x32_bf16(Bx[n][k], At[m][k], acc[ai][bj][m][n], 0, 0, 0);     \
;     __builtin_amdgcn_s_setprio(0); } while (0)
; #define WAIT_V(n) asm volatile("s_waitcnt vmcnt(" #n ")" ::: "memory")
; #define WAIT_L(n) asm volatile("s_waitcnt lgkmcnt(" #n ")" ::: "memory")
; #define BAR __builtin_amdgcn_s_barrier()
; template <int EPI>
; __device__ __forceinline__ void gemm_tile(const bf16* __restrict__ A, int lda, const bf16* __restrict__ Bt, int K,
;                                           int brow, int bcol, const EpiArgs& ea, char* shmc, bool has_next, int nbrow, int nbcol, bool first_tile) {
;     ...
;     LDB(B1, 1, 1); WAIT_V(0); BAR; WAIT_L(0); MMA(0, 1, At, B1); BAR;
;     LDA(At, 1, 1); BAR; WAIT_L(0); MMA(1, 0, At, B0); MMA(1, 1, At, B1); BAR; }
;   if (wr == 0) BAR;
	ds_read_b128 v[206:209], v153
	ds_read_b128 v[210:213], v154
	ds_read_b128 v[214:217], v155
	ds_read_b128 v[218:221], v156
	s_waitcnt vmcnt(0)
	s_barrier
	s_waitcnt lgkmcnt(0)
	s_waitcnt lgkmcnt(0)
	v_mfma_f32_16x16x32_bf16 v[92:95], v[206:209], v[24:27], v[92:95]
	v_mfma_f32_16x16x32_bf16 v[24:27], v[214:217], v[24:27], v[88:91]
	v_mfma_f32_16x16x32_bf16 v[124:127], v[218:221], v[28:31], v[24:27]
	v_mfma_f32_16x16x32_bf16 v[24:27], v[206:209], v[40:43], v[174:177]
	v_mfma_f32_16x16x32_bf16 v[104:107], v[210:213], v[44:47], v[24:27]
	v_mfma_f32_16x16x32_bf16 v[24:27], v[214:217], v[40:43], v[178:181]
	v_mfma_f32_16x16x32_bf16 v[108:111], v[218:221], v[44:47], v[24:27]
	v_mfma_f32_16x16x32_bf16 v[24:27], v[206:209], v[56:59], v[76:79]
	v_mfma_f32_16x16x32_bf16 v[88:91], v[210:213], v[194:197], v[24:27]
	v_mfma_f32_16x16x32_bf16 v[24:27], v[214:217], v[56:59], v[72:75]
	v_mfma_f32_16x16x32_bf16 v[120:123], v[210:213], v[28:31], v[92:95]
	v_mfma_f32_16x16x32_bf16 v[92:95], v[218:221], v[194:197], v[24:27]
	v_mfma_f32_16x16x32_bf16 v[24:27], v[206:209], v[198:201], v[182:185]
	v_mfma_f32_16x16x32_bf16 v[72:75], v[210:213], v[202:205], v[24:27]
	v_mfma_f32_16x16x32_bf16 v[24:27], v[214:217], v[198:201], v[186:189]
	v_mfma_f32_16x16x32_bf16 v[76:79], v[218:221], v[202:205], v[24:27]
	s_barrier
	ds_read_b128 v[174:177], v160 offset:49152
	ds_read_b128 v[178:181], v160 offset:50176
	ds_read_b128 v[182:185], v160 offset:51200
	ds_read_b128 v[186:189], v160 offset:52224
	ds_read_b128 v[194:197], v160 offset:53248
	ds_read_b128 v[198:201], v160 offset:54272
	ds_read_b128 v[202:205], v160 offset:55296
	ds_read_b128 v[234:237], v160 offset:56320
	s_barrier
	s_waitcnt lgkmcnt(0)
	s_waitcnt lgkmcnt(0)
	v_mfma_f32_16x16x32_bf16 v[24:27], v[0:3], v[174:177], v[60:63]
	v_mfma_f32_16x16x32_bf16 v[56:59], v[4:7], v[178:181], v[24:27]
	v_mfma_f32_16x16x32_bf16 v[24:27], v[170:173], v[174:177], v[222:225]
	v_mfma_f32_16x16x32_bf16 v[60:63], v[190:193], v[178:181], v[24:27]
	v_mfma_f32_16x16x32_bf16 v[24:27], v[0:3], v[182:185], v[52:55]
	v_mfma_f32_16x16x32_bf16 v[40:43], v[4:7], v[186:189], v[24:27]
	v_mfma_f32_16x16x32_bf16 v[24:27], v[170:173], v[182:185], v[48:51]
	v_mfma_f32_16x16x32_bf16 v[44:47], v[190:193], v[186:189], v[24:27]
	v_mfma_f32_16x16x32_bf16 v[24:27], v[0:3], v[194:197], v[226:229]
	v_mfma_f32_16x16x32_bf16 v[0:3], v[0:3], v[202:205], v[36:39]
	v_mfma_f32_16x16x32_bf16 v[24:27], v[4:7], v[198:201], v[24:27]
	v_mfma_f32_16x16x32_bf16 v[28:31], v[170:173], v[194:197], v[230:233]
	v_mfma_f32_16x16x32_bf16 v[0:3], v[4:7], v[234:237], v[0:3]
	v_mfma_f32_16x16x32_bf16 v[4:7], v[170:173], v[202:205], v[32:35]
	v_mfma_f32_16x16x32_bf16 v[28:31], v[190:193], v[198:201], v[28:31]
	v_mfma_f32_16x16x32_bf16 v[4:7], v[190:193], v[234:237], v[4:7]
	v_mfma_f32_16x16x32_bf16 v[32:35], v[206:209], v[174:177], v[132:135]
	v_mfma_f32_16x16x32_bf16 v[48:51], v[210:213], v[178:181], v[32:35]
	v_mfma_f32_16x16x32_bf16 v[32:35], v[214:217], v[174:177], v[136:139]
	v_mfma_f32_16x16x32_bf16 v[20:23], v[206:209], v[182:185], v[20:23]
	v_mfma_f32_16x16x32_bf16 v[16:19], v[214:217], v[182:185], v[16:19]
	v_mfma_f32_16x16x32_bf16 v[12:15], v[206:209], v[194:197], v[12:15]
	v_mfma_f32_16x16x32_bf16 v[8:11], v[214:217], v[194:197], v[8:11]
	v_mfma_f32_16x16x32_bf16 v[52:55], v[218:221], v[178:181], v[32:35]
	v_mfma_f32_16x16x32_bf16 v[32:35], v[210:213], v[186:189], v[20:23]
	v_mfma_f32_16x16x32_bf16 v[36:39], v[218:221], v[186:189], v[16:19]
	v_mfma_f32_16x16x32_bf16 v[16:19], v[210:213], v[198:201], v[12:15]
	v_mfma_f32_16x16x32_bf16 v[20:23], v[218:221], v[198:201], v[8:11]
	v_mfma_f32_16x16x32_bf16 v[8:11], v[206:209], v[202:205], v[162:165]
	v_mfma_f32_16x16x32_bf16 v[12:15], v[214:217], v[202:205], v[166:169]
	v_mfma_f32_16x16x32_bf16 v[8:11], v[210:213], v[234:237], v[8:11]
	v_mfma_f32_16x16x32_bf16 v[12:15], v[218:221], v[234:237], v[12:15]
	s_barrier
	s_and_saveexec_b64 s[20:21], s[4:5]
	s_cbranch_execz .LBB0_730
	s_barrier

; #define STA(b, h, half, kt) STAGE(((b) * 2 + (h)) * G_HT * 2, pA, ((size_t)(half) * G_HALF * lda + (size_t)(kt) * G_BK) * 2, lda)
; #define STB(b, h, half, kt) STAGE((4 + (b) * 2 + (h)) * G_HT * 2, pB, ((size_t)(half) * G_HALF * K + (size_t)(kt) * G_BK) * 2, K)
; #define LDA(dst, b, h) for (int m = 0; m < 4; ++m) for (int k = 0; k < 2; ++k) \
;     dst[m][k] = *reinterpret_cast<const bf16x8*>(aRd + (((b) * 2 + (h)) * G_HT * 2 + m * 2048 + k * 1024))
; #define LDB(dst, b, h) for (int n = 0; n < 2; ++n) for (int k = 0; k < 2; ++k) \
;     dst[n][k] = *reinterpret_cast<const bf16x8*>(bRd + (((b) * 2 + (h)) * G_HT * 2 + n * 2048 + k * 1024))
; #define MMA(ai, bj, At, Bx) do { __builtin_amdgcn_s_setprio(1); \
;     for (int m = 0; m < 4; ++m) for (int n = 0; n < 2; ++n) for (int k = 0; k < 2; ++k) \
;       acc[ai][bj][m][n] = __builtin_amdgcn_mfma_f32_16x16x32_bf16(Bx[n][k], At[m][k], acc[ai][bj][m][n], 0, 0, 0);     \
;     __builtin_amdgcn_s_setprio(0); } while (0)
; #define WAIT_V(n) asm volatile("s_waitcnt vmcnt(" #n ")" ::: "memory")
; #define WAIT_L(n) asm volatile("s_waitcnt lgkmcnt(" #n ")" ::: "memory")
; #define BAR __builtin_amdgcn_s_barrier()
; #define SCHED __builtin_amdgcn_sched_barrier(0)
; template <int EPI>
; __device__ __forceinline__ void gemm_tile(const bf16* __restrict__ A, int lda, const bf16* __restrict__ Bt, int K,
;                                           int brow, int bcol, const EpiArgs& ea, char* shmc, bool has_next, int nbrow, int nbcol, bool first_tile) {
;     ...
;     LDB(B0, 0, 0); SCHED; LDA(At, 0, 0); STA(1, 1, 1, t + 1);
;     WAIT_L(8); BAR; WAIT_L(0); MMA(0, 0, At, B0); BAR; SCHED;
;     LDB(B1, 0, 1); STB(0, 0, 0, t + 2);
;     BAR; WAIT_L(0); MMA(0, 1, At, B1); BAR;
;     LDA(At, 0, 1); STA(0, 0, 0, t + 2);
;     BAR; WAIT_L(0); MMA(1, 0, At, B0); BAR; SCHED;
;     STB(0, 1, 1, t + 2);
;     WAIT_V(6); BAR; MMA(1, 1, At, B1); BAR;
.LBB0_784:
	ds_read_b128 v[136:139], v141
	ds_read_b128 v[162:165], v142
	ds_read_b128 v[166:169], v143
	ds_read_b128 v[170:173], v144
	s_add_u32 s40, s18, 0xffffff00
	s_addc_u32 s41, s19, -1
	s_mov_b32 m0, s34
	ds_read_b128 v[174:177], v160
	ds_read_b128 v[178:181], v160 offset:1024
	ds_read_b128 v[182:185], v160 offset:2048
	ds_read_b128 v[186:189], v160 offset:3072
	ds_read_b128 v[190:193], v160 offset:4096
	ds_read_b128 v[194:197], v160 offset:5120
	ds_read_b128 v[198:201], v160 offset:6144
	ds_read_b128 v[202:205], v160 offset:7168
	v_lshl_add_u64 v[206:207], v[132:133], 0, s[40:41]
	global_load_lds_dwordx4 v[206:207], off
	v_lshl_add_u64 v[206:207], v[206:207], 0, s[4:5]
	s_mov_b32 m0, s24
	s_nop 0
	global_load_lds_dwordx4 v[206:207], off
	s_waitcnt lgkmcnt(8)
	s_barrier
	s_waitcnt lgkmcnt(0)
	v_mfma_f32_16x16x32_bf16 v[124:127], v[136:139], v[174:177], v[124:127]
	v_mfma_f32_16x16x32_bf16 v[120:123], v[166:169], v[174:177], v[120:123]
	v_mfma_f32_16x16x32_bf16 v[116:119], v[136:139], v[182:185], v[116:119]
	v_mfma_f32_16x16x32_bf16 v[112:115], v[166:169], v[182:185], v[112:115]
	v_mfma_f32_16x16x32_bf16 v[108:111], v[136:139], v[190:193], v[108:111]
	v_mfma_f32_16x16x32_bf16 v[104:107], v[166:169], v[190:193], v[104:107]
	v_mfma_f32_16x16x32_bf16 v[100:103], v[136:139], v[198:201], v[100:103]
	v_mfma_f32_16x16x32_bf16 v[96:99], v[166:169], v[198:201], v[96:99]
	v_mfma_f32_16x16x32_bf16 v[124:127], v[162:165], v[178:181], v[124:127]
	v_mfma_f32_16x16x32_bf16 v[120:123], v[170:173], v[178:181], v[120:123]
	v_mfma_f32_16x16x32_bf16 v[116:119], v[162:165], v[186:189], v[116:119]
	v_mfma_f32_16x16x32_bf16 v[112:115], v[170:173], v[186:189], v[112:115]
	v_mfma_f32_16x16x32_bf16 v[108:111], v[162:165], v[194:197], v[108:111]
	v_mfma_f32_16x16x32_bf16 v[104:107], v[170:173], v[194:197], v[104:107]
	v_mfma_f32_16x16x32_bf16 v[100:103], v[162:165], v[202:205], v[100:103]
	v_mfma_f32_16x16x32_bf16 v[96:99], v[170:173], v[202:205], v[96:99]
	s_barrier
	s_add_u32 s40, s18, 0xffbfff80
	s_addc_u32 s41, s19, -1
	s_mov_b64 s[42:43], s[40:41]
	s_mov_b32 m0, s27
	ds_read_b128 v[206:209], v145
	ds_read_b128 v[210:213], v146
	ds_read_b128 v[214:217], v147
	ds_read_b128 v[218:221], v148
	v_lshl_add_u64 v[222:223], v[134:135], 0, s[42:43]
	global_load_lds_dwordx4 v[222:223], off
	v_lshl_add_u64 v[222:223], v[222:223], 0, s[4:5]
	s_mov_b32 m0, s28
	s_nop 0
	global_load_lds_dwordx4 v[222:223], off
	s_barrier
	s_waitcnt lgkmcnt(0)
	v_mfma_f32_16x16x32_bf16 v[92:95], v[206:209], v[174:177], v[92:95]
	v_mfma_f32_16x16x32_bf16 v[88:91], v[214:217], v[174:177], v[88:91]
	v_mfma_f32_16x16x32_bf16 v[84:87], v[206:209], v[182:185], v[84:87]
	v_mfma_f32_16x16x32_bf16 v[80:83], v[214:217], v[182:185], v[80:83]
	v_mfma_f32_16x16x32_bf16 v[76:79], v[206:209], v[190:193], v[76:79]
	v_mfma_f32_16x16x32_bf16 v[72:75], v[214:217], v[190:193], v[72:75]
	v_mfma_f32_16x16x32_bf16 v[68:71], v[206:209], v[198:201], v[68:71]
	v_mfma_f32_16x16x32_bf16 v[64:67], v[214:217], v[198:201], v[64:67]
	v_mfma_f32_16x16x32_bf16 v[92:95], v[210:213], v[178:181], v[92:95]
	v_mfma_f32_16x16x32_bf16 v[88:91], v[218:221], v[178:181], v[88:91]
	v_mfma_f32_16x16x32_bf16 v[84:87], v[210:213], v[186:189], v[84:87]
	v_mfma_f32_16x16x32_bf16 v[80:83], v[218:221], v[186:189], v[80:83]
	v_mfma_f32_16x16x32_bf16 v[76:79], v[210:213], v[194:197], v[76:79]
	v_mfma_f32_16x16x32_bf16 v[72:75], v[218:221], v[194:197], v[72:75]
	v_mfma_f32_16x16x32_bf16 v[68:71], v[210:213], v[202:205], v[68:71]
	v_mfma_f32_16x16x32_bf16 v[64:67], v[218:221], v[202:205], v[64:67]
	s_mov_b32 m0, s15
	s_barrier
	ds_read_b128 v[174:177], v160 offset:16384
	ds_read_b128 v[178:181], v160 offset:17408
	ds_read_b128 v[182:185], v160 offset:18432
	ds_read_b128 v[186:189], v160 offset:19456
	ds_read_b128 v[190:193], v160 offset:20480
	ds_read_b128 v[194:197], v160 offset:21504
	ds_read_b128 v[198:201], v160 offset:22528
	ds_read_b128 v[202:205], v160 offset:23552
	v_lshl_add_u64 v[222:223], v[132:133], 0, s[40:41]
	global_load_lds_dwordx4 v[222:223], off
	v_lshl_add_u64 v[222:223], v[222:223], 0, s[4:5]
	s_mov_b32 m0, s35
	s_nop 0
	global_load_lds_dwordx4 v[222:223], off
	s_barrier
	s_waitcnt lgkmcnt(0)
	v_mfma_f32_16x16x32_bf16 v[60:63], v[136:139], v[174:177], v[60:63]
	v_mfma_f32_16x16x32_bf16 v[56:59], v[166:169], v[174:177], v[56:59]
	v_mfma_f32_16x16x32_bf16 v[52:55], v[136:139], v[182:185], v[52:55]
	v_mfma_f32_16x16x32_bf16 v[48:51], v[166:169], v[182:185], v[48:51]
	v_mfma_f32_16x16x32_bf16 v[44:47], v[136:139], v[190:193], v[44:47]
	v_mfma_f32_16x16x32_bf16 v[40:43], v[166:169], v[190:193], v[40:43]
	v_mfma_f32_16x16x32_bf16 v[36:39], v[136:139], v[198:201], v[36:39]
	v_mfma_f32_16x16x32_bf16 v[32:35], v[166:169], v[198:201], v[32:35]
	v_mfma_f32_16x16x32_bf16 v[60:63], v[162:165], v[178:181], v[60:63]
	v_mfma_f32_16x16x32_bf16 v[56:59], v[170:173], v[178:181], v[56:59]
	v_mfma_f32_16x16x32_bf16 v[52:55], v[162:165], v[186:189], v[52:55]
	v_mfma_f32_16x16x32_bf16 v[48:51], v[170:173], v[186:189], v[48:51]
	v_mfma_f32_16x16x32_bf16 v[44:47], v[162:165], v[194:197], v[44:47]
	v_mfma_f32_16x16x32_bf16 v[40:43], v[170:173], v[194:197], v[40:43]
	v_mfma_f32_16x16x32_bf16 v[36:39], v[162:165], v[202:205], v[36:39]
	v_mfma_f32_16x16x32_bf16 v[32:35], v[170:173], v[202:205], v[32:35]
	s_barrier
	s_add_u32 s40, s18, 0xffffff80
	s_addc_u32 s41, s19, -1
	s_mov_b64 s[42:43], s[40:41]
	s_mov_b32 m0, s29
	v_lshl_add_u64 v[136:137], v[134:135], 0, s[42:43]
	global_load_lds_dwordx4 v[136:137], off
	v_lshl_add_u64 v[136:137], v[136:137], 0, s[4:5]
	s_mov_b32 m0, s30
	s_nop 0
	global_load_lds_dwordx4 v[136:137], off
	s_waitcnt vmcnt(6)
	s_barrier
; #define STA(b, h, half, kt) STAGE(((b) * 2 + (h)) * G_HT * 2, pA, ((size_t)(half) * G_HALF * lda + (size_t)(kt) * G_BK) * 2, lda)
; #define STB(b, h, half, kt) STAGE((4 + (b) * 2 + (h)) * G_HT * 2, pB, ((size_t)(half) * G_HALF * K + (size_t)(kt) * G_BK) * 2, K)
; #define LDA(dst, b, h) for (int m = 0; m < 4; ++m) for (int k = 0; k < 2; ++k) \
;     dst[m][k] = *reinterpret_cast<const bf16x8*>(aRd + (((b) * 2 + (h)) * G_HT * 2 + m * 2048 + k * 1024))
; #define LDB(dst, b, h) for (int n = 0; n < 2; ++n) for (int k = 0; k < 2; ++k) \
;     dst[n][k] = *reinterpret_cast<const bf16x8*>(bRd + (((b) * 2 + (h)) * G_HT * 2 + n * 2048 + k * 1024))
; #define MMA(ai, bj, At, Bx) do { __builtin_amdgcn_s_setprio(1); \
;     for (int m = 0; m < 4; ++m) for (int n = 0; n < 2; ++n) for (int k = 0; k < 2; ++k) \
;       acc[ai][bj][m][n] = __builtin_amdgcn_mfma_f32_16x16x32_bf16(Bx[n][k], At[m][k], acc[ai][bj][m][n], 0, 0, 0);     \
;     __builtin_amdgcn_s_setprio(0); } while (0)
; #define WAIT_V(n) asm volatile("s_waitcnt vmcnt(" #n ")" ::: "memory")
; #define WAIT_L(n) asm volatile("s_waitcnt lgkmcnt(" #n ")" ::: "memory")
; #define BAR __builtin_amdgcn_s_barrier()
; #define SCHED __builtin_amdgcn_sched_barrier(0)
; template <int EPI>
; __device__ __forceinline__ void gemm_tile(const bf16* __restrict__ A, int lda, const bf16* __restrict__ Bt, int K,
;                                           int brow, int bcol, const EpiArgs& ea, char* shmc, bool has_next, int nbrow, int nbcol, bool first_tile) {
;     ...
;     WAIT_V(6); BAR; MMA(1, 1, At, B1); BAR;
;     LDB(B0, 1, 0); SCHED; LDA(At, 1, 0); STA(0, 1, 1, t + 2);
;     WAIT_L(8); BAR; WAIT_L(0); MMA(0, 0, At, B0); BAR; SCHED;
;     LDB(B1, 1, 1); STB(1, 0, 0, t + 3);
;     BAR; WAIT_L(0); MMA(0, 1, At, B1); BAR;
;     LDA(At, 1, 1); STA(1, 0, 0, t + 3);
	v_mfma_f32_16x16x32_bf16 v[28:31], v[206:209], v[174:177], v[28:31]
	v_mfma_f32_16x16x32_bf16 v[24:27], v[214:217], v[174:177], v[24:27]
	v_mfma_f32_16x16x32_bf16 v[20:23], v[206:209], v[182:185], v[20:23]
	v_mfma_f32_16x16x32_bf16 v[16:19], v[214:217], v[182:185], v[16:19]
	v_mfma_f32_16x16x32_bf16 v[12:15], v[206:209], v[190:193], v[12:15]
	v_mfma_f32_16x16x32_bf16 v[8:11], v[214:217], v[190:193], v[8:11]
	v_mfma_f32_16x16x32_bf16 v[4:7], v[206:209], v[198:201], v[4:7]
	v_mfma_f32_16x16x32_bf16 v[0:3], v[214:217], v[198:201], v[0:3]
	v_mfma_f32_16x16x32_bf16 v[28:31], v[210:213], v[178:181], v[28:31]
	v_mfma_f32_16x16x32_bf16 v[24:27], v[218:221], v[178:181], v[24:27]
	v_mfma_f32_16x16x32_bf16 v[20:23], v[210:213], v[186:189], v[20:23]
	v_mfma_f32_16x16x32_bf16 v[16:19], v[218:221], v[186:189], v[16:19]
	v_mfma_f32_16x16x32_bf16 v[12:15], v[210:213], v[194:197], v[12:15]
	v_mfma_f32_16x16x32_bf16 v[8:11], v[218:221], v[194:197], v[8:11]
	v_mfma_f32_16x16x32_bf16 v[4:7], v[210:213], v[202:205], v[4:7]
	v_mfma_f32_16x16x32_bf16 v[0:3], v[218:221], v[202:205], v[0:3]
	s_barrier
	ds_read_b128 v[136:139], v149
	ds_read_b128 v[162:165], v150
	ds_read_b128 v[166:169], v151
	ds_read_b128 v[170:173], v152
	s_mov_b32 m0, s36
	ds_read_b128 v[174:177], v160 offset:32768
	ds_read_b128 v[178:181], v160 offset:33792
	ds_read_b128 v[182:185], v160 offset:34816
	ds_read_b128 v[186:189], v160 offset:35840
	ds_read_b128 v[190:193], v160 offset:36864
	ds_read_b128 v[194:197], v160 offset:37888
	ds_read_b128 v[198:201], v160 offset:38912
	ds_read_b128 v[202:205], v160 offset:39936
	v_lshl_add_u64 v[206:207], v[132:133], 0, s[40:41]
	global_load_lds_dwordx4 v[206:207], off
	v_lshl_add_u64 v[206:207], v[206:207], 0, s[4:5]
	s_mov_b32 m0, s37
	s_nop 0
	global_load_lds_dwordx4 v[206:207], off
	s_waitcnt lgkmcnt(8)
	s_barrier
	s_waitcnt lgkmcnt(0)
	v_mfma_f32_16x16x32_bf16 v[124:127], v[136:139], v[174:177], v[124:127]
	v_mfma_f32_16x16x32_bf16 v[120:123], v[166:169], v[174:177], v[120:123]
	v_mfma_f32_16x16x32_bf16 v[116:119], v[136:139], v[182:185], v[116:119]
	v_mfma_f32_16x16x32_bf16 v[112:115], v[166:169], v[182:185], v[112:115]
	v_mfma_f32_16x16x32_bf16 v[108:111], v[136:139], v[190:193], v[108:111]
	v_mfma_f32_16x16x32_bf16 v[104:107], v[166:169], v[190:193], v[104:107]
	v_mfma_f32_16x16x32_bf16 v[100:103], v[136:139], v[198:201], v[100:103]
	v_mfma_f32_16x16x32_bf16 v[96:99], v[166:169], v[198:201], v[96:99]
	v_mfma_f32_16x16x32_bf16 v[124:127], v[162:165], v[178:181], v[124:127]
	v_mfma_f32_16x16x32_bf16 v[120:123], v[170:173], v[178:181], v[120:123]
	v_mfma_f32_16x16x32_bf16 v[116:119], v[162:165], v[186:189], v[116:119]
	v_mfma_f32_16x16x32_bf16 v[112:115], v[170:173], v[186:189], v[112:115]
	v_mfma_f32_16x16x32_bf16 v[108:111], v[162:165], v[194:197], v[108:111]
	v_mfma_f32_16x16x32_bf16 v[104:107], v[170:173], v[194:197], v[104:107]
	v_mfma_f32_16x16x32_bf16 v[100:103], v[162:165], v[202:205], v[100:103]
	v_mfma_f32_16x16x32_bf16 v[96:99], v[170:173], v[202:205], v[96:99]
	s_barrier
	s_add_u32 s40, s18, 0xffc00000
	s_addc_u32 s41, s19, -1
	s_mov_b64 s[42:43], s[40:41]
	s_mov_b32 m0, s17
	ds_read_b128 v[206:209], v153
	ds_read_b128 v[210:213], v154
	ds_read_b128 v[214:217], v155
	ds_read_b128 v[218:221], v156
	v_lshl_add_u64 v[222:223], v[134:135], 0, s[42:43]
	global_load_lds_dwordx4 v[222:223], off
	v_lshl_add_u64 v[222:223], v[222:223], 0, s[4:5]
	s_mov_b32 m0, s21
	s_nop 0
	global_load_lds_dwordx4 v[222:223], off
	s_barrier
	s_waitcnt lgkmcnt(0)
	v_mfma_f32_16x16x32_bf16 v[92:95], v[206:209], v[174:177], v[92:95]
	v_mfma_f32_16x16x32_bf16 v[88:91], v[214:217], v[174:177], v[88:91]
	v_mfma_f32_16x16x32_bf16 v[84:87], v[206:209], v[182:185], v[84:87]
	v_mfma_f32_16x16x32_bf16 v[80:83], v[214:217], v[182:185], v[80:83]
	v_mfma_f32_16x16x32_bf16 v[76:79], v[206:209], v[190:193], v[76:79]
	v_mfma_f32_16x16x32_bf16 v[72:75], v[214:217], v[190:193], v[72:75]
	v_mfma_f32_16x16x32_bf16 v[68:71], v[206:209], v[198:201], v[68:71]
	v_mfma_f32_16x16x32_bf16 v[64:67], v[214:217], v[198:201], v[64:67]
	v_mfma_f32_16x16x32_bf16 v[92:95], v[210:213], v[178:181], v[92:95]
	v_mfma_f32_16x16x32_bf16 v[88:91], v[218:221], v[178:181], v[88:91]
	v_mfma_f32_16x16x32_bf16 v[84:87], v[210:213], v[186:189], v[84:87]
	v_mfma_f32_16x16x32_bf16 v[80:83], v[218:221], v[186:189], v[80:83]
	v_mfma_f32_16x16x32_bf16 v[76:79], v[210:213], v[194:197], v[76:79]
	v_mfma_f32_16x16x32_bf16 v[72:75], v[218:221], v[194:197], v[72:75]
	v_mfma_f32_16x16x32_bf16 v[68:71], v[210:213], v[202:205], v[68:71]
	v_mfma_f32_16x16x32_bf16 v[64:67], v[218:221], v[202:205], v[64:67]
	s_mov_b32 m0, s22
	s_barrier
	ds_read_b128 v[174:177], v160 offset:49152
	ds_read_b128 v[178:181], v160 offset:50176
	ds_read_b128 v[182:185], v160 offset:51200
	ds_read_b128 v[186:189], v160 offset:52224
	ds_read_b128 v[190:193], v160 offset:53248
	ds_read_b128 v[194:197], v160 offset:54272
	ds_read_b128 v[198:201], v160 offset:55296
	ds_read_b128 v[202:205], v160 offset:56320
	v_lshl_add_u64 v[222:223], v[132:133], 0, s[40:41]
	global_load_lds_dwordx4 v[222:223], off
	v_lshl_add_u64 v[222:223], v[222:223], 0, s[4:5]
	s_mov_b32 m0, s23
	s_nop 0
	global_load_lds_dwordx4 v[222:223], off
	s_barrier
; #define STA(b, h, half, kt) STAGE(((b) * 2 + (h)) * G_HT * 2, pA, ((size_t)(half) * G_HALF * lda + (size_t)(kt) * G_BK) * 2, lda)
; #define STB(b, h, half, kt) STAGE((4 + (b) * 2 + (h)) * G_HT * 2, pB, ((size_t)(half) * G_HALF * K + (size_t)(kt) * G_BK) * 2, K)
; #define LDA(dst, b, h) for (int m = 0; m < 4; ++m) for (int k = 0; k < 2; ++k) \
;     dst[m][k] = *reinterpret_cast<const bf16x8*>(aRd + (((b) * 2 + (h)) * G_HT * 2 + m * 2048 + k * 1024))
; #define LDB(dst, b, h) for (int n = 0; n < 2; ++n) for (int k = 0; k < 2; ++k) \
;     dst[n][k] = *reinterpret_cast<const bf16x8*>(bRd + (((b) * 2 + (h)) * G_HT * 2 + n * 2048 + k * 1024))
; #define MMA(ai, bj, At, Bx) do { __builtin_amdgcn_s_setprio(1); \
;     for (int m = 0; m < 4; ++m) for (int n = 0; n < 2; ++n) for (int k = 0; k < 2; ++k) \
;       acc[ai][bj][m][n] = __builtin_amdgcn_mfma_f32_16x16x32_bf16(Bx[n][k], At[m][k], acc[ai][bj][m][n], 0, 0, 0);     \
;     __builtin_amdgcn_s_setprio(0); } while (0)
; #define WAIT_V(n) asm volatile("s_waitcnt vmcnt(" #n ")" ::: "memory")
; #define WAIT_L(n) asm volatile("s_waitcnt lgkmcnt(" #n ")" ::: "memory")
; #define BAR __builtin_amdgcn_s_barrier()
; #define SCHED __builtin_amdgcn_sched_barrier(0)
; template <int EPI>
; __device__ __forceinline__ void gemm_tile(const bf16* __restrict__ A, int lda, const bf16* __restrict__ Bt, int K,
;                                           int brow, int bcol, const EpiArgs& ea, char* shmc, bool has_next, int nbrow, int nbcol, bool first_tile) {
;     ...
;     BAR; WAIT_L(0); MMA(1, 0, At, B0); BAR; SCHED;
;     STB(1, 1, 1, t + 3);
;     WAIT_V(6); BAR; MMA(1, 1, At, B1); BAR;
;   }
;   { LDB(B0, 0, 0); LDA(At, 0, 0); STA(1, 1, 1, nt - 1);
;     BAR; WAIT_L(0); MMA(0, 0, At, B0); BAR;
;     LDB(B1, 0, 1); BAR; WAIT_L(0); MMA(0, 1, At, B1); BAR;
	s_waitcnt lgkmcnt(0)
	v_mfma_f32_16x16x32_bf16 v[60:63], v[136:139], v[174:177], v[60:63]
	v_mfma_f32_16x16x32_bf16 v[56:59], v[166:169], v[174:177], v[56:59]
	v_mfma_f32_16x16x32_bf16 v[52:55], v[136:139], v[182:185], v[52:55]
	v_mfma_f32_16x16x32_bf16 v[48:51], v[166:169], v[182:185], v[48:51]
	v_mfma_f32_16x16x32_bf16 v[44:47], v[136:139], v[190:193], v[44:47]
	v_mfma_f32_16x16x32_bf16 v[40:43], v[166:169], v[190:193], v[40:43]
	v_mfma_f32_16x16x32_bf16 v[36:39], v[136:139], v[198:201], v[36:39]
	v_mfma_f32_16x16x32_bf16 v[32:35], v[166:169], v[198:201], v[32:35]
	v_mfma_f32_16x16x32_bf16 v[60:63], v[162:165], v[178:181], v[60:63]
	v_mfma_f32_16x16x32_bf16 v[56:59], v[170:173], v[178:181], v[56:59]
	v_mfma_f32_16x16x32_bf16 v[52:55], v[162:165], v[186:189], v[52:55]
	v_mfma_f32_16x16x32_bf16 v[48:51], v[170:173], v[186:189], v[48:51]
	v_mfma_f32_16x16x32_bf16 v[44:47], v[162:165], v[194:197], v[44:47]
	v_mfma_f32_16x16x32_bf16 v[40:43], v[170:173], v[194:197], v[40:43]
	v_mfma_f32_16x16x32_bf16 v[36:39], v[162:165], v[202:205], v[36:39]
	v_mfma_f32_16x16x32_bf16 v[32:35], v[170:173], v[202:205], v[32:35]
	s_barrier
	s_mov_b64 s[40:41], s[18:19]
	s_mov_b32 m0, s25
	v_lshl_add_u64 v[136:137], v[134:135], 0, s[40:41]
	global_load_lds_dwordx4 v[136:137], off
	v_lshl_add_u64 v[136:137], v[136:137], 0, s[4:5]
	s_mov_b32 m0, s26
	s_nop 0
	global_load_lds_dwordx4 v[136:137], off
	s_waitcnt vmcnt(6)
	s_barrier
	v_mfma_f32_16x16x32_bf16 v[28:31], v[206:209], v[174:177], v[28:31]
	v_mfma_f32_16x16x32_bf16 v[24:27], v[214:217], v[174:177], v[24:27]
	v_mfma_f32_16x16x32_bf16 v[20:23], v[206:209], v[182:185], v[20:23]
	v_mfma_f32_16x16x32_bf16 v[16:19], v[214:217], v[182:185], v[16:19]
	v_mfma_f32_16x16x32_bf16 v[12:15], v[206:209], v[190:193], v[12:15]
	v_mfma_f32_16x16x32_bf16 v[8:11], v[214:217], v[190:193], v[8:11]
	v_mfma_f32_16x16x32_bf16 v[4:7], v[206:209], v[198:201], v[4:7]
	v_mfma_f32_16x16x32_bf16 v[0:3], v[214:217], v[198:201], v[0:3]
	v_mfma_f32_16x16x32_bf16 v[28:31], v[210:213], v[178:181], v[28:31]
	v_mfma_f32_16x16x32_bf16 v[24:27], v[218:221], v[178:181], v[24:27]
	v_mfma_f32_16x16x32_bf16 v[20:23], v[210:213], v[186:189], v[20:23]
	v_mfma_f32_16x16x32_bf16 v[16:19], v[218:221], v[186:189], v[16:19]
	v_mfma_f32_16x16x32_bf16 v[12:15], v[210:213], v[194:197], v[12:15]
	v_mfma_f32_16x16x32_bf16 v[8:11], v[218:221], v[194:197], v[8:11]
	v_mfma_f32_16x16x32_bf16 v[4:7], v[210:213], v[202:205], v[4:7]
	v_mfma_f32_16x16x32_bf16 v[0:3], v[218:221], v[202:205], v[0:3]
	s_add_i32 s31, s31, 2
	s_add_u32 s18, s18, 0x100
	s_addc_u32 s19, s19, 0
	s_cmpk_lt_u32 s31, 0xfc
	s_barrier
	s_cbranch_scc1 .LBB0_784
	s_mov_b64 s[18:19], 0x407f80
	s_mov_b32 m0, s34
	ds_read_b128 v[134:137], v141
	ds_read_b128 v[162:165], v142
	ds_read_b128 v[166:169], v143
	ds_read_b128 v[170:173], v144
	ds_read_b128 v[174:177], v160
	ds_read_b128 v[178:181], v160 offset:1024
	ds_read_b128 v[182:185], v160 offset:2048
	ds_read_b128 v[186:189], v160 offset:3072
	ds_read_b128 v[190:193], v160 offset:4096
	ds_read_b128 v[194:197], v160 offset:5120
	ds_read_b128 v[198:201], v160 offset:6144
	ds_read_b128 v[202:205], v160 offset:7168
	s_nop 0
	v_lshl_add_u64 v[132:133], v[132:133], 0, s[18:19]
	global_load_lds_dwordx4 v[132:133], off
	v_lshl_add_u64 v[132:133], v[132:133], 0, s[4:5]
	s_mov_b32 m0, s24
	s_nop 0
	global_load_lds_dwordx4 v[132:133], off
	s_barrier
	s_waitcnt lgkmcnt(0)
	s_waitcnt lgkmcnt(0)
	v_mfma_f32_16x16x32_bf16 v[124:127], v[134:137], v[174:177], v[124:127]
	v_mfma_f32_16x16x32_bf16 v[120:123], v[166:169], v[174:177], v[120:123]
	v_mfma_f32_16x16x32_bf16 v[116:119], v[134:137], v[182:185], v[116:119]
	v_mfma_f32_16x16x32_bf16 v[112:115], v[166:169], v[182:185], v[112:115]
	v_mfma_f32_16x16x32_bf16 v[100:103], v[134:137], v[198:201], v[100:103]
	v_mfma_f32_16x16x32_bf16 v[96:99], v[166:169], v[198:201], v[96:99]
	v_mfma_f32_16x16x32_bf16 v[124:127], v[162:165], v[178:181], v[124:127]
	v_mfma_f32_16x16x32_bf16 v[120:123], v[170:173], v[178:181], v[120:123]
	v_mfma_f32_16x16x32_bf16 v[116:119], v[162:165], v[186:189], v[116:119]
	v_mfma_f32_16x16x32_bf16 v[112:115], v[170:173], v[186:189], v[112:115]
	v_mfma_f32_16x16x32_bf16 v[108:111], v[134:137], v[190:193], v[108:111]
	v_mfma_f32_16x16x32_bf16 v[104:107], v[166:169], v[190:193], v[104:107]
	v_mfma_f32_16x16x32_bf16 v[100:103], v[162:165], v[202:205], v[100:103]
	v_mfma_f32_16x16x32_bf16 v[96:99], v[170:173], v[202:205], v[96:99]
	v_mfma_f32_16x16x32_bf16 v[206:209], v[162:165], v[194:197], v[108:111]
	v_mfma_f32_16x16x32_bf16 v[210:213], v[170:173], v[194:197], v[104:107]
	s_barrier
	s_nop 1
	ds_read_b128 v[104:107], v145
	ds_read_b128 v[108:111], v146
	ds_read_b128 v[214:217], v147
	ds_read_b128 v[218:221], v148
	s_barrier
	s_waitcnt lgkmcnt(0)
	s_waitcnt lgkmcnt(0)
	v_mfma_f32_16x16x32_bf16 v[84:87], v[104:107], v[182:185], v[84:87]
	v_mfma_f32_16x16x32_bf16 v[80:83], v[214:217], v[182:185], v[80:83]
	v_mfma_f32_16x16x32_bf16 v[68:71], v[104:107], v[198:201], v[68:71]
	v_mfma_f32_16x16x32_bf16 v[64:67], v[214:217], v[198:201], v[64:67]
	v_mfma_f32_16x16x32_bf16 v[92:95], v[104:107], v[174:177], v[92:95]
	v_mfma_f32_16x16x32_bf16 v[88:91], v[214:217], v[174:177], v[88:91]
	v_mfma_f32_16x16x32_bf16 v[84:87], v[108:111], v[186:189], v[84:87]
	v_mfma_f32_16x16x32_bf16 v[80:83], v[218:221], v[186:189], v[80:83]
	v_mfma_f32_16x16x32_bf16 v[76:79], v[104:107], v[190:193], v[76:79]
	v_mfma_f32_16x16x32_bf16 v[72:75], v[214:217], v[190:193], v[72:75]
	v_mfma_f32_16x16x32_bf16 v[68:71], v[108:111], v[202:205], v[68:71]
	v_mfma_f32_16x16x32_bf16 v[64:67], v[218:221], v[202:205], v[64:67]
	v_mfma_f32_16x16x32_bf16 v[222:225], v[108:111], v[178:181], v[92:95]
	v_mfma_f32_16x16x32_bf16 v[174:177], v[218:221], v[178:181], v[88:91]
	v_mfma_f32_16x16x32_bf16 v[178:181], v[108:111], v[194:197], v[76:79]
	v_mfma_f32_16x16x32_bf16 v[182:185], v[218:221], v[194:197], v[72:75]
	s_barrier
; #define LDA(dst, b, h) for (int m = 0; m < 4; ++m) for (int k = 0; k < 2; ++k) \
;     dst[m][k] = *reinterpret_cast<const bf16x8*>(aRd + (((b) * 2 + (h)) * G_HT * 2 + m * 2048 + k * 1024))
; #define LDB(dst, b, h) for (int n = 0; n < 2; ++n) for (int k = 0; k < 2; ++k) \
;     dst[n][k] = *reinterpret_cast<const bf16x8*>(bRd + (((b) * 2 + (h)) * G_HT * 2 + n * 2048 + k * 1024))
; #define MMA(ai, bj, At, Bx) do { __builtin_amdgcn_s_setprio(1); \
;     for (int m = 0; m < 4; ++m) for (int n = 0; n < 2; ++n) for (int k = 0; k < 2; ++k) \
;       acc[ai][bj][m][n] = __builtin_amdgcn_mfma_f32_16x16x32_bf16(Bx[n][k], At[m][k], acc[ai][bj][m][n], 0, 0, 0);     \
;     __builtin_amdgcn_s_setprio(0); } while (0)
; #define WAIT_V(n) asm volatile("s_waitcnt vmcnt(" #n ")" ::: "memory")
; #define WAIT_L(n) asm volatile("s_waitcnt lgkmcnt(" #n ")" ::: "memory")
; #define BAR __builtin_amdgcn_s_barrier()
; template <int EPI>
; __device__ __forceinline__ void gemm_tile(const bf16* __restrict__ A, int lda, const bf16* __restrict__ Bt, int K,
;                                           int brow, int bcol, const EpiArgs& ea, char* shmc, bool has_next, int nbrow, int nbcol, bool first_tile) {
;     ...
;     LDA(At, 0, 1); WAIT_V(4); BAR; WAIT_L(0); MMA(1, 0, At, B0); MMA(1, 1, At, B1); BAR; }
;   { LDB(B0, 1, 0); LDA(At, 1, 0); WAIT_V(2); BAR; WAIT_L(0); MMA(0, 0, At, B0); BAR;
	s_nop 0
	ds_read_b128 v[72:75], v160 offset:16384
	ds_read_b128 v[76:79], v160 offset:17408
	ds_read_b128 v[88:91], v160 offset:18432
	ds_read_b128 v[92:95], v160 offset:19456
	ds_read_b128 v[186:189], v160 offset:20480
	ds_read_b128 v[190:193], v160 offset:21504
	ds_read_b128 v[194:197], v160 offset:22528
	ds_read_b128 v[198:201], v160 offset:23552
	s_waitcnt vmcnt(4)
	s_barrier
	s_waitcnt lgkmcnt(0)
	s_waitcnt lgkmcnt(0)
	v_mfma_f32_16x16x32_bf16 v[60:63], v[134:137], v[72:75], v[60:63]
	v_mfma_f32_16x16x32_bf16 v[56:59], v[166:169], v[72:75], v[56:59]
	v_mfma_f32_16x16x32_bf16 v[52:55], v[134:137], v[88:91], v[52:55]
	v_mfma_f32_16x16x32_bf16 v[48:51], v[166:169], v[88:91], v[48:51]
	v_mfma_f32_16x16x32_bf16 v[36:39], v[134:137], v[194:197], v[36:39]
	v_mfma_f32_16x16x32_bf16 v[32:35], v[166:169], v[194:197], v[32:35]
	v_mfma_f32_16x16x32_bf16 v[60:63], v[162:165], v[76:79], v[60:63]
	v_mfma_f32_16x16x32_bf16 v[56:59], v[170:173], v[76:79], v[56:59]
	v_mfma_f32_16x16x32_bf16 v[52:55], v[162:165], v[92:95], v[52:55]
	v_mfma_f32_16x16x32_bf16 v[48:51], v[170:173], v[92:95], v[48:51]
	v_mfma_f32_16x16x32_bf16 v[44:47], v[134:137], v[186:189], v[44:47]
	v_mfma_f32_16x16x32_bf16 v[40:43], v[166:169], v[186:189], v[40:43]
	v_mfma_f32_16x16x32_bf16 v[36:39], v[162:165], v[198:201], v[36:39]
	v_mfma_f32_16x16x32_bf16 v[32:35], v[170:173], v[198:201], v[32:35]
	v_mfma_f32_16x16x32_bf16 v[202:205], v[162:165], v[190:193], v[44:47]
	v_mfma_f32_16x16x32_bf16 v[226:229], v[170:173], v[190:193], v[40:43]
	v_mfma_f32_16x16x32_bf16 v[20:23], v[104:107], v[88:91], v[20:23]
	v_mfma_f32_16x16x32_bf16 v[16:19], v[214:217], v[88:91], v[16:19]
	v_mfma_f32_16x16x32_bf16 v[4:7], v[104:107], v[194:197], v[4:7]
	v_mfma_f32_16x16x32_bf16 v[0:3], v[214:217], v[194:197], v[0:3]
	v_mfma_f32_16x16x32_bf16 v[28:31], v[104:107], v[72:75], v[28:31]
	v_mfma_f32_16x16x32_bf16 v[24:27], v[214:217], v[72:75], v[24:27]
	v_mfma_f32_16x16x32_bf16 v[20:23], v[108:111], v[92:95], v[20:23]
	v_mfma_f32_16x16x32_bf16 v[16:19], v[218:221], v[92:95], v[16:19]
	v_mfma_f32_16x16x32_bf16 v[12:15], v[104:107], v[186:189], v[12:15]
	v_mfma_f32_16x16x32_bf16 v[8:11], v[214:217], v[186:189], v[8:11]
	v_mfma_f32_16x16x32_bf16 v[4:7], v[108:111], v[198:201], v[4:7]
	v_mfma_f32_16x16x32_bf16 v[0:3], v[218:221], v[198:201], v[0:3]
	v_mfma_f32_16x16x32_bf16 v[132:135], v[108:111], v[76:79], v[28:31]
	v_mfma_f32_16x16x32_bf16 v[136:139], v[218:221], v[76:79], v[24:27]
	v_mfma_f32_16x16x32_bf16 v[162:165], v[108:111], v[190:193], v[12:15]
	v_mfma_f32_16x16x32_bf16 v[166:169], v[218:221], v[190:193], v[8:11]
	s_barrier
	s_nop 0
	ds_read_b128 v[8:11], v149
	ds_read_b128 v[12:15], v150
	ds_read_b128 v[170:173], v151
	ds_read_b128 v[186:189], v152
	ds_read_b128 v[24:27], v160 offset:32768
	ds_read_b128 v[28:31], v160 offset:33792
	ds_read_b128 v[40:43], v160 offset:34816
	ds_read_b128 v[44:47], v160 offset:35840
	ds_read_b128 v[190:193], v160 offset:36864
	ds_read_b128 v[194:197], v160 offset:37888
	ds_read_b128 v[198:201], v160 offset:38912
	ds_read_b128 v[214:217], v160 offset:39936
	s_waitcnt vmcnt(2)
	s_barrier
	s_waitcnt lgkmcnt(0)
	s_waitcnt lgkmcnt(0)
	v_mfma_f32_16x16x32_bf16 v[72:75], v[8:11], v[24:27], v[124:127]
	v_mfma_f32_16x16x32_bf16 v[124:127], v[12:15], v[28:31], v[72:75]
	v_mfma_f32_16x16x32_bf16 v[72:75], v[170:173], v[24:27], v[120:123]
	v_mfma_f32_16x16x32_bf16 v[120:123], v[186:189], v[28:31], v[72:75]
	v_mfma_f32_16x16x32_bf16 v[72:75], v[8:11], v[40:43], v[116:119]
	v_mfma_f32_16x16x32_bf16 v[108:111], v[12:15], v[44:47], v[72:75]
	v_mfma_f32_16x16x32_bf16 v[72:75], v[170:173], v[40:43], v[112:115]
	v_mfma_f32_16x16x32_bf16 v[104:107], v[186:189], v[44:47], v[72:75]
	v_mfma_f32_16x16x32_bf16 v[72:75], v[8:11], v[190:193], v[206:209]
	v_mfma_f32_16x16x32_bf16 v[92:95], v[12:15], v[194:197], v[72:75]
	v_mfma_f32_16x16x32_bf16 v[72:75], v[170:173], v[190:193], v[210:213]
	v_mfma_f32_16x16x32_bf16 v[88:91], v[186:189], v[194:197], v[72:75]
	v_mfma_f32_16x16x32_bf16 v[72:75], v[8:11], v[198:201], v[100:103]
	v_mfma_f32_16x16x32_bf16 v[76:79], v[12:15], v[214:217], v[72:75]
	v_mfma_f32_16x16x32_bf16 v[72:75], v[170:173], v[198:201], v[96:99]
	v_mfma_f32_16x16x32_bf16 v[72:75], v[186:189], v[214:217], v[72:75]
	s_barrier
; #define LDA(dst, b, h) for (int m = 0; m < 4; ++m) for (int k = 0; k < 2; ++k) \
;     dst[m][k] = *reinterpret_cast<const bf16x8*>(aRd + (((b) * 2 + (h)) * G_HT * 2 + m * 2048 + k * 1024))
; #define LDB(dst, b, h) for (int n = 0; n < 2; ++n) for (int k = 0; k < 2; ++k) \
;     dst[n][k] = *reinterpret_cast<const bf16x8*>(bRd + (((b) * 2 + (h)) * G_HT * 2 + n * 2048 + k * 1024))
; #define MMA(ai, bj, At, Bx) do { __builtin_amdgcn_s_setprio(1); \
;     for (int m = 0; m < 4; ++m) for (int n = 0; n < 2; ++n) for (int k = 0; k < 2; ++k) \
;       acc[ai][bj][m][n] = __builtin_amdgcn_mfma_f32_16x16x32_bf16(Bx[n][k], At[m][k], acc[ai][bj][m][n], 0, 0, 0);     \
;     __builtin_amdgcn_s_setprio(0); } while (0)
; #define WAIT_V(n) asm volatile("s_waitcnt vmcnt(" #n ")" ::: "memory")
; #define WAIT_L(n) asm volatile("s_waitcnt lgkmcnt(" #n ")" ::: "memory")
; #define BAR __builtin_amdgcn_s_barrier()
; template <int EPI>
; __device__ __forceinline__ void gemm_tile(const bf16* __restrict__ A, int lda, const bf16* __restrict__ Bt, int K,
;                                           int brow, int bcol, const EpiArgs& ea, char* shmc, bool has_next, int nbrow, int nbcol, bool first_tile) {
;     ...
;     LDB(B1, 1, 1); WAIT_V(0); BAR; WAIT_L(0); MMA(0, 1, At, B1); BAR;
;     LDA(At, 1, 1); BAR; WAIT_L(0); MMA(1, 0, At, B0); MMA(1, 1, At, B1); BAR; }
;   if (wr == 0) BAR;
	ds_read_b128 v[206:209], v153
	ds_read_b128 v[210:213], v154
	ds_read_b128 v[218:221], v155
	ds_read_b128 v[230:233], v156
	s_waitcnt vmcnt(0)
	s_barrier
	s_waitcnt lgkmcnt(0)
	s_waitcnt lgkmcnt(0)
	v_mfma_f32_16x16x32_bf16 v[96:99], v[206:209], v[24:27], v[222:225]
	v_mfma_f32_16x16x32_bf16 v[24:27], v[218:221], v[24:27], v[174:177]
	v_mfma_f32_16x16x32_bf16 v[112:115], v[230:233], v[28:31], v[24:27]
	v_mfma_f32_16x16x32_bf16 v[24:27], v[206:209], v[40:43], v[84:87]
	v_mfma_f32_16x16x32_bf16 v[100:103], v[210:213], v[44:47], v[24:27]
	v_mfma_f32_16x16x32_bf16 v[24:27], v[218:221], v[40:43], v[80:83]
	v_mfma_f32_16x16x32_bf16 v[116:119], v[210:213], v[28:31], v[96:99]
	v_mfma_f32_16x16x32_bf16 v[96:99], v[230:233], v[44:47], v[24:27]
	v_mfma_f32_16x16x32_bf16 v[24:27], v[206:209], v[190:193], v[178:181]
	v_mfma_f32_16x16x32_bf16 v[84:87], v[210:213], v[194:197], v[24:27]
	v_mfma_f32_16x16x32_bf16 v[24:27], v[218:221], v[190:193], v[182:185]
	v_mfma_f32_16x16x32_bf16 v[80:83], v[230:233], v[194:197], v[24:27]
	v_mfma_f32_16x16x32_bf16 v[24:27], v[206:209], v[198:201], v[68:71]
	v_mfma_f32_16x16x32_bf16 v[68:71], v[210:213], v[214:217], v[24:27]
	v_mfma_f32_16x16x32_bf16 v[24:27], v[218:221], v[198:201], v[64:67]
	v_mfma_f32_16x16x32_bf16 v[64:67], v[230:233], v[214:217], v[24:27]
	s_barrier
	ds_read_b128 v[174:177], v160 offset:49152
	ds_read_b128 v[178:181], v160 offset:50176
	ds_read_b128 v[182:185], v160 offset:51200
	ds_read_b128 v[190:193], v160 offset:52224
	ds_read_b128 v[194:197], v160 offset:53248
	ds_read_b128 v[198:201], v160 offset:54272
	ds_read_b128 v[214:217], v160 offset:55296
	ds_read_b128 v[222:225], v160 offset:56320
	s_barrier
	s_waitcnt lgkmcnt(0)
	s_waitcnt lgkmcnt(0)
	v_mfma_f32_16x16x32_bf16 v[24:27], v[8:11], v[174:177], v[60:63]
	v_mfma_f32_16x16x32_bf16 v[60:63], v[12:15], v[178:181], v[24:27]
	v_mfma_f32_16x16x32_bf16 v[24:27], v[170:173], v[174:177], v[56:59]
	v_mfma_f32_16x16x32_bf16 v[56:59], v[186:189], v[178:181], v[24:27]
	v_mfma_f32_16x16x32_bf16 v[24:27], v[8:11], v[182:185], v[52:55]
	v_mfma_f32_16x16x32_bf16 v[44:47], v[12:15], v[190:193], v[24:27]
	v_mfma_f32_16x16x32_bf16 v[24:27], v[170:173], v[182:185], v[48:51]
	v_mfma_f32_16x16x32_bf16 v[40:43], v[186:189], v[190:193], v[24:27]
	v_mfma_f32_16x16x32_bf16 v[24:27], v[8:11], v[194:197], v[202:205]
	v_mfma_f32_16x16x32_bf16 v[8:11], v[8:11], v[214:217], v[36:39]
	v_mfma_f32_16x16x32_bf16 v[28:31], v[12:15], v[198:201], v[24:27]
	v_mfma_f32_16x16x32_bf16 v[24:27], v[170:173], v[194:197], v[226:229]
	v_mfma_f32_16x16x32_bf16 v[12:15], v[12:15], v[222:225], v[8:11]
	v_mfma_f32_16x16x32_bf16 v[8:11], v[170:173], v[214:217], v[32:35]
	v_mfma_f32_16x16x32_bf16 v[24:27], v[186:189], v[198:201], v[24:27]
	v_mfma_f32_16x16x32_bf16 v[8:11], v[186:189], v[222:225], v[8:11]
	v_mfma_f32_16x16x32_bf16 v[32:35], v[206:209], v[174:177], v[132:135]
	v_mfma_f32_16x16x32_bf16 v[52:55], v[210:213], v[178:181], v[32:35]
	v_mfma_f32_16x16x32_bf16 v[32:35], v[218:221], v[174:177], v[136:139]
	v_mfma_f32_16x16x32_bf16 v[16:19], v[218:221], v[182:185], v[16:19]
	v_mfma_f32_16x16x32_bf16 v[48:51], v[230:233], v[178:181], v[32:35]
	v_mfma_f32_16x16x32_bf16 v[20:23], v[206:209], v[182:185], v[20:23]
	v_mfma_f32_16x16x32_bf16 v[32:35], v[230:233], v[190:193], v[16:19]
	v_mfma_f32_16x16x32_bf16 v[16:19], v[206:209], v[194:197], v[162:165]
	v_mfma_f32_16x16x32_bf16 v[36:39], v[210:213], v[190:193], v[20:23]
	v_mfma_f32_16x16x32_bf16 v[20:23], v[210:213], v[198:201], v[16:19]
	v_mfma_f32_16x16x32_bf16 v[16:19], v[218:221], v[194:197], v[166:169]
	v_mfma_f32_16x16x32_bf16 v[4:7], v[206:209], v[214:217], v[4:7]
	v_mfma_f32_16x16x32_bf16 v[0:3], v[218:221], v[214:217], v[0:3]
	v_mfma_f32_16x16x32_bf16 v[16:19], v[230:233], v[198:201], v[16:19]
	v_mfma_f32_16x16x32_bf16 v[4:7], v[210:213], v[222:225], v[4:7]
	v_mfma_f32_16x16x32_bf16 v[0:3], v[230:233], v[222:225], v[0:3]
	s_barrier
	s_and_saveexec_b64 s[18:19], s[2:3]
	s_cbranch_execz .LBB0_787
	s_barrier
